# epilogues: accumulators permuted across lanes once (lane' = 4*row+colgroup) so GateA/GateB/EpiRes/EpiUp global loads+stores are quad-coalesced
# speedup vs baseline: 1.0186x; 1.0088x over previous
; DEVI unsigned char* WSP() { return *(unsigned char* const __attribute__((address_space(4)))*)(kargs() + 8 * 22); }
;     DEVI void operator()(AccRef acc, const Unit& u, int wr, int wc, int fr, int fq) const {
;         bf16_t* gb = (bf16_t*)(WSP() + O_GB);
; #pragma unroll
;         for (int ai = 0; ai < 2; ++ai) {
;             u32x4 w[4][2];
; #pragma unroll
;             for (int m = 0; m < 4; ++m)
; #pragma unroll
;                 for (int bj = 0; bj < 2; ++bj) w[m][bj] = *(const u32x4*)(gb + (unsigned)ROWOF(u) * 1024u + u.pn * 256 + bj * 128 + wc * 32 + 8 * fq);
; #pragma unroll
.LBB0_1396:
	s_mov_b64 s[54:55], s[0:1]
	v_mbcnt_lo_u32_b32 v0, -1, 0
	v_mbcnt_hi_u32_b32 v0, -1, v0
	v_lshl_or_b32 v0, s33, 6, v0
	v_bfe_u32 v175, v0, 2, 4
	v_and_b32_e32 v174, 3, v0
	v_lshl_add_u32 v174, v174, 4, v175
	v_lshlrev_b32_e32 v174, 2, v174
	ds_bpermute_b32 v2, v174, v2
	ds_bpermute_b32 v3, v174, v3
	ds_bpermute_b32 v4, v174, v4
	ds_bpermute_b32 v5, v174, v5
	ds_bpermute_b32 v6, v174, v6
	ds_bpermute_b32 v7, v174, v7
	ds_bpermute_b32 v8, v174, v8
	ds_bpermute_b32 v9, v174, v9
	s_waitcnt lgkmcnt(7)
	ds_bpermute_b32 v10, v174, v10
	ds_bpermute_b32 v11, v174, v11
	ds_bpermute_b32 v12, v174, v12
	ds_bpermute_b32 v13, v174, v13
	ds_bpermute_b32 v14, v174, v14
	ds_bpermute_b32 v15, v174, v15
	ds_bpermute_b32 v16, v174, v16
	ds_bpermute_b32 v17, v174, v17
	s_waitcnt lgkmcnt(7)
	ds_bpermute_b32 v18, v174, v18
	ds_bpermute_b32 v19, v174, v19
	ds_bpermute_b32 v20, v174, v20
	ds_bpermute_b32 v21, v174, v21
	ds_bpermute_b32 v22, v174, v22
	ds_bpermute_b32 v23, v174, v23
	ds_bpermute_b32 v24, v174, v24
	ds_bpermute_b32 v25, v174, v25
	s_waitcnt lgkmcnt(7)
	ds_bpermute_b32 v26, v174, v26
	ds_bpermute_b32 v27, v174, v27
	ds_bpermute_b32 v28, v174, v28
	ds_bpermute_b32 v29, v174, v29
	ds_bpermute_b32 v30, v174, v30
	ds_bpermute_b32 v31, v174, v31
	ds_bpermute_b32 v32, v174, v32
	ds_bpermute_b32 v33, v174, v33
	s_waitcnt lgkmcnt(7)
	ds_bpermute_b32 v34, v174, v34
	ds_bpermute_b32 v35, v174, v35
	ds_bpermute_b32 v36, v174, v36
	ds_bpermute_b32 v37, v174, v37
	ds_bpermute_b32 v38, v174, v38
	ds_bpermute_b32 v39, v174, v39
	ds_bpermute_b32 v40, v174, v40
	ds_bpermute_b32 v41, v174, v41
	s_waitcnt lgkmcnt(7)
	ds_bpermute_b32 v42, v174, v42
	ds_bpermute_b32 v43, v174, v43
	ds_bpermute_b32 v44, v174, v44
	ds_bpermute_b32 v45, v174, v45
	ds_bpermute_b32 v46, v174, v46
	ds_bpermute_b32 v47, v174, v47
	ds_bpermute_b32 v48, v174, v48
	ds_bpermute_b32 v49, v174, v49
	s_waitcnt lgkmcnt(7)
	ds_bpermute_b32 v50, v174, v50
	ds_bpermute_b32 v51, v174, v51
	ds_bpermute_b32 v52, v174, v52
	ds_bpermute_b32 v53, v174, v53
	ds_bpermute_b32 v54, v174, v54
	ds_bpermute_b32 v55, v174, v55
	ds_bpermute_b32 v56, v174, v56
	ds_bpermute_b32 v57, v174, v57
	s_waitcnt lgkmcnt(7)
	ds_bpermute_b32 v58, v174, v58
	ds_bpermute_b32 v59, v174, v59
	ds_bpermute_b32 v60, v174, v60
	ds_bpermute_b32 v61, v174, v61
	ds_bpermute_b32 v62, v174, v62
	ds_bpermute_b32 v63, v174, v63
	ds_bpermute_b32 v64, v174, v64
	ds_bpermute_b32 v65, v174, v65
	s_waitcnt lgkmcnt(7)
	ds_bpermute_b32 v66, v174, v66
	ds_bpermute_b32 v67, v174, v67
	ds_bpermute_b32 v68, v174, v68
	ds_bpermute_b32 v69, v174, v69
	ds_bpermute_b32 v70, v174, v70
	ds_bpermute_b32 v71, v174, v71
	ds_bpermute_b32 v72, v174, v72
	ds_bpermute_b32 v73, v174, v73
	s_waitcnt lgkmcnt(7)
	ds_bpermute_b32 v74, v174, v74
	ds_bpermute_b32 v75, v174, v75
	ds_bpermute_b32 v76, v174, v76
	ds_bpermute_b32 v77, v174, v77
	ds_bpermute_b32 v78, v174, v78
	ds_bpermute_b32 v79, v174, v79
	ds_bpermute_b32 v80, v174, v80
	ds_bpermute_b32 v81, v174, v81
	s_waitcnt lgkmcnt(7)
	ds_bpermute_b32 v82, v174, v82
	ds_bpermute_b32 v83, v174, v83
	ds_bpermute_b32 v84, v174, v84
	ds_bpermute_b32 v85, v174, v85
	ds_bpermute_b32 v86, v174, v86
	ds_bpermute_b32 v87, v174, v87
	ds_bpermute_b32 v88, v174, v88
	ds_bpermute_b32 v89, v174, v89
	s_waitcnt lgkmcnt(7)
	ds_bpermute_b32 v90, v174, v90
	ds_bpermute_b32 v91, v174, v91
	ds_bpermute_b32 v92, v174, v92
	ds_bpermute_b32 v93, v174, v93
	ds_bpermute_b32 v94, v174, v94
	ds_bpermute_b32 v95, v174, v95
	ds_bpermute_b32 v96, v174, v96
	ds_bpermute_b32 v97, v174, v97
	s_waitcnt lgkmcnt(7)
	ds_bpermute_b32 v98, v174, v98
	ds_bpermute_b32 v99, v174, v99
	ds_bpermute_b32 v100, v174, v100
	ds_bpermute_b32 v101, v174, v101
	ds_bpermute_b32 v102, v174, v102
	ds_bpermute_b32 v103, v174, v103
	ds_bpermute_b32 v104, v174, v104
	ds_bpermute_b32 v105, v174, v105
	s_waitcnt lgkmcnt(7)
	ds_bpermute_b32 v106, v174, v106
	ds_bpermute_b32 v107, v174, v107
	ds_bpermute_b32 v108, v174, v108
	ds_bpermute_b32 v109, v174, v109
	ds_bpermute_b32 v110, v174, v110
	ds_bpermute_b32 v111, v174, v111
	ds_bpermute_b32 v112, v174, v112
	ds_bpermute_b32 v113, v174, v113
	s_waitcnt lgkmcnt(7)
	ds_bpermute_b32 v114, v174, v114
	ds_bpermute_b32 v115, v174, v115
	ds_bpermute_b32 v116, v174, v116
	ds_bpermute_b32 v117, v174, v117
	ds_bpermute_b32 v118, v174, v118
	ds_bpermute_b32 v119, v174, v119
	ds_bpermute_b32 v120, v174, v120
	ds_bpermute_b32 v121, v174, v121
	s_waitcnt lgkmcnt(7)
	ds_bpermute_b32 v122, v174, v122
	ds_bpermute_b32 v123, v174, v123
	ds_bpermute_b32 v124, v174, v124
	ds_bpermute_b32 v125, v174, v125
	ds_bpermute_b32 v126, v174, v126
	ds_bpermute_b32 v127, v174, v127
	ds_bpermute_b32 v128, v174, v128
	ds_bpermute_b32 v129, v174, v129
	s_waitcnt lgkmcnt(0)
	s_load_dwordx2 s[54:55], s[54:55], 0xb0
	v_readfirstlane_b32 s9, v0
	s_lshl_b32 s11, s52, 8
	s_lshr_b32 s52, s9, 2
	s_lshl_b32 s56, s66, 8
	s_and_b32 s52, s52, 0x3fffc0
	s_ashr_i32 s57, s56, 31
	s_add_i32 s52, s52, s11
	s_lshl_b64 s[56:57], s[56:57], 1
	s_waitcnt lgkmcnt(0)
	s_add_u32 s11, s54, s56
	v_bfe_u32 v132, v0, 2, 4
	v_or_b32_e32 v132, s52, v132
	s_addc_u32 s52, s55, s57
	s_and_b32 s9, s9, 0xc0
	s_add_u32 s54, s11, s9
	s_addc_u32 s55, s52, 0
	v_and_b32_e32 v0, 3, v0
	v_lshlrev_b32_e32 v0, 4, v0
	v_lshl_add_u64 v[130:131], s[54:55], 0, v[0:1]
	s_mov_b64 s[54:55], 0x186d0800
	v_lshlrev_b32_e32 v0, 10, v132
	v_lshl_add_u64 v[162:163], v[130:131], 0, s[54:55]
	v_mov_b32_e32 v131, v1
	v_or_b32_e32 v130, 0x4000, v0
	v_lshl_add_u64 v[170:171], v[0:1], 1, v[162:163]
	v_lshl_add_u64 v[168:169], v[130:131], 1, v[162:163]
	global_load_dwordx4 v[174:177], v[170:171], off
	global_load_dwordx4 v[178:181], v[170:171], off offset:256
	global_load_dwordx4 v[182:185], v[168:169], off
	global_load_dwordx4 v[146:149], v[168:169], off offset:256
	v_or_b32_e32 v130, 0x8000, v0
	v_lshl_add_u64 v[166:167], v[130:131], 1, v[162:163]
	global_load_dwordx4 v[142:145], v[166:167], off
	v_or_b32_e32 v130, 0xc000, v0
	v_lshl_add_u64 v[164:165], v[130:131], 1, v[162:163]
	global_load_dwordx4 v[138:141], v[166:167], off offset:256
	global_load_dwordx4 v[134:137], v[164:165], off
	global_load_dwordx4 v[130:133], v[164:165], off offset:256
	s_andn2_b64 vcc, exec, s[2:3]
	s_mov_b64 s[2:3], -1
	s_waitcnt vmcnt(0)
; DEVI u32x4 pack8(const f32x4 a, const f32x4 b) { u32x4 w; w.x = cvtpk(a[0], a[1]); w.y = cvtpk(a[2], a[3]); w.z = cvtpk(b[0], b[1]); w.w = cvtpk(b[2], b[3]); return w; }
; DEVI f32x4 unpk_lo(const u32x4 w) { return (f32x4){bflo(w.x), bfhi(w.x), bflo(w.y), bfhi(w.y)}; }
; DEVI f32x4 unpk_hi(const u32x4 w) { return (f32x4){bflo(w.z), bfhi(w.z), bflo(w.w), bfhi(w.w)}; }
; #define FENCE() asm volatile("" ::: "memory")
;     DEVI void operator()(AccRef acc, const Unit& u, int wr, int wc, int fr, int fq) const {
;     ...
;                 for (int bj = 0; bj < 2; ++bj) w[m][bj] = *(const u32x4*)(gb + (unsigned)ROWOF(u) * 1024u + u.pn * 256 + bj * 128 + wc * 32 + 8 * fq);
; #pragma unroll
;             for (int m = 0; m < 4; ++m)
; #pragma unroll
;                 for (int bj = 0; bj < 2; ++bj)
;                     *(u32x4*)(gb + (unsigned)ROWOF(u) * 1024u + u.pn * 256 + bj * 128 + wc * 32 + 8 * fq) = pack8(acc[ai][bj][m][0] * unpk_lo(w[m][bj]), acc[ai][bj][m][1] * unpk_hi(w[m][bj]));
;             FENCE();
	v_lshlrev_b32_e32 v186, 16, v174
	v_and_b32_e32 v187, 0xffff0000, v174
	v_lshlrev_b32_e32 v174, 16, v175
	v_and_b32_e32 v175, 0xffff0000, v175
	v_lshlrev_b32_e32 v188, 16, v176
	v_and_b32_e32 v189, 0xffff0000, v176
	v_lshlrev_b32_e32 v176, 16, v177
	v_and_b32_e32 v177, 0xffff0000, v177
	v_lshlrev_b32_e32 v190, 16, v178
	v_and_b32_e32 v191, 0xffff0000, v178
	v_lshlrev_b32_e32 v178, 16, v179
	v_and_b32_e32 v179, 0xffff0000, v179
	v_lshlrev_b32_e32 v192, 16, v180
	v_and_b32_e32 v193, 0xffff0000, v180
	v_lshlrev_b32_e32 v180, 16, v181
	v_and_b32_e32 v181, 0xffff0000, v181
	v_lshlrev_b32_e32 v194, 16, v182
	v_and_b32_e32 v195, 0xffff0000, v182
	v_lshlrev_b32_e32 v182, 16, v183
	v_and_b32_e32 v183, 0xffff0000, v183
	v_lshlrev_b32_e32 v196, 16, v184
	v_and_b32_e32 v197, 0xffff0000, v184
	v_lshlrev_b32_e32 v184, 16, v185
	v_and_b32_e32 v185, 0xffff0000, v185
	v_lshlrev_b32_e32 v198, 16, v146
	v_and_b32_e32 v199, 0xffff0000, v146
	v_lshlrev_b32_e32 v146, 16, v147
	v_and_b32_e32 v147, 0xffff0000, v147
	v_pk_mul_f32 v[128:129], v[128:129], v[174:175]
	v_pk_mul_f32 v[126:127], v[126:127], v[186:187]
	v_pk_mul_f32 v[124:125], v[124:125], v[176:177]
	v_pk_mul_f32 v[122:123], v[122:123], v[188:189]
	v_pk_mul_f32 v[112:113], v[112:113], v[178:179]
	v_pk_mul_f32 v[110:111], v[110:111], v[190:191]
	v_pk_mul_f32 v[174:175], v[108:109], v[180:181]
	v_pk_mul_f32 v[176:177], v[106:107], v[192:193]
	v_pk_mul_f32 v[120:121], v[120:121], v[182:183]
	v_pk_mul_f32 v[118:119], v[118:119], v[194:195]
	v_pk_mul_f32 v[116:117], v[116:117], v[184:185]
	v_pk_mul_f32 v[114:115], v[114:115], v[196:197]
	v_pk_mul_f32 v[146:147], v[104:105], v[146:147]
	v_cvt_pk_bf16_f32 v104, v126, v127
	v_cvt_pk_bf16_f32 v105, v128, v129
	v_cvt_pk_bf16_f32 v106, v122, v123
	v_cvt_pk_bf16_f32 v107, v124, v125
	v_cvt_pk_bf16_f32 v108, v110, v111
	v_cvt_pk_bf16_f32 v109, v112, v113
	v_cvt_pk_bf16_f32 v110, v176, v177
	v_cvt_pk_bf16_f32 v111, v174, v175
	v_cvt_pk_bf16_f32 v112, v118, v119
	v_cvt_pk_bf16_f32 v113, v120, v121
	v_cvt_pk_bf16_f32 v114, v114, v115
	v_cvt_pk_bf16_f32 v115, v116, v117
	global_store_dwordx4 v[170:171], v[104:107], off
	global_store_dwordx4 v[170:171], v[108:111], off offset:256
	global_store_dwordx4 v[168:169], v[112:115], off
	v_lshlrev_b32_e32 v104, 16, v148
	v_and_b32_e32 v105, 0xffff0000, v148
	v_lshlrev_b32_e32 v106, 16, v149
	v_and_b32_e32 v107, 0xffff0000, v149
	v_pk_mul_f32 v[102:103], v[102:103], v[198:199]
	v_pk_mul_f32 v[106:107], v[96:97], v[106:107]
	v_pk_mul_f32 v[96:97], v[94:95], v[104:105]
	v_cvt_pk_bf16_f32 v94, v102, v103
	v_cvt_pk_bf16_f32 v95, v146, v147
	v_cvt_pk_bf16_f32 v96, v96, v97
	v_cvt_pk_bf16_f32 v97, v106, v107
	global_store_dwordx4 v[168:169], v[94:97], off offset:256
	s_nop 1
	v_lshlrev_b32_e32 v94, 16, v142
	v_and_b32_e32 v95, 0xffff0000, v142
	v_lshlrev_b32_e32 v96, 16, v143
	v_and_b32_e32 v97, 0xffff0000, v143
	v_pk_mul_f32 v[96:97], v[100:101], v[96:97]
	v_pk_mul_f32 v[94:95], v[98:99], v[94:95]
	v_lshlrev_b32_e32 v98, 16, v144
	v_and_b32_e32 v99, 0xffff0000, v144
	v_lshlrev_b32_e32 v100, 16, v145
	v_and_b32_e32 v101, 0xffff0000, v145
	v_pk_mul_f32 v[100:101], v[92:93], v[100:101]
	v_pk_mul_f32 v[92:93], v[90:91], v[98:99]
	v_cvt_pk_bf16_f32 v90, v94, v95
	v_cvt_pk_bf16_f32 v91, v96, v97
	v_cvt_pk_bf16_f32 v92, v92, v93
	v_cvt_pk_bf16_f32 v93, v100, v101
	global_store_dwordx4 v[166:167], v[90:93], off
	s_nop 1
	v_lshlrev_b32_e32 v90, 16, v138
	v_and_b32_e32 v91, 0xffff0000, v138
	v_lshlrev_b32_e32 v92, 16, v139
	v_and_b32_e32 v93, 0xffff0000, v139
	v_pk_mul_f32 v[88:89], v[88:89], v[92:93]
	v_pk_mul_f32 v[86:87], v[86:87], v[90:91]
	v_lshlrev_b32_e32 v90, 16, v140
	v_and_b32_e32 v91, 0xffff0000, v140
	v_lshlrev_b32_e32 v92, 16, v141
	v_and_b32_e32 v93, 0xffff0000, v141
	v_pk_mul_f32 v[92:93], v[80:81], v[92:93]
	v_pk_mul_f32 v[80:81], v[78:79], v[90:91]
	v_cvt_pk_bf16_f32 v78, v86, v87
	v_cvt_pk_bf16_f32 v79, v88, v89
	v_cvt_pk_bf16_f32 v80, v80, v81
	v_cvt_pk_bf16_f32 v81, v92, v93
	global_store_dwordx4 v[166:167], v[78:81], off offset:256
	s_nop 1
	v_lshlrev_b32_e32 v78, 16, v134
	v_and_b32_e32 v79, 0xffff0000, v134
	v_lshlrev_b32_e32 v80, 16, v135
	v_and_b32_e32 v81, 0xffff0000, v135
	v_pk_mul_f32 v[80:81], v[84:85], v[80:81]
	v_pk_mul_f32 v[78:79], v[82:83], v[78:79]
	v_lshlrev_b32_e32 v82, 16, v136
	v_and_b32_e32 v83, 0xffff0000, v136
	v_lshlrev_b32_e32 v84, 16, v137
	v_and_b32_e32 v85, 0xffff0000, v137
	v_pk_mul_f32 v[84:85], v[76:77], v[84:85]
	v_pk_mul_f32 v[76:77], v[74:75], v[82:83]
	v_cvt_pk_bf16_f32 v74, v78, v79
	v_cvt_pk_bf16_f32 v75, v80, v81
	v_cvt_pk_bf16_f32 v76, v76, v77
	v_cvt_pk_bf16_f32 v77, v84, v85
	global_store_dwordx4 v[164:165], v[74:77], off
	s_nop 1
	v_lshlrev_b32_e32 v74, 16, v130
	v_and_b32_e32 v75, 0xffff0000, v130
	v_lshlrev_b32_e32 v76, 16, v131
	v_and_b32_e32 v77, 0xffff0000, v131
	v_pk_mul_f32 v[72:73], v[72:73], v[76:77]
	v_pk_mul_f32 v[70:71], v[70:71], v[74:75]
	v_lshlrev_b32_e32 v74, 16, v132
	v_and_b32_e32 v75, 0xffff0000, v132
	v_lshlrev_b32_e32 v76, 16, v133
	v_and_b32_e32 v77, 0xffff0000, v133
	v_pk_mul_f32 v[76:77], v[68:69], v[76:77]
	v_pk_mul_f32 v[68:69], v[66:67], v[74:75]
	v_cvt_pk_bf16_f32 v66, v70, v71
	v_cvt_pk_bf16_f32 v67, v72, v73
	v_cvt_pk_bf16_f32 v68, v68, v69
	v_cvt_pk_bf16_f32 v69, v76, v77
	global_store_dwordx4 v[164:165], v[66:69], off offset:256
	s_nop 1
	v_add_u32_e32 v66, 0x20000, v0
	v_mov_b32_e32 v67, v1
	v_lshl_add_u64 v[100:101], v[66:67], 1, v[162:163]
	global_load_dwordx4 v[68:71], v[100:101], off
	global_load_dwordx4 v[72:75], v[100:101], off offset:256
	v_add_u32_e32 v66, 0x24000, v0
	v_lshl_add_u64 v[102:103], v[66:67], 1, v[162:163]
	global_load_dwordx4 v[76:79], v[102:103], off
	global_load_dwordx4 v[80:83], v[102:103], off offset:256
	v_add_u32_e32 v66, 0x28000, v0
	v_lshl_add_u64 v[104:105], v[66:67], 1, v[162:163]
	global_load_dwordx4 v[84:87], v[104:105], off
	global_load_dwordx4 v[88:91], v[104:105], off offset:256
	v_add_u32_e32 v0, 0x2c000, v0
	v_lshl_add_u64 v[66:67], v[0:1], 1, v[162:163]
	global_load_dwordx4 v[92:95], v[66:67], off
	global_load_dwordx4 v[96:99], v[66:67], off offset:256
	s_waitcnt vmcnt(7)
; DEVI u32x4 pack8(const f32x4 a, const f32x4 b) { u32x4 w; w.x = cvtpk(a[0], a[1]); w.y = cvtpk(a[2], a[3]); w.z = cvtpk(b[0], b[1]); w.w = cvtpk(b[2], b[3]); return w; }
; DEVI f32x4 unpk_lo(const u32x4 w) { return (f32x4){bflo(w.x), bfhi(w.x), bflo(w.y), bfhi(w.y)}; }
; DEVI f32x4 unpk_hi(const u32x4 w) { return (f32x4){bflo(w.z), bfhi(w.z), bflo(w.w), bfhi(w.w)}; }
; #define FENCE() asm volatile("" ::: "memory")
;     DEVI void operator()(AccRef acc, const Unit& u, int wr, int wc, int fr, int fq) const {
;     ...
;                 for (int bj = 0; bj < 2; ++bj) w[m][bj] = *(const u32x4*)(gb + (unsigned)ROWOF(u) * 1024u + u.pn * 256 + bj * 128 + wc * 32 + 8 * fq);
; #pragma unroll
;             for (int m = 0; m < 4; ++m)
; #pragma unroll
;                 for (int bj = 0; bj < 2; ++bj)
;                     *(u32x4*)(gb + (unsigned)ROWOF(u) * 1024u + u.pn * 256 + bj * 128 + wc * 32 + 8 * fq) = pack8(acc[ai][bj][m][0] * unpk_lo(w[m][bj]), acc[ai][bj][m][1] * unpk_hi(w[m][bj]));
;             FENCE();
	v_lshlrev_b32_e32 v106, 16, v68
	v_and_b32_e32 v107, 0xffff0000, v68
	v_lshlrev_b32_e32 v68, 16, v69
	v_and_b32_e32 v69, 0xffff0000, v69
	v_pk_mul_f32 v[64:65], v[64:65], v[68:69]
	v_lshlrev_b32_e32 v68, 16, v70
	v_and_b32_e32 v69, 0xffff0000, v70
	v_lshlrev_b32_e32 v70, 16, v71
	v_and_b32_e32 v71, 0xffff0000, v71
	v_pk_mul_f32 v[62:63], v[62:63], v[106:107]
	v_pk_mul_f32 v[70:71], v[60:61], v[70:71]
	v_pk_mul_f32 v[60:61], v[58:59], v[68:69]
	v_cvt_pk_bf16_f32 v58, v62, v63
	v_cvt_pk_bf16_f32 v59, v64, v65
	v_cvt_pk_bf16_f32 v60, v60, v61
	v_cvt_pk_bf16_f32 v61, v70, v71
	global_store_dwordx4 v[100:101], v[58:61], off
	s_waitcnt vmcnt(7)
	s_nop 0
	v_lshlrev_b32_e32 v58, 16, v72
	v_and_b32_e32 v59, 0xffff0000, v72
	v_lshlrev_b32_e32 v60, 16, v73
	v_and_b32_e32 v61, 0xffff0000, v73
	v_pk_mul_f32 v[56:57], v[56:57], v[60:61]
	v_pk_mul_f32 v[54:55], v[54:55], v[58:59]
	v_lshlrev_b32_e32 v58, 16, v74
	v_and_b32_e32 v59, 0xffff0000, v74
	v_lshlrev_b32_e32 v60, 16, v75
	v_and_b32_e32 v61, 0xffff0000, v75
	v_pk_mul_f32 v[60:61], v[48:49], v[60:61]
	v_pk_mul_f32 v[48:49], v[46:47], v[58:59]
	v_cvt_pk_bf16_f32 v46, v54, v55
	v_cvt_pk_bf16_f32 v47, v56, v57
	v_cvt_pk_bf16_f32 v48, v48, v49
	v_cvt_pk_bf16_f32 v49, v60, v61
	global_store_dwordx4 v[100:101], v[46:49], off offset:256
	s_waitcnt vmcnt(7)
	s_nop 0
	v_lshlrev_b32_e32 v46, 16, v76
	v_and_b32_e32 v47, 0xffff0000, v76
	v_lshlrev_b32_e32 v48, 16, v77
	v_and_b32_e32 v49, 0xffff0000, v77
	v_pk_mul_f32 v[48:49], v[52:53], v[48:49]
	v_pk_mul_f32 v[46:47], v[50:51], v[46:47]
	v_lshlrev_b32_e32 v50, 16, v78
	v_and_b32_e32 v51, 0xffff0000, v78
	v_lshlrev_b32_e32 v52, 16, v79
	v_and_b32_e32 v53, 0xffff0000, v79
	v_pk_mul_f32 v[52:53], v[44:45], v[52:53]
	v_pk_mul_f32 v[44:45], v[42:43], v[50:51]
	v_cvt_pk_bf16_f32 v42, v46, v47
	v_cvt_pk_bf16_f32 v43, v48, v49
	v_cvt_pk_bf16_f32 v44, v44, v45
	v_cvt_pk_bf16_f32 v45, v52, v53
	global_store_dwordx4 v[102:103], v[42:45], off
	s_waitcnt vmcnt(7)
	s_nop 0
	v_lshlrev_b32_e32 v42, 16, v80
	v_and_b32_e32 v43, 0xffff0000, v80
	v_lshlrev_b32_e32 v44, 16, v81
	v_and_b32_e32 v45, 0xffff0000, v81
	v_pk_mul_f32 v[40:41], v[40:41], v[44:45]
	v_pk_mul_f32 v[38:39], v[38:39], v[42:43]
	v_lshlrev_b32_e32 v42, 16, v82
	v_and_b32_e32 v43, 0xffff0000, v82
	v_lshlrev_b32_e32 v44, 16, v83
	v_and_b32_e32 v45, 0xffff0000, v83
	v_pk_mul_f32 v[44:45], v[32:33], v[44:45]
	v_pk_mul_f32 v[32:33], v[30:31], v[42:43]
	v_cvt_pk_bf16_f32 v30, v38, v39
	v_cvt_pk_bf16_f32 v31, v40, v41
	v_cvt_pk_bf16_f32 v32, v32, v33
	v_cvt_pk_bf16_f32 v33, v44, v45
	global_store_dwordx4 v[102:103], v[30:33], off offset:256
	s_waitcnt vmcnt(7)
	s_nop 0
	v_lshlrev_b32_e32 v30, 16, v84
	v_and_b32_e32 v31, 0xffff0000, v84
	v_lshlrev_b32_e32 v32, 16, v85
	v_and_b32_e32 v33, 0xffff0000, v85
	v_pk_mul_f32 v[32:33], v[36:37], v[32:33]
	v_pk_mul_f32 v[30:31], v[34:35], v[30:31]
	v_lshlrev_b32_e32 v34, 16, v86
	v_and_b32_e32 v35, 0xffff0000, v86
	v_lshlrev_b32_e32 v36, 16, v87
	v_and_b32_e32 v37, 0xffff0000, v87
	v_pk_mul_f32 v[36:37], v[28:29], v[36:37]
	v_pk_mul_f32 v[28:29], v[26:27], v[34:35]
	v_cvt_pk_bf16_f32 v26, v30, v31
	v_cvt_pk_bf16_f32 v27, v32, v33
	v_cvt_pk_bf16_f32 v28, v28, v29
	v_cvt_pk_bf16_f32 v29, v36, v37
	global_store_dwordx4 v[104:105], v[26:29], off
	s_waitcnt vmcnt(7)
	s_nop 0
	v_lshlrev_b32_e32 v26, 16, v88
	v_and_b32_e32 v27, 0xffff0000, v88
	v_lshlrev_b32_e32 v28, 16, v89
	v_and_b32_e32 v29, 0xffff0000, v89
	v_pk_mul_f32 v[24:25], v[24:25], v[28:29]
	v_pk_mul_f32 v[22:23], v[22:23], v[26:27]
	v_lshlrev_b32_e32 v26, 16, v90
	v_and_b32_e32 v27, 0xffff0000, v90
	v_lshlrev_b32_e32 v28, 16, v91
	v_and_b32_e32 v29, 0xffff0000, v91
	v_pk_mul_f32 v[28:29], v[16:17], v[28:29]
	v_pk_mul_f32 v[16:17], v[14:15], v[26:27]
	v_cvt_pk_bf16_f32 v14, v22, v23
	v_cvt_pk_bf16_f32 v15, v24, v25
	v_cvt_pk_bf16_f32 v16, v16, v17
	v_cvt_pk_bf16_f32 v17, v28, v29
	global_store_dwordx4 v[104:105], v[14:17], off offset:256
	s_waitcnt vmcnt(7)
	s_nop 0
	v_lshlrev_b32_e32 v14, 16, v92
	v_and_b32_e32 v15, 0xffff0000, v92
	v_lshlrev_b32_e32 v16, 16, v93
	v_and_b32_e32 v17, 0xffff0000, v93
	v_pk_mul_f32 v[16:17], v[20:21], v[16:17]
	v_pk_mul_f32 v[14:15], v[18:19], v[14:15]
	v_lshlrev_b32_e32 v18, 16, v94
	v_and_b32_e32 v19, 0xffff0000, v94
	v_lshlrev_b32_e32 v20, 16, v95
	v_and_b32_e32 v21, 0xffff0000, v95
	v_pk_mul_f32 v[20:21], v[12:13], v[20:21]
	v_pk_mul_f32 v[12:13], v[10:11], v[18:19]
	v_cvt_pk_bf16_f32 v10, v14, v15
	v_cvt_pk_bf16_f32 v11, v16, v17
	v_cvt_pk_bf16_f32 v12, v12, v13
	v_cvt_pk_bf16_f32 v13, v20, v21
	global_store_dwordx4 v[66:67], v[10:13], off
	s_waitcnt vmcnt(7)
	s_nop 0
	v_lshlrev_b32_e32 v10, 16, v96
	v_and_b32_e32 v11, 0xffff0000, v96
	v_lshlrev_b32_e32 v12, 16, v97
	v_and_b32_e32 v13, 0xffff0000, v97
	v_pk_mul_f32 v[8:9], v[8:9], v[12:13]
	v_pk_mul_f32 v[6:7], v[6:7], v[10:11]
	v_lshlrev_b32_e32 v10, 16, v98
	v_and_b32_e32 v11, 0xffff0000, v98
	v_lshlrev_b32_e32 v12, 16, v99
	v_and_b32_e32 v13, 0xffff0000, v99
	v_pk_mul_f32 v[12:13], v[4:5], v[12:13]
	v_pk_mul_f32 v[4:5], v[2:3], v[10:11]
	v_cvt_pk_bf16_f32 v2, v6, v7
	v_cvt_pk_bf16_f32 v3, v8, v9
	v_cvt_pk_bf16_f32 v4, v4, v5
	v_cvt_pk_bf16_f32 v5, v12, v13
	global_store_dwordx4 v[66:67], v[2:5], off offset:256
	s_cbranch_vccnz .LBB0_1389
	s_andn2_b64 vcc, exec, s[4:5]
	s_cbranch_vccnz .LBB0_1388
	s_barrier
	s_branch .LBB0_1388

; #define TID() tid_now(wv)
; DEVI unsigned char* WSP() { return *(unsigned char* const __attribute__((address_space(4)))*)(kargs() + 8 * 22); }
; template <class Epi, class Sched>
; __device__ __forceinline__ void gemm_phase(int wv, LAS unsigned char* lds, const Gemm g, const Sched& S, const Epi& E) {
;     ...
;         { const int t2 = TID(), w2 = __builtin_amdgcn_readfirstlane(t2 >> 6), l2 = t2 & 63; Unit eu = cur; eu.ks = 0; if (g.nNr) { eu.pn = cur.pn % g.nNr; eu.ks = cur.pn / g.nNr; } E(acc, eu, w2 >> 2, w2 & 3, l2 & 15, l2 >> 4); }
;     DEVI void operator()(AccRef acc, const Unit& u, int wr, int wc, int fr, int fq) const {
;         unsigned char* ws = WSP();
;         const bf16_t* ga = (const bf16_t*)(ws + O_GA); bf16_t* mb = (bf16_t*)(ws + O_GB);
.LBB0_1464:
	s_mov_b64 s[54:55], s[0:1]
	v_mbcnt_lo_u32_b32 v0, -1, 0
	v_mbcnt_hi_u32_b32 v0, -1, v0
	v_lshl_or_b32 v0, s33, 6, v0
	v_bfe_u32 v191, v0, 2, 4
	v_and_b32_e32 v190, 3, v0
	v_lshl_add_u32 v190, v190, 4, v191
	v_lshlrev_b32_e32 v190, 2, v190
	ds_bpermute_b32 v2, v190, v2
	ds_bpermute_b32 v3, v190, v3
	ds_bpermute_b32 v4, v190, v4
	ds_bpermute_b32 v5, v190, v5
	ds_bpermute_b32 v6, v190, v6
	ds_bpermute_b32 v7, v190, v7
	ds_bpermute_b32 v8, v190, v8
	ds_bpermute_b32 v9, v190, v9
	s_waitcnt lgkmcnt(7)
	ds_bpermute_b32 v10, v190, v10
	ds_bpermute_b32 v11, v190, v11
	ds_bpermute_b32 v12, v190, v12
	ds_bpermute_b32 v13, v190, v13
	ds_bpermute_b32 v14, v190, v14
	ds_bpermute_b32 v15, v190, v15
	ds_bpermute_b32 v16, v190, v16
	ds_bpermute_b32 v17, v190, v17
	s_waitcnt lgkmcnt(7)
	ds_bpermute_b32 v18, v190, v18
	ds_bpermute_b32 v19, v190, v19
	ds_bpermute_b32 v20, v190, v20
	ds_bpermute_b32 v21, v190, v21
	ds_bpermute_b32 v22, v190, v22
	ds_bpermute_b32 v23, v190, v23
	ds_bpermute_b32 v24, v190, v24
	ds_bpermute_b32 v25, v190, v25
	s_waitcnt lgkmcnt(7)
	ds_bpermute_b32 v26, v190, v26
	ds_bpermute_b32 v27, v190, v27
	ds_bpermute_b32 v28, v190, v28
	ds_bpermute_b32 v29, v190, v29
	ds_bpermute_b32 v30, v190, v30
	ds_bpermute_b32 v31, v190, v31
	ds_bpermute_b32 v32, v190, v32
	ds_bpermute_b32 v33, v190, v33
	s_waitcnt lgkmcnt(7)
	ds_bpermute_b32 v34, v190, v34
	ds_bpermute_b32 v35, v190, v35
	ds_bpermute_b32 v36, v190, v36
	ds_bpermute_b32 v37, v190, v37
	ds_bpermute_b32 v38, v190, v38
	ds_bpermute_b32 v39, v190, v39
	ds_bpermute_b32 v40, v190, v40
	ds_bpermute_b32 v41, v190, v41
	s_waitcnt lgkmcnt(7)
	ds_bpermute_b32 v42, v190, v42
	ds_bpermute_b32 v43, v190, v43
	ds_bpermute_b32 v44, v190, v44
	ds_bpermute_b32 v45, v190, v45
	ds_bpermute_b32 v46, v190, v46
	ds_bpermute_b32 v47, v190, v47
	ds_bpermute_b32 v48, v190, v48
	ds_bpermute_b32 v49, v190, v49
	s_waitcnt lgkmcnt(7)
	ds_bpermute_b32 v50, v190, v50
	ds_bpermute_b32 v51, v190, v51
	ds_bpermute_b32 v52, v190, v52
	ds_bpermute_b32 v53, v190, v53
	ds_bpermute_b32 v54, v190, v54
	ds_bpermute_b32 v55, v190, v55
	ds_bpermute_b32 v56, v190, v56
	ds_bpermute_b32 v57, v190, v57
	s_waitcnt lgkmcnt(7)
	ds_bpermute_b32 v58, v190, v58
	ds_bpermute_b32 v59, v190, v59
	ds_bpermute_b32 v60, v190, v60
	ds_bpermute_b32 v61, v190, v61
	ds_bpermute_b32 v62, v190, v62
	ds_bpermute_b32 v63, v190, v63
	ds_bpermute_b32 v64, v190, v64
	ds_bpermute_b32 v65, v190, v65
	s_waitcnt lgkmcnt(7)
	ds_bpermute_b32 v66, v190, v66
	ds_bpermute_b32 v67, v190, v67
	ds_bpermute_b32 v68, v190, v68
	ds_bpermute_b32 v69, v190, v69
	ds_bpermute_b32 v70, v190, v70
	ds_bpermute_b32 v71, v190, v71
	ds_bpermute_b32 v72, v190, v72
	ds_bpermute_b32 v73, v190, v73
	s_waitcnt lgkmcnt(7)
	ds_bpermute_b32 v74, v190, v74
	ds_bpermute_b32 v75, v190, v75
	ds_bpermute_b32 v76, v190, v76
	ds_bpermute_b32 v77, v190, v77
	ds_bpermute_b32 v78, v190, v78
	ds_bpermute_b32 v79, v190, v79
	ds_bpermute_b32 v80, v190, v80
	ds_bpermute_b32 v81, v190, v81
	s_waitcnt lgkmcnt(7)
	ds_bpermute_b32 v82, v190, v82
	ds_bpermute_b32 v83, v190, v83
	ds_bpermute_b32 v84, v190, v84
	ds_bpermute_b32 v85, v190, v85
	ds_bpermute_b32 v86, v190, v86
	ds_bpermute_b32 v87, v190, v87
	ds_bpermute_b32 v88, v190, v88
	ds_bpermute_b32 v89, v190, v89
	s_waitcnt lgkmcnt(7)
	ds_bpermute_b32 v90, v190, v90
	ds_bpermute_b32 v91, v190, v91
	ds_bpermute_b32 v92, v190, v92
	ds_bpermute_b32 v93, v190, v93
	ds_bpermute_b32 v94, v190, v94
	ds_bpermute_b32 v95, v190, v95
	ds_bpermute_b32 v96, v190, v96
	ds_bpermute_b32 v97, v190, v97
	s_waitcnt lgkmcnt(7)
	ds_bpermute_b32 v98, v190, v98
	ds_bpermute_b32 v99, v190, v99
	ds_bpermute_b32 v100, v190, v100
	ds_bpermute_b32 v101, v190, v101
	ds_bpermute_b32 v102, v190, v102
	ds_bpermute_b32 v103, v190, v103
	ds_bpermute_b32 v104, v190, v104
	ds_bpermute_b32 v105, v190, v105
	s_waitcnt lgkmcnt(7)
	ds_bpermute_b32 v106, v190, v106
	ds_bpermute_b32 v107, v190, v107
	ds_bpermute_b32 v108, v190, v108
	ds_bpermute_b32 v109, v190, v109
	ds_bpermute_b32 v110, v190, v110
	ds_bpermute_b32 v111, v190, v111
	ds_bpermute_b32 v112, v190, v112
	ds_bpermute_b32 v113, v190, v113
	s_waitcnt lgkmcnt(7)
	ds_bpermute_b32 v114, v190, v114
	ds_bpermute_b32 v115, v190, v115
	ds_bpermute_b32 v116, v190, v116
	ds_bpermute_b32 v117, v190, v117
	ds_bpermute_b32 v118, v190, v118
	ds_bpermute_b32 v119, v190, v119
	ds_bpermute_b32 v120, v190, v120
	ds_bpermute_b32 v121, v190, v121
	s_waitcnt lgkmcnt(7)
	ds_bpermute_b32 v122, v190, v122
	ds_bpermute_b32 v123, v190, v123
	ds_bpermute_b32 v124, v190, v124
	ds_bpermute_b32 v125, v190, v125
	ds_bpermute_b32 v126, v190, v126
	ds_bpermute_b32 v127, v190, v127
	ds_bpermute_b32 v128, v190, v128
	ds_bpermute_b32 v129, v190, v129
	s_waitcnt lgkmcnt(0)
	s_load_dwordx2 s[54:55], s[54:55], 0xb0
	v_readfirstlane_b32 s9, v0
	v_mov_b32_e32 v171, v1
	s_waitcnt lgkmcnt(0)
; DEVI u32x4 pack8(const f32x4 a, const f32x4 b) { u32x4 w; w.x = cvtpk(a[0], a[1]); w.y = cvtpk(a[2], a[3]); w.z = cvtpk(b[0], b[1]); w.w = cvtpk(b[2], b[3]); return w; }
; DEVI f32x4 unpk_lo(const u32x4 w) { return (f32x4){bflo(w.x), bfhi(w.x), bflo(w.y), bfhi(w.y)}; }
; DEVI f32x4 unpk_hi(const u32x4 w) { return (f32x4){bflo(w.z), bfhi(w.z), bflo(w.w), bfhi(w.w)}; }
;     DEVI void operator()(AccRef acc, const Unit& u, int wr, int wc, int fr, int fq) const {
;     ...
;         for (int ai = 0; ai < 2; ++ai) {
;             u32x4 g[4][2], w[4][2];
; #pragma unroll
;             for (int m = 0; m < 4; ++m)
; #pragma unroll
;                 for (int bj = 0; bj < 2; ++bj) { const unsigned off = (unsigned)ROWOF(u) * 1024u + u.pn * 256 + bj * 128 + wc * 32 + 8 * fq; g[m][bj] = *(const u32x4*)(ga + off); w[m][bj] = *(const u32x4*)(mb + off); }
; #pragma unroll
;             for (int m = 0; m < 4; ++m)
; #pragma unroll
;                 for (int bj = 0; bj < 2; ++bj) { const unsigned off = (unsigned)ROWOF(u) * 1024u + u.pn * 256 + bj * 128 + wc * 32 + 8 * fq;
;                     *(u32x4*)(mb + off) = pack8(acc[ai][bj][m][0] * unpk_lo(g[m][bj]) + unpk_lo(w[m][bj]), acc[ai][bj][m][1] * unpk_hi(g[m][bj]) + unpk_hi(w[m][bj])); }
	s_add_u32 s56, s54, 0x145d0800
	s_addc_u32 s57, s55, 0
	s_add_u32 s54, s54, 0x186d0800
	s_addc_u32 s55, s55, 0
	s_lshl_b32 s11, s52, 8
	s_lshr_b32 s52, s9, 2
	s_and_b32 s52, s52, 0x3fffc0
	s_lshr_b32 s9, s9, 1
	s_add_i32 s52, s52, s11
	s_lshl_b32 s11, s53, 8
	s_and_b32 s9, s9, 0x60
	v_bfe_u32 v130, v0, 2, 4
	v_or_b32_e32 v130, s52, v130
	s_or_b32 s9, s9, s11
	v_and_b32_e32 v0, 3, v0
	v_lshl_or_b32 v0, v0, 3, s9
	v_lshl_add_u32 v0, v130, 10, v0
	v_lshlrev_b64 v[130:131], 1, v[0:1]
	v_lshl_add_u64 v[132:133], s[56:57], 0, v[130:131]
	v_lshl_add_u64 v[230:231], s[54:55], 0, v[130:131]
	global_load_dwordx4 v[190:193], v[132:133], off
	global_load_dwordx4 v[186:189], v[230:231], off
	v_add_u32_e32 v170, 0xc080, v0
	v_or_b32_e32 v130, 0x80, v0
	v_mov_b32_e32 v131, v1
	v_lshlrev_b64 v[182:183], 1, v[170:171]
	v_lshlrev_b64 v[130:131], 1, v[130:131]
	v_lshl_add_u64 v[170:171], s[56:57], 0, v[182:183]
	v_lshl_add_u64 v[228:229], s[54:55], 0, v[130:131]
	global_load_dwordx4 v[170:173], v[170:171], off
	v_lshl_add_u64 v[132:133], s[56:57], 0, v[130:131]
	global_load_dwordx4 v[178:181], v[132:133], off
	global_load_dwordx4 v[174:177], v[228:229], off
	v_add_u32_e32 v130, 0x4000, v0
	v_mov_b32_e32 v131, v1
	v_lshlrev_b64 v[130:131], 1, v[130:131]
	v_lshl_add_u64 v[224:225], s[54:55], 0, v[130:131]
	global_load_dwordx4 v[162:165], v[224:225], off
	v_lshl_add_u64 v[132:133], s[56:57], 0, v[130:131]
	global_load_dwordx4 v[166:169], v[132:133], off
	v_add_u32_e32 v130, 0x4080, v0
	v_mov_b32_e32 v131, v1
	v_lshlrev_b64 v[130:131], 1, v[130:131]
	v_lshl_add_u64 v[222:223], s[54:55], 0, v[130:131]
	global_load_dwordx4 v[154:157], v[222:223], off
	v_lshl_add_u64 v[132:133], s[56:57], 0, v[130:131]
	global_load_dwordx4 v[158:161], v[132:133], off
	v_add_u32_e32 v130, 0x8000, v0
	v_mov_b32_e32 v131, v1
	v_lshlrev_b64 v[130:131], 1, v[130:131]
	v_lshl_add_u64 v[220:221], s[54:55], 0, v[130:131]
	global_load_dwordx4 v[146:149], v[220:221], off
	v_lshl_add_u64 v[132:133], s[56:57], 0, v[130:131]
	global_load_dwordx4 v[150:153], v[132:133], off
	v_add_u32_e32 v130, 0x8080, v0
	v_mov_b32_e32 v131, v1
	v_lshlrev_b64 v[130:131], 1, v[130:131]
	v_lshl_add_u64 v[218:219], s[54:55], 0, v[130:131]
	global_load_dwordx4 v[138:141], v[218:219], off
	v_lshl_add_u64 v[132:133], s[56:57], 0, v[130:131]
	global_load_dwordx4 v[142:145], v[132:133], off
	v_add_u32_e32 v130, 0xc000, v0
	v_mov_b32_e32 v131, v1
	v_lshlrev_b64 v[130:131], 1, v[130:131]
	v_lshl_add_u64 v[226:227], s[54:55], 0, v[182:183]
	v_lshl_add_u64 v[216:217], s[54:55], 0, v[130:131]
	global_load_dwordx4 v[182:185], v[226:227], off
	v_lshl_add_u64 v[132:133], s[56:57], 0, v[130:131]
	global_load_dwordx4 v[134:137], v[132:133], off
	s_mov_b64 s[52:53], -1
	global_load_dwordx4 v[130:133], v[216:217], off
	s_andn2_b64 vcc, exec, s[2:3]
	s_waitcnt vmcnt(0)
	v_lshlrev_b32_e32 v194, 16, v190
	v_and_b32_e32 v195, 0xffff0000, v190
	v_lshlrev_b32_e32 v190, 16, v191
	v_and_b32_e32 v191, 0xffff0000, v191
	v_lshlrev_b32_e32 v196, 16, v186
	v_and_b32_e32 v197, 0xffff0000, v186
	v_lshlrev_b32_e32 v186, 16, v187
	v_and_b32_e32 v187, 0xffff0000, v187
	v_pk_fma_f32 v[128:129], v[128:129], v[190:191], v[186:187]
	v_lshlrev_b32_e32 v186, 16, v192
	v_and_b32_e32 v187, 0xffff0000, v192
	v_lshlrev_b32_e32 v190, 16, v193
	v_and_b32_e32 v191, 0xffff0000, v193
	v_lshlrev_b32_e32 v192, 16, v188
	v_and_b32_e32 v193, 0xffff0000, v188
	v_lshlrev_b32_e32 v188, 16, v189
	v_and_b32_e32 v189, 0xffff0000, v189
	v_pk_fma_f32 v[126:127], v[126:127], v[194:195], v[196:197]
	v_pk_fma_f32 v[188:189], v[124:125], v[190:191], v[188:189]
	v_pk_fma_f32 v[124:125], v[122:123], v[186:187], v[192:193]
	v_cvt_pk_bf16_f32 v122, v126, v127
	v_cvt_pk_bf16_f32 v123, v128, v129
	v_cvt_pk_bf16_f32 v124, v124, v125
	v_cvt_pk_bf16_f32 v125, v188, v189
	global_store_dwordx4 v[230:231], v[122:125], off
	v_lshlrev_b32_e32 v126, 16, v174
	v_and_b32_e32 v127, 0xffff0000, v174
	v_lshlrev_b32_e32 v122, 16, v178
	v_and_b32_e32 v123, 0xffff0000, v178
	v_lshlrev_b32_e32 v124, 16, v179
	v_and_b32_e32 v125, 0xffff0000, v179
	v_lshlrev_b32_e32 v128, 16, v175
	v_and_b32_e32 v129, 0xffff0000, v175
	v_pk_fma_f32 v[120:121], v[120:121], v[124:125], v[128:129]
	v_pk_fma_f32 v[118:119], v[118:119], v[122:123], v[126:127]
	v_lshlrev_b32_e32 v122, 16, v180
	v_and_b32_e32 v123, 0xffff0000, v180
	v_lshlrev_b32_e32 v124, 16, v181
	v_and_b32_e32 v125, 0xffff0000, v181
	v_lshlrev_b32_e32 v126, 16, v176
	v_and_b32_e32 v127, 0xffff0000, v176
	v_lshlrev_b32_e32 v128, 16, v177
	v_and_b32_e32 v129, 0xffff0000, v177
	v_pk_fma_f32 v[124:125], v[116:117], v[124:125], v[128:129]
	v_pk_fma_f32 v[116:117], v[114:115], v[122:123], v[126:127]
	v_cvt_pk_bf16_f32 v114, v118, v119
	v_cvt_pk_bf16_f32 v115, v120, v121
	v_cvt_pk_bf16_f32 v116, v116, v117
	v_cvt_pk_bf16_f32 v117, v124, v125
	global_store_dwordx4 v[228:229], v[114:117], off
	v_lshlrev_b32_e32 v118, 16, v162
	v_and_b32_e32 v119, 0xffff0000, v162
	v_lshlrev_b32_e32 v114, 16, v166
	v_and_b32_e32 v115, 0xffff0000, v166
	v_lshlrev_b32_e32 v116, 16, v167
	v_and_b32_e32 v117, 0xffff0000, v167
	v_lshlrev_b32_e32 v120, 16, v163
	v_and_b32_e32 v121, 0xffff0000, v163
	v_pk_fma_f32 v[112:113], v[112:113], v[116:117], v[120:121]
	v_pk_fma_f32 v[110:111], v[110:111], v[114:115], v[118:119]
	v_lshlrev_b32_e32 v114, 16, v168
	v_and_b32_e32 v115, 0xffff0000, v168
	v_lshlrev_b32_e32 v116, 16, v169
	v_and_b32_e32 v117, 0xffff0000, v169
	v_lshlrev_b32_e32 v118, 16, v164
	v_and_b32_e32 v119, 0xffff0000, v164
	v_lshlrev_b32_e32 v120, 16, v165
	v_and_b32_e32 v121, 0xffff0000, v165
	v_pk_fma_f32 v[116:117], v[108:109], v[116:117], v[120:121]
; DEVI u32x4 pack8(const f32x4 a, const f32x4 b) { u32x4 w; w.x = cvtpk(a[0], a[1]); w.y = cvtpk(a[2], a[3]); w.z = cvtpk(b[0], b[1]); w.w = cvtpk(b[2], b[3]); return w; }
; DEVI f32x4 unpk_lo(const u32x4 w) { return (f32x4){bflo(w.x), bfhi(w.x), bflo(w.y), bfhi(w.y)}; }
; DEVI f32x4 unpk_hi(const u32x4 w) { return (f32x4){bflo(w.z), bfhi(w.z), bflo(w.w), bfhi(w.w)}; }
;     DEVI void operator()(AccRef acc, const Unit& u, int wr, int wc, int fr, int fq) const {
;     ...
;         for (int ai = 0; ai < 2; ++ai) {
;             u32x4 g[4][2], w[4][2];
; #pragma unroll
;             for (int m = 0; m < 4; ++m)
; #pragma unroll
;                 for (int bj = 0; bj < 2; ++bj) { const unsigned off = (unsigned)ROWOF(u) * 1024u + u.pn * 256 + bj * 128 + wc * 32 + 8 * fq; g[m][bj] = *(const u32x4*)(ga + off); w[m][bj] = *(const u32x4*)(mb + off); }
; #pragma unroll
;             for (int m = 0; m < 4; ++m)
; #pragma unroll
;                 for (int bj = 0; bj < 2; ++bj) { const unsigned off = (unsigned)ROWOF(u) * 1024u + u.pn * 256 + bj * 128 + wc * 32 + 8 * fq;
;                     *(u32x4*)(mb + off) = pack8(acc[ai][bj][m][0] * unpk_lo(g[m][bj]) + unpk_lo(w[m][bj]), acc[ai][bj][m][1] * unpk_hi(g[m][bj]) + unpk_hi(w[m][bj])); }
	v_pk_fma_f32 v[108:109], v[106:107], v[114:115], v[118:119]
	v_cvt_pk_bf16_f32 v106, v110, v111
	v_cvt_pk_bf16_f32 v107, v112, v113
	v_cvt_pk_bf16_f32 v108, v108, v109
	v_cvt_pk_bf16_f32 v109, v116, v117
	global_store_dwordx4 v[224:225], v[106:109], off
	v_lshlrev_b32_e32 v110, 16, v154
	v_and_b32_e32 v111, 0xffff0000, v154
	v_lshlrev_b32_e32 v106, 16, v158
	v_and_b32_e32 v107, 0xffff0000, v158
	v_lshlrev_b32_e32 v108, 16, v159
	v_and_b32_e32 v109, 0xffff0000, v159
	v_lshlrev_b32_e32 v112, 16, v155
	v_and_b32_e32 v113, 0xffff0000, v155
	v_pk_fma_f32 v[104:105], v[104:105], v[108:109], v[112:113]
	v_pk_fma_f32 v[102:103], v[102:103], v[106:107], v[110:111]
	v_lshlrev_b32_e32 v106, 16, v160
	v_and_b32_e32 v107, 0xffff0000, v160
	v_lshlrev_b32_e32 v108, 16, v161
	v_and_b32_e32 v109, 0xffff0000, v161
	v_lshlrev_b32_e32 v110, 16, v156
	v_and_b32_e32 v111, 0xffff0000, v156
	v_lshlrev_b32_e32 v112, 16, v157
	v_and_b32_e32 v113, 0xffff0000, v157
	v_pk_fma_f32 v[108:109], v[100:101], v[108:109], v[112:113]
	v_pk_fma_f32 v[100:101], v[98:99], v[106:107], v[110:111]
	v_cvt_pk_bf16_f32 v98, v102, v103
	v_cvt_pk_bf16_f32 v99, v104, v105
	v_cvt_pk_bf16_f32 v100, v100, v101
	v_cvt_pk_bf16_f32 v101, v108, v109
	global_store_dwordx4 v[222:223], v[98:101], off
	v_lshlrev_b32_e32 v102, 16, v146
	v_and_b32_e32 v103, 0xffff0000, v146
	v_lshlrev_b32_e32 v98, 16, v150
	v_and_b32_e32 v99, 0xffff0000, v150
	v_lshlrev_b32_e32 v100, 16, v151
	v_and_b32_e32 v101, 0xffff0000, v151
	v_lshlrev_b32_e32 v104, 16, v147
	v_and_b32_e32 v105, 0xffff0000, v147
	v_pk_fma_f32 v[96:97], v[96:97], v[100:101], v[104:105]
	v_pk_fma_f32 v[94:95], v[94:95], v[98:99], v[102:103]
	v_lshlrev_b32_e32 v98, 16, v152
	v_and_b32_e32 v99, 0xffff0000, v152
	v_lshlrev_b32_e32 v100, 16, v153
	v_and_b32_e32 v101, 0xffff0000, v153
	v_lshlrev_b32_e32 v102, 16, v148
	v_and_b32_e32 v103, 0xffff0000, v148
	v_lshlrev_b32_e32 v104, 16, v149
	v_and_b32_e32 v105, 0xffff0000, v149
	v_pk_fma_f32 v[100:101], v[92:93], v[100:101], v[104:105]
	v_pk_fma_f32 v[92:93], v[90:91], v[98:99], v[102:103]
	v_cvt_pk_bf16_f32 v90, v94, v95
	v_cvt_pk_bf16_f32 v91, v96, v97
	v_cvt_pk_bf16_f32 v92, v92, v93
	v_cvt_pk_bf16_f32 v93, v100, v101
	global_store_dwordx4 v[220:221], v[90:93], off
	v_lshlrev_b32_e32 v94, 16, v138
	v_and_b32_e32 v95, 0xffff0000, v138
	v_lshlrev_b32_e32 v90, 16, v142
	v_and_b32_e32 v91, 0xffff0000, v142
	v_lshlrev_b32_e32 v92, 16, v143
	v_and_b32_e32 v93, 0xffff0000, v143
	v_lshlrev_b32_e32 v96, 16, v139
	v_and_b32_e32 v97, 0xffff0000, v139
	v_pk_fma_f32 v[88:89], v[88:89], v[92:93], v[96:97]
	v_pk_fma_f32 v[86:87], v[86:87], v[90:91], v[94:95]
	v_lshlrev_b32_e32 v90, 16, v144
	v_and_b32_e32 v91, 0xffff0000, v144
	v_lshlrev_b32_e32 v92, 16, v145
	v_and_b32_e32 v93, 0xffff0000, v145
	v_lshlrev_b32_e32 v94, 16, v140
	v_and_b32_e32 v95, 0xffff0000, v140
	v_lshlrev_b32_e32 v96, 16, v141
	v_and_b32_e32 v97, 0xffff0000, v141
	v_pk_fma_f32 v[92:93], v[84:85], v[92:93], v[96:97]
	v_pk_fma_f32 v[84:85], v[82:83], v[90:91], v[94:95]
	v_cvt_pk_bf16_f32 v82, v86, v87
	v_cvt_pk_bf16_f32 v83, v88, v89
	v_cvt_pk_bf16_f32 v84, v84, v85
	v_cvt_pk_bf16_f32 v85, v92, v93
	global_store_dwordx4 v[218:219], v[82:85], off
	v_lshlrev_b32_e32 v86, 16, v130
	v_and_b32_e32 v87, 0xffff0000, v130
	v_lshlrev_b32_e32 v82, 16, v134
	v_and_b32_e32 v83, 0xffff0000, v134
	v_lshlrev_b32_e32 v84, 16, v135
	v_and_b32_e32 v85, 0xffff0000, v135
	v_lshlrev_b32_e32 v88, 16, v131
	v_and_b32_e32 v89, 0xffff0000, v131
	v_pk_fma_f32 v[80:81], v[80:81], v[84:85], v[88:89]
	v_pk_fma_f32 v[78:79], v[78:79], v[82:83], v[86:87]
	v_lshlrev_b32_e32 v82, 16, v136
	v_and_b32_e32 v83, 0xffff0000, v136
	v_lshlrev_b32_e32 v84, 16, v137
	v_and_b32_e32 v85, 0xffff0000, v137
	v_lshlrev_b32_e32 v86, 16, v132
	v_and_b32_e32 v87, 0xffff0000, v132
	v_lshlrev_b32_e32 v88, 16, v133
	v_and_b32_e32 v89, 0xffff0000, v133
	v_pk_fma_f32 v[84:85], v[76:77], v[84:85], v[88:89]
	v_pk_fma_f32 v[76:77], v[74:75], v[82:83], v[86:87]
	v_cvt_pk_bf16_f32 v74, v78, v79
	v_cvt_pk_bf16_f32 v75, v80, v81
	v_cvt_pk_bf16_f32 v76, v76, v77
	v_cvt_pk_bf16_f32 v77, v84, v85
	global_store_dwordx4 v[216:217], v[74:77], off
	v_lshlrev_b32_e32 v78, 16, v182
	v_and_b32_e32 v79, 0xffff0000, v182
	v_lshlrev_b32_e32 v74, 16, v170
	v_and_b32_e32 v75, 0xffff0000, v170
	v_lshlrev_b32_e32 v76, 16, v171
	v_and_b32_e32 v77, 0xffff0000, v171
	v_lshlrev_b32_e32 v80, 16, v183
	v_and_b32_e32 v81, 0xffff0000, v183
	v_pk_fma_f32 v[72:73], v[72:73], v[76:77], v[80:81]
	v_pk_fma_f32 v[70:71], v[70:71], v[74:75], v[78:79]
	v_lshlrev_b32_e32 v74, 16, v172
	v_and_b32_e32 v75, 0xffff0000, v172
	v_lshlrev_b32_e32 v76, 16, v173
	v_and_b32_e32 v77, 0xffff0000, v173
	v_lshlrev_b32_e32 v78, 16, v184
	v_and_b32_e32 v79, 0xffff0000, v184
	v_lshlrev_b32_e32 v80, 16, v185
	v_and_b32_e32 v81, 0xffff0000, v185
	v_pk_fma_f32 v[76:77], v[68:69], v[76:77], v[80:81]
	v_pk_fma_f32 v[68:69], v[66:67], v[74:75], v[78:79]
	v_cvt_pk_bf16_f32 v66, v70, v71
	v_cvt_pk_bf16_f32 v67, v72, v73
	v_cvt_pk_bf16_f32 v68, v68, v69
	v_cvt_pk_bf16_f32 v69, v76, v77
	global_store_dwordx4 v[226:227], v[66:69], off
	s_nop 1
	v_add_u32_e32 v66, 0x20000, v0
	v_mov_b32_e32 v67, v1
	v_lshlrev_b64 v[66:67], 1, v[66:67]
	v_lshl_add_u64 v[68:69], s[56:57], 0, v[66:67]
	v_lshl_add_u64 v[140:141], s[54:55], 0, v[66:67]
	global_load_dwordx4 v[108:111], v[68:69], off
	global_load_dwordx4 v[112:115], v[140:141], off
	v_add_u32_e32 v66, 0x20080, v0
	v_mov_b32_e32 v67, v1
	v_lshlrev_b64 v[66:67], 1, v[66:67]
	v_lshl_add_u64 v[68:69], s[56:57], 0, v[66:67]
	v_lshl_add_u64 v[142:143], s[54:55], 0, v[66:67]
	global_load_dwordx4 v[116:119], v[68:69], off
; DEVI u32x4 pack8(const f32x4 a, const f32x4 b) { u32x4 w; w.x = cvtpk(a[0], a[1]); w.y = cvtpk(a[2], a[3]); w.z = cvtpk(b[0], b[1]); w.w = cvtpk(b[2], b[3]); return w; }
; DEVI f32x4 unpk_lo(const u32x4 w) { return (f32x4){bflo(w.x), bfhi(w.x), bflo(w.y), bfhi(w.y)}; }
; DEVI f32x4 unpk_hi(const u32x4 w) { return (f32x4){bflo(w.z), bfhi(w.z), bflo(w.w), bfhi(w.w)}; }
;     DEVI void operator()(AccRef acc, const Unit& u, int wr, int wc, int fr, int fq) const {
;     ...
;         for (int ai = 0; ai < 2; ++ai) {
;             u32x4 g[4][2], w[4][2];
; #pragma unroll
;             for (int m = 0; m < 4; ++m)
; #pragma unroll
;                 for (int bj = 0; bj < 2; ++bj) { const unsigned off = (unsigned)ROWOF(u) * 1024u + u.pn * 256 + bj * 128 + wc * 32 + 8 * fq; g[m][bj] = *(const u32x4*)(ga + off); w[m][bj] = *(const u32x4*)(mb + off); }
; #pragma unroll
;             for (int m = 0; m < 4; ++m)
; #pragma unroll
;                 for (int bj = 0; bj < 2; ++bj) { const unsigned off = (unsigned)ROWOF(u) * 1024u + u.pn * 256 + bj * 128 + wc * 32 + 8 * fq;
;                     *(u32x4*)(mb + off) = pack8(acc[ai][bj][m][0] * unpk_lo(g[m][bj]) + unpk_lo(w[m][bj]), acc[ai][bj][m][1] * unpk_hi(g[m][bj]) + unpk_hi(w[m][bj])); }
	global_load_dwordx4 v[120:123], v[142:143], off
	v_add_u32_e32 v66, 0x24000, v0
	v_mov_b32_e32 v67, v1
	v_lshlrev_b64 v[66:67], 1, v[66:67]
	v_lshl_add_u64 v[68:69], s[56:57], 0, v[66:67]
	v_lshl_add_u64 v[144:145], s[54:55], 0, v[66:67]
	global_load_dwordx4 v[124:127], v[68:69], off
	global_load_dwordx4 v[128:131], v[144:145], off
	v_add_u32_e32 v66, 0x24080, v0
	v_mov_b32_e32 v67, v1
	v_lshlrev_b64 v[66:67], 1, v[66:67]
	v_lshl_add_u64 v[106:107], s[54:55], 0, v[66:67]
	global_load_dwordx4 v[136:139], v[106:107], off
	v_lshl_add_u64 v[68:69], s[56:57], 0, v[66:67]
	global_load_dwordx4 v[132:135], v[68:69], off
	v_add_u32_e32 v66, 0x28000, v0
	v_mov_b32_e32 v67, v1
	v_lshlrev_b64 v[66:67], 1, v[66:67]
	v_lshl_add_u64 v[104:105], s[54:55], 0, v[66:67]
	global_load_dwordx4 v[94:97], v[104:105], off
	v_lshl_add_u64 v[68:69], s[56:57], 0, v[66:67]
	global_load_dwordx4 v[90:93], v[68:69], off
	v_add_u32_e32 v66, 0x28080, v0
	v_mov_b32_e32 v67, v1
	v_lshlrev_b64 v[66:67], 1, v[66:67]
	v_lshl_add_u64 v[102:103], s[54:55], 0, v[66:67]
	global_load_dwordx4 v[86:89], v[102:103], off
	v_lshl_add_u64 v[68:69], s[56:57], 0, v[66:67]
	global_load_dwordx4 v[82:85], v[68:69], off
	v_add_u32_e32 v66, 0x2c000, v0
	v_mov_b32_e32 v67, v1
	v_lshlrev_b64 v[66:67], 1, v[66:67]
	v_lshl_add_u64 v[100:101], s[54:55], 0, v[66:67]
	global_load_dwordx4 v[78:81], v[100:101], off
	v_lshl_add_u64 v[68:69], s[56:57], 0, v[66:67]
	global_load_dwordx4 v[74:77], v[68:69], off
	v_add_u32_e32 v0, 0x2c080, v0
	v_lshlrev_b64 v[70:71], 1, v[0:1]
	v_lshl_add_u64 v[66:67], s[56:57], 0, v[70:71]
	v_lshl_add_u64 v[98:99], s[54:55], 0, v[70:71]
	global_load_dwordx4 v[66:69], v[66:67], off
	s_waitcnt vmcnt(14)
	v_lshlrev_b32_e32 v146, 16, v108
	global_load_dwordx4 v[70:73], v[98:99], off
	v_and_b32_e32 v147, 0xffff0000, v108
	v_lshlrev_b32_e32 v108, 16, v109
	v_and_b32_e32 v109, 0xffff0000, v109
	s_waitcnt vmcnt(14)
	v_lshlrev_b32_e32 v148, 16, v112
	v_and_b32_e32 v149, 0xffff0000, v112
	v_lshlrev_b32_e32 v112, 16, v113
	v_and_b32_e32 v113, 0xffff0000, v113
	v_pk_fma_f32 v[64:65], v[64:65], v[108:109], v[112:113]
	v_lshlrev_b32_e32 v108, 16, v110
	v_and_b32_e32 v109, 0xffff0000, v110
	v_lshlrev_b32_e32 v110, 16, v111
	v_and_b32_e32 v111, 0xffff0000, v111
	v_lshlrev_b32_e32 v112, 16, v114
	v_and_b32_e32 v113, 0xffff0000, v114
	v_lshlrev_b32_e32 v114, 16, v115
	v_and_b32_e32 v115, 0xffff0000, v115
	v_pk_fma_f32 v[62:63], v[62:63], v[146:147], v[148:149]
	v_pk_fma_f32 v[110:111], v[60:61], v[110:111], v[114:115]
	v_pk_fma_f32 v[60:61], v[58:59], v[108:109], v[112:113]
	v_cvt_pk_bf16_f32 v58, v62, v63
	v_cvt_pk_bf16_f32 v59, v64, v65
	v_cvt_pk_bf16_f32 v60, v60, v61
	v_cvt_pk_bf16_f32 v61, v110, v111
	global_store_dwordx4 v[140:141], v[58:61], off
	s_waitcnt vmcnt(13)
	v_lshlrev_b32_e32 v62, 16, v120
	v_and_b32_e32 v63, 0xffff0000, v120
	v_lshlrev_b32_e32 v58, 16, v116
	v_and_b32_e32 v59, 0xffff0000, v116
	v_lshlrev_b32_e32 v60, 16, v117
	v_and_b32_e32 v61, 0xffff0000, v117
	v_lshlrev_b32_e32 v64, 16, v121
	v_and_b32_e32 v65, 0xffff0000, v121
	v_pk_fma_f32 v[56:57], v[56:57], v[60:61], v[64:65]
	v_pk_fma_f32 v[54:55], v[54:55], v[58:59], v[62:63]
	v_lshlrev_b32_e32 v58, 16, v118
	v_and_b32_e32 v59, 0xffff0000, v118
	v_lshlrev_b32_e32 v60, 16, v119
	v_and_b32_e32 v61, 0xffff0000, v119
	v_lshlrev_b32_e32 v62, 16, v122
	v_and_b32_e32 v63, 0xffff0000, v122
	v_lshlrev_b32_e32 v64, 16, v123
	v_and_b32_e32 v65, 0xffff0000, v123
	v_pk_fma_f32 v[60:61], v[52:53], v[60:61], v[64:65]
	v_pk_fma_f32 v[52:53], v[50:51], v[58:59], v[62:63]
	v_cvt_pk_bf16_f32 v50, v54, v55
	v_cvt_pk_bf16_f32 v51, v56, v57
	v_cvt_pk_bf16_f32 v52, v52, v53
	v_cvt_pk_bf16_f32 v53, v60, v61
	global_store_dwordx4 v[142:143], v[50:53], off
	s_waitcnt vmcnt(12)
	v_lshlrev_b32_e32 v54, 16, v128
	v_and_b32_e32 v55, 0xffff0000, v128
	v_lshlrev_b32_e32 v50, 16, v124
	v_and_b32_e32 v51, 0xffff0000, v124
	v_lshlrev_b32_e32 v52, 16, v125
	v_and_b32_e32 v53, 0xffff0000, v125
	v_lshlrev_b32_e32 v56, 16, v129
	v_and_b32_e32 v57, 0xffff0000, v129
	v_pk_fma_f32 v[48:49], v[48:49], v[52:53], v[56:57]
	v_pk_fma_f32 v[46:47], v[46:47], v[50:51], v[54:55]
	v_lshlrev_b32_e32 v50, 16, v126
	v_and_b32_e32 v51, 0xffff0000, v126
	v_lshlrev_b32_e32 v52, 16, v127
	v_and_b32_e32 v53, 0xffff0000, v127
	v_lshlrev_b32_e32 v54, 16, v130
	v_and_b32_e32 v55, 0xffff0000, v130
	v_lshlrev_b32_e32 v56, 16, v131
	v_and_b32_e32 v57, 0xffff0000, v131
	v_pk_fma_f32 v[52:53], v[44:45], v[52:53], v[56:57]
	v_pk_fma_f32 v[44:45], v[42:43], v[50:51], v[54:55]
	v_cvt_pk_bf16_f32 v42, v46, v47
	v_cvt_pk_bf16_f32 v43, v48, v49
	v_cvt_pk_bf16_f32 v44, v44, v45
	v_cvt_pk_bf16_f32 v45, v52, v53
	global_store_dwordx4 v[144:145], v[42:45], off
	s_waitcnt vmcnt(12)
	v_lshlrev_b32_e32 v46, 16, v136
	v_and_b32_e32 v47, 0xffff0000, v136
	s_waitcnt vmcnt(11)
; DEVI u32x4 pack8(const f32x4 a, const f32x4 b) { u32x4 w; w.x = cvtpk(a[0], a[1]); w.y = cvtpk(a[2], a[3]); w.z = cvtpk(b[0], b[1]); w.w = cvtpk(b[2], b[3]); return w; }
; DEVI f32x4 unpk_lo(const u32x4 w) { return (f32x4){bflo(w.x), bfhi(w.x), bflo(w.y), bfhi(w.y)}; }
; DEVI f32x4 unpk_hi(const u32x4 w) { return (f32x4){bflo(w.z), bfhi(w.z), bflo(w.w), bfhi(w.w)}; }
; #define PG8_BAR __builtin_amdgcn_s_barrier()
; #define FENCE() asm volatile("" ::: "memory")
; template <class Epi, class Sched>
; __device__ __forceinline__ void gemm_phase(int wv, LAS unsigned char* lds, const Gemm g, const Sched& S, const Epi& E) {
;     ...
;         cur = nxt; cA = nA; cB = nB; ++ui;
;         if (wr == 1) PG8_BAR;
;     DEVI void operator()(AccRef acc, const Unit& u, int wr, int wc, int fr, int fq) const {
;     ...
;             for (int m = 0; m < 4; ++m)
; #pragma unroll
;                 for (int bj = 0; bj < 2; ++bj) { const unsigned off = (unsigned)ROWOF(u) * 1024u + u.pn * 256 + bj * 128 + wc * 32 + 8 * fq;
;                     *(u32x4*)(mb + off) = pack8(acc[ai][bj][m][0] * unpk_lo(g[m][bj]) + unpk_lo(w[m][bj]), acc[ai][bj][m][1] * unpk_hi(g[m][bj]) + unpk_hi(w[m][bj])); }
;             FENCE();
	v_lshlrev_b32_e32 v42, 16, v132
	v_and_b32_e32 v43, 0xffff0000, v132
	v_lshlrev_b32_e32 v44, 16, v133
	v_and_b32_e32 v45, 0xffff0000, v133
	v_lshlrev_b32_e32 v48, 16, v137
	v_and_b32_e32 v49, 0xffff0000, v137
	v_pk_fma_f32 v[40:41], v[40:41], v[44:45], v[48:49]
	v_pk_fma_f32 v[38:39], v[38:39], v[42:43], v[46:47]
	v_lshlrev_b32_e32 v42, 16, v134
	v_and_b32_e32 v43, 0xffff0000, v134
	v_lshlrev_b32_e32 v44, 16, v135
	v_and_b32_e32 v45, 0xffff0000, v135
	v_lshlrev_b32_e32 v46, 16, v138
	v_and_b32_e32 v47, 0xffff0000, v138
	v_lshlrev_b32_e32 v48, 16, v139
	v_and_b32_e32 v49, 0xffff0000, v139
	v_pk_fma_f32 v[44:45], v[36:37], v[44:45], v[48:49]
	v_pk_fma_f32 v[36:37], v[34:35], v[42:43], v[46:47]
	v_cvt_pk_bf16_f32 v34, v38, v39
	v_cvt_pk_bf16_f32 v35, v40, v41
	v_cvt_pk_bf16_f32 v36, v36, v37
	v_cvt_pk_bf16_f32 v37, v44, v45
	global_store_dwordx4 v[106:107], v[34:37], off
	s_waitcnt vmcnt(11)
	v_lshlrev_b32_e32 v38, 16, v94
	v_and_b32_e32 v39, 0xffff0000, v94
	s_waitcnt vmcnt(10)
	v_lshlrev_b32_e32 v34, 16, v90
	v_and_b32_e32 v35, 0xffff0000, v90
	v_lshlrev_b32_e32 v36, 16, v91
	v_and_b32_e32 v37, 0xffff0000, v91
	v_lshlrev_b32_e32 v40, 16, v95
	v_and_b32_e32 v41, 0xffff0000, v95
	v_pk_fma_f32 v[32:33], v[32:33], v[36:37], v[40:41]
	v_pk_fma_f32 v[30:31], v[30:31], v[34:35], v[38:39]
	v_lshlrev_b32_e32 v34, 16, v92
	v_and_b32_e32 v35, 0xffff0000, v92
	v_lshlrev_b32_e32 v36, 16, v93
	v_and_b32_e32 v37, 0xffff0000, v93
	v_lshlrev_b32_e32 v38, 16, v96
	v_and_b32_e32 v39, 0xffff0000, v96
	v_lshlrev_b32_e32 v40, 16, v97
	v_and_b32_e32 v41, 0xffff0000, v97
	v_pk_fma_f32 v[36:37], v[28:29], v[36:37], v[40:41]
	v_pk_fma_f32 v[28:29], v[26:27], v[34:35], v[38:39]
	v_cvt_pk_bf16_f32 v26, v30, v31
	v_cvt_pk_bf16_f32 v27, v32, v33
	v_cvt_pk_bf16_f32 v28, v28, v29
	v_cvt_pk_bf16_f32 v29, v36, v37
	global_store_dwordx4 v[104:105], v[26:29], off
	s_waitcnt vmcnt(10)
	v_lshlrev_b32_e32 v30, 16, v86
	v_and_b32_e32 v31, 0xffff0000, v86
	s_waitcnt vmcnt(9)
	v_lshlrev_b32_e32 v26, 16, v82
	v_and_b32_e32 v27, 0xffff0000, v82
	v_lshlrev_b32_e32 v28, 16, v83
	v_and_b32_e32 v29, 0xffff0000, v83
	v_lshlrev_b32_e32 v32, 16, v87
	v_and_b32_e32 v33, 0xffff0000, v87
	v_pk_fma_f32 v[24:25], v[24:25], v[28:29], v[32:33]
	v_pk_fma_f32 v[22:23], v[22:23], v[26:27], v[30:31]
	v_lshlrev_b32_e32 v26, 16, v84
	v_and_b32_e32 v27, 0xffff0000, v84
	v_lshlrev_b32_e32 v28, 16, v85
	v_and_b32_e32 v29, 0xffff0000, v85
	v_lshlrev_b32_e32 v30, 16, v88
	v_and_b32_e32 v31, 0xffff0000, v88
	v_lshlrev_b32_e32 v32, 16, v89
	v_and_b32_e32 v33, 0xffff0000, v89
	v_pk_fma_f32 v[28:29], v[20:21], v[28:29], v[32:33]
	v_pk_fma_f32 v[20:21], v[18:19], v[26:27], v[30:31]
	v_cvt_pk_bf16_f32 v18, v22, v23
	v_cvt_pk_bf16_f32 v19, v24, v25
	v_cvt_pk_bf16_f32 v20, v20, v21
	v_cvt_pk_bf16_f32 v21, v28, v29
	global_store_dwordx4 v[102:103], v[18:21], off
	s_waitcnt vmcnt(9)
	v_lshlrev_b32_e32 v22, 16, v78
	v_and_b32_e32 v23, 0xffff0000, v78
	s_waitcnt vmcnt(8)
	v_lshlrev_b32_e32 v18, 16, v74
	v_and_b32_e32 v19, 0xffff0000, v74
	v_lshlrev_b32_e32 v20, 16, v75
	v_and_b32_e32 v21, 0xffff0000, v75
	v_lshlrev_b32_e32 v24, 16, v79
	v_and_b32_e32 v25, 0xffff0000, v79
	v_pk_fma_f32 v[16:17], v[16:17], v[20:21], v[24:25]
	v_pk_fma_f32 v[14:15], v[14:15], v[18:19], v[22:23]
	v_lshlrev_b32_e32 v18, 16, v76
	v_and_b32_e32 v19, 0xffff0000, v76
	v_lshlrev_b32_e32 v20, 16, v77
	v_and_b32_e32 v21, 0xffff0000, v77
	v_lshlrev_b32_e32 v22, 16, v80
	v_and_b32_e32 v23, 0xffff0000, v80
	v_lshlrev_b32_e32 v24, 16, v81
	v_and_b32_e32 v25, 0xffff0000, v81
	v_pk_fma_f32 v[20:21], v[12:13], v[20:21], v[24:25]
	v_pk_fma_f32 v[12:13], v[10:11], v[18:19], v[22:23]
	v_cvt_pk_bf16_f32 v10, v14, v15
	v_cvt_pk_bf16_f32 v11, v16, v17
	v_cvt_pk_bf16_f32 v12, v12, v13
	v_cvt_pk_bf16_f32 v13, v20, v21
	global_store_dwordx4 v[100:101], v[10:13], off
	s_waitcnt vmcnt(7)
	v_lshlrev_b32_e32 v14, 16, v70
	v_and_b32_e32 v15, 0xffff0000, v70
	v_lshlrev_b32_e32 v10, 16, v66
	v_and_b32_e32 v11, 0xffff0000, v66
	v_lshlrev_b32_e32 v12, 16, v67
	v_and_b32_e32 v13, 0xffff0000, v67
	v_lshlrev_b32_e32 v16, 16, v71
	v_and_b32_e32 v17, 0xffff0000, v71
	v_pk_fma_f32 v[8:9], v[8:9], v[12:13], v[16:17]
	v_pk_fma_f32 v[6:7], v[6:7], v[10:11], v[14:15]
	v_lshlrev_b32_e32 v10, 16, v68
	v_and_b32_e32 v11, 0xffff0000, v68
	v_lshlrev_b32_e32 v12, 16, v69
	v_and_b32_e32 v13, 0xffff0000, v69
	v_lshlrev_b32_e32 v14, 16, v72
	v_and_b32_e32 v15, 0xffff0000, v72
	v_lshlrev_b32_e32 v16, 16, v73
	v_and_b32_e32 v17, 0xffff0000, v73
	v_pk_fma_f32 v[12:13], v[4:5], v[12:13], v[16:17]
	v_pk_fma_f32 v[4:5], v[2:3], v[10:11], v[14:15]
	v_cvt_pk_bf16_f32 v2, v6, v7
	v_cvt_pk_bf16_f32 v3, v8, v9
	v_cvt_pk_bf16_f32 v4, v4, v5
	v_cvt_pk_bf16_f32 v5, v12, v13
	global_store_dwordx4 v[98:99], v[2:5], off
	s_cbranch_vccnz .LBB0_1457
	s_andn2_b64 vcc, exec, s[4:5]
	s_cbranch_vccnz .LBB0_1456
	s_barrier
	s_branch .LBB0_1456

; #define TID() tid_now(wv)
; DEVI const float* IN(int i) { return *(const float* const __attribute__((address_space(4)))*)(kargs() + 8 * i); }
; DEVI float* OUTP() { return *(float* const __attribute__((address_space(4)))*)(kargs() + 8 * 21); }
; DEVI unsigned char* WSP() { return *(unsigned char* const __attribute__((address_space(4)))*)(kargs() + 8 * 22); }
; template <class Epi, class Sched>
; __device__ __forceinline__ void gemm_phase(int wv, LAS unsigned char* lds, const Gemm g, const Sched& S, const Epi& E) {
;     ...
;         { const int t2 = TID(), w2 = __builtin_amdgcn_readfirstlane(t2 >> 6), l2 = t2 & 63; Unit eu = cur; eu.ks = 0; if (g.nNr) { eu.pn = cur.pn % g.nNr; eu.ks = cur.pn / g.nNr; } E(acc, eu, w2 >> 2, w2 & 3, l2 & 15, l2 >> 4); }
;     DEVI void operator()(AccRef acc, const Unit& u, int wr, int wc, int fr, int fq) const {
;         unsigned char* ws = WSP(); float* out = OUTP();
;         const bool samp = u.pm * 256 >= MP;
;         const float* base = from_in ? (samp ? IN(1) - (size_t)MP * 1024 : IN(0)) : out;
;         bf16_t* xb = (bf16_t*)(ws + O_XB); float* ssq = (float*)(ws + O_SSQZ) + (size_t)ssq_slot * MT;
.LBB0_1534:
	s_mov_b64 s[52:53], s[0:1]
	v_mbcnt_lo_u32_b32 v0, -1, 0
	v_mbcnt_hi_u32_b32 v0, -1, v0
	v_lshl_or_b32 v0, s33, 6, v0
	v_bfe_u32 v195, v0, 2, 4
	v_and_b32_e32 v194, 3, v0
	v_lshl_add_u32 v194, v194, 4, v195
	v_lshlrev_b32_e32 v194, 2, v194
	ds_bpermute_b32 v2, v194, v2
	ds_bpermute_b32 v3, v194, v3
	ds_bpermute_b32 v4, v194, v4
	ds_bpermute_b32 v5, v194, v5
	ds_bpermute_b32 v6, v194, v6
	ds_bpermute_b32 v7, v194, v7
	ds_bpermute_b32 v8, v194, v8
	ds_bpermute_b32 v9, v194, v9
	s_waitcnt lgkmcnt(7)
	ds_bpermute_b32 v10, v194, v10
	ds_bpermute_b32 v11, v194, v11
	ds_bpermute_b32 v12, v194, v12
	ds_bpermute_b32 v13, v194, v13
	ds_bpermute_b32 v14, v194, v14
	ds_bpermute_b32 v15, v194, v15
	ds_bpermute_b32 v16, v194, v16
	ds_bpermute_b32 v17, v194, v17
	s_waitcnt lgkmcnt(7)
	ds_bpermute_b32 v18, v194, v18
	ds_bpermute_b32 v19, v194, v19
	ds_bpermute_b32 v20, v194, v20
	ds_bpermute_b32 v21, v194, v21
	ds_bpermute_b32 v22, v194, v22
	ds_bpermute_b32 v23, v194, v23
	ds_bpermute_b32 v24, v194, v24
	ds_bpermute_b32 v25, v194, v25
	s_waitcnt lgkmcnt(7)
	ds_bpermute_b32 v26, v194, v26
	ds_bpermute_b32 v27, v194, v27
	ds_bpermute_b32 v28, v194, v28
	ds_bpermute_b32 v29, v194, v29
	ds_bpermute_b32 v30, v194, v30
	ds_bpermute_b32 v31, v194, v31
	ds_bpermute_b32 v32, v194, v32
	ds_bpermute_b32 v33, v194, v33
	s_waitcnt lgkmcnt(7)
	ds_bpermute_b32 v34, v194, v34
	ds_bpermute_b32 v35, v194, v35
	ds_bpermute_b32 v36, v194, v36
	ds_bpermute_b32 v37, v194, v37
	ds_bpermute_b32 v38, v194, v38
	ds_bpermute_b32 v39, v194, v39
	ds_bpermute_b32 v40, v194, v40
	ds_bpermute_b32 v41, v194, v41
	s_waitcnt lgkmcnt(7)
	ds_bpermute_b32 v42, v194, v42
	ds_bpermute_b32 v43, v194, v43
	ds_bpermute_b32 v44, v194, v44
	ds_bpermute_b32 v45, v194, v45
	ds_bpermute_b32 v46, v194, v46
	ds_bpermute_b32 v47, v194, v47
	ds_bpermute_b32 v48, v194, v48
	ds_bpermute_b32 v49, v194, v49
	s_waitcnt lgkmcnt(7)
	ds_bpermute_b32 v50, v194, v50
	ds_bpermute_b32 v51, v194, v51
	ds_bpermute_b32 v52, v194, v52
	ds_bpermute_b32 v53, v194, v53
	ds_bpermute_b32 v54, v194, v54
	ds_bpermute_b32 v55, v194, v55
	ds_bpermute_b32 v56, v194, v56
	ds_bpermute_b32 v57, v194, v57
	s_waitcnt lgkmcnt(7)
	ds_bpermute_b32 v58, v194, v58
	ds_bpermute_b32 v59, v194, v59
	ds_bpermute_b32 v60, v194, v60
	ds_bpermute_b32 v61, v194, v61
	ds_bpermute_b32 v62, v194, v62
	ds_bpermute_b32 v63, v194, v63
	ds_bpermute_b32 v64, v194, v64
	ds_bpermute_b32 v65, v194, v65
	s_waitcnt lgkmcnt(7)
	ds_bpermute_b32 v66, v194, v66
	ds_bpermute_b32 v67, v194, v67
	ds_bpermute_b32 v68, v194, v68
	ds_bpermute_b32 v69, v194, v69
	ds_bpermute_b32 v70, v194, v70
	ds_bpermute_b32 v71, v194, v71
	ds_bpermute_b32 v72, v194, v72
	ds_bpermute_b32 v73, v194, v73
	s_waitcnt lgkmcnt(7)
	ds_bpermute_b32 v74, v194, v74
	ds_bpermute_b32 v75, v194, v75
	ds_bpermute_b32 v76, v194, v76
	ds_bpermute_b32 v77, v194, v77
	ds_bpermute_b32 v78, v194, v78
	ds_bpermute_b32 v79, v194, v79
	ds_bpermute_b32 v80, v194, v80
	ds_bpermute_b32 v81, v194, v81
	s_waitcnt lgkmcnt(7)
	ds_bpermute_b32 v82, v194, v82
	ds_bpermute_b32 v83, v194, v83
	ds_bpermute_b32 v84, v194, v84
	ds_bpermute_b32 v85, v194, v85
	ds_bpermute_b32 v86, v194, v86
	ds_bpermute_b32 v87, v194, v87
	ds_bpermute_b32 v88, v194, v88
	ds_bpermute_b32 v89, v194, v89
	s_waitcnt lgkmcnt(7)
	ds_bpermute_b32 v90, v194, v90
	ds_bpermute_b32 v91, v194, v91
	ds_bpermute_b32 v92, v194, v92
	ds_bpermute_b32 v93, v194, v93
	ds_bpermute_b32 v94, v194, v94
	ds_bpermute_b32 v95, v194, v95
	ds_bpermute_b32 v96, v194, v96
	ds_bpermute_b32 v97, v194, v97
	s_waitcnt lgkmcnt(7)
	ds_bpermute_b32 v98, v194, v98
	ds_bpermute_b32 v99, v194, v99
	ds_bpermute_b32 v100, v194, v100
	ds_bpermute_b32 v101, v194, v101
	ds_bpermute_b32 v102, v194, v102
	ds_bpermute_b32 v103, v194, v103
	ds_bpermute_b32 v104, v194, v104
	ds_bpermute_b32 v105, v194, v105
	s_waitcnt lgkmcnt(7)
	ds_bpermute_b32 v106, v194, v106
	ds_bpermute_b32 v107, v194, v107
	ds_bpermute_b32 v108, v194, v108
	ds_bpermute_b32 v109, v194, v109
	ds_bpermute_b32 v110, v194, v110
	ds_bpermute_b32 v111, v194, v111
	ds_bpermute_b32 v112, v194, v112
	ds_bpermute_b32 v113, v194, v113
	s_waitcnt lgkmcnt(7)
	ds_bpermute_b32 v114, v194, v114
	ds_bpermute_b32 v115, v194, v115
	ds_bpermute_b32 v116, v194, v116
	ds_bpermute_b32 v117, v194, v117
	ds_bpermute_b32 v118, v194, v118
	ds_bpermute_b32 v119, v194, v119
	ds_bpermute_b32 v120, v194, v120
	ds_bpermute_b32 v121, v194, v121
	s_waitcnt lgkmcnt(7)
	ds_bpermute_b32 v122, v194, v122
	ds_bpermute_b32 v123, v194, v123
	ds_bpermute_b32 v124, v194, v124
	ds_bpermute_b32 v125, v194, v125
	ds_bpermute_b32 v126, v194, v126
	ds_bpermute_b32 v127, v194, v127
	ds_bpermute_b32 v128, v194, v128
	ds_bpermute_b32 v129, v194, v129
	s_waitcnt lgkmcnt(0)
	s_mov_b64 s[54:55], s[0:1]
	s_load_dwordx2 s[52:53], s[52:53], 0xb0
	s_load_dwordx2 s[56:57], s[54:55], 0xa8
	v_readfirstlane_b32 s5, v0
	s_andn2_b64 vcc, exec, s[44:45]
	s_waitcnt lgkmcnt(0)
	s_mov_b64 s[60:61], s[56:57]
	s_cbranch_vccnz .LBB0_1539
	s_cmpk_lt_i32 s58, 0x80
	s_mov_b64 s[54:55], -1
	s_cbranch_scc0 .LBB0_1537
	s_mov_b64 s[54:55], s[0:1]
	s_load_dwordx2 s[60:61], s[54:55], 0x0
	s_mov_b64 s[54:55], 0

; DEVI u32x4 pack8(const f32x4 a, const f32x4 b) { u32x4 w; w.x = cvtpk(a[0], a[1]); w.y = cvtpk(a[2], a[3]); w.z = cvtpk(b[0], b[1]); w.w = cvtpk(b[2], b[3]); return w; }
; DEVI float ss4(const f32x4 a) { return (a[0] * a[0] + a[1] * a[1]) + (a[2] * a[2] + a[3] * a[3]); }
; DEVI float red_fq(float s) { s += __shfl_xor(s, 16); s += __shfl_xor(s, 32); return s; }
;     DEVI void operator()(AccRef acc, const Unit& u, int wr, int wc, int fr, int fq) const {
;     ...
; #pragma unroll
;         for (int ai = 0; ai < 2; ++ai) {
;             f32x4 b0[4][2], b1[4][2];
; #pragma unroll
;             for (int m = 0; m < 4; ++m)
; #pragma unroll
;                 for (int bj = 0; bj < 2; ++bj) { const float* bp = base + (unsigned)ROWOF(u) * 1024u + u.pn * 256 + bj * 128 + wc * 32 + 8 * fq; b0[m][bj] = *(const f32x4*)bp; b1[m][bj] = *(const f32x4*)(bp + 4); }
; #pragma unroll
;             for (int m = 0; m < 4; ++m) {
;                 const int row = ROWOF(u);
;                 float s = 0.f;
; #pragma unroll
;                 for (int bj = 0; bj < 2; ++bj) {
;                     const unsigned off = (unsigned)row * 1024u + u.pn * 256 + bj * 128 + wc * 32 + 8 * fq;
;                     const f32x4 o0 = b0[m][bj] + acc[ai][bj][m][0], o1 = b1[m][bj] + acc[ai][bj][m][1];
;                     *(f32x4*)(out + off) = o0; *(f32x4*)(out + off + 4) = o1;
;                     if (wxb) { *(u32x4*)(xb + off) = pack8(o0, o1); s += ss4(o0) + ss4(o1); }
;                 }
;                 if (wxb) { s = red_fq(s); if (fq == 0) unsafeAtomicAdd(ssq + row, s); }
;             }
.LBB0_1539:
	s_add_u32 s54, s52, 0xbbb0800
	s_addc_u32 s55, s53, 0
	s_add_u32 s11, s52, s12
	s_addc_u32 s47, s53, 0
	s_add_u32 s52, s11, 0xa5000
	s_addc_u32 s53, s47, 0
	s_ashr_i32 s47, s5, 2
	s_lshl_b32 s70, s4, 8
	s_lshl_b32 s11, s58, 8
	s_andn2_b32 s47, s47, 63
	s_ashr_i32 s71, s70, 31
	s_add_i32 s47, s47, s11
	s_lshl_b64 s[72:73], s[70:71], 2
	s_waitcnt lgkmcnt(0)
	s_add_u32 s4, s60, s72
	s_addc_u32 s11, s61, s73
	s_lshr_b32 s5, s5, 1
	v_bfe_u32 v190, v0, 2, 4
	v_or_b32_e32 v190, s47, v190
	s_and_b32 s47, s5, 0x60
	s_lshl_b32 s5, s47, 2
	v_and_b32_e32 v130, 3, v0
	s_add_u32 s4, s4, s5
	s_addc_u32 s5, s11, 0
	v_lshlrev_b32_e32 v0, 5, v130
	v_lshl_add_u64 v[192:193], s[4:5], 0, v[0:1]
	s_or_b32 s4, s47, s70
	v_lshlrev_b32_e32 v0, 10, v190
	v_lshl_or_b32 v206, v130, 3, s4
	v_cmp_eq_u32_e32 vcc, 0, v130
	v_lshl_add_u64 v[130:131], v[0:1], 2, v[192:193]
	global_load_dwordx4 v[194:197], v[130:131], off offset:16
	global_load_dwordx4 v[198:201], v[130:131], off
	global_load_dwordx4 v[208:211], v[130:131], off offset:528
	global_load_dwordx4 v[212:215], v[130:131], off offset:512
	v_or_b32_e32 v130, 0x4000, v0
	v_mov_b32_e32 v131, v1
	v_lshl_add_u64 v[130:131], v[130:131], 2, v[192:193]
	global_load_dwordx4 v[170:173], v[130:131], off offset:16
	global_load_dwordx4 v[174:177], v[130:131], off
	global_load_dwordx4 v[162:165], v[130:131], off offset:528
	global_load_dwordx4 v[166:169], v[130:131], off offset:512
	v_or_b32_e32 v130, 0x8000, v0
	v_mov_b32_e32 v131, v1
	v_lshl_add_u64 v[130:131], v[130:131], 2, v[192:193]
	global_load_dwordx4 v[154:157], v[130:131], off offset:16
	global_load_dwordx4 v[158:161], v[130:131], off
	global_load_dwordx4 v[138:141], v[130:131], off offset:528
	global_load_dwordx4 v[146:149], v[130:131], off offset:512
	v_or_b32_e32 v130, 0xc000, v0
	v_mov_b32_e32 v131, v1
	v_lshl_add_u64 v[134:135], v[130:131], 2, v[192:193]
	global_load_dwordx4 v[142:145], v[134:135], off offset:16
	global_load_dwordx4 v[150:153], v[134:135], off
	global_load_dwordx4 v[130:133], v[134:135], off offset:528
	s_nop 0
	global_load_dwordx4 v[134:137], v[134:135], off offset:512
	v_add_u32_e32 v202, v0, v206
	v_mov_b32_e32 v203, v1
	v_ashrrev_i32_e32 v191, 31, v190
	s_waitcnt vmcnt(0)
	v_pk_add_f32 v[122:123], v[122:123], v[194:195]
	v_pk_add_f32 v[128:129], v[128:129], v[200:201]
	v_pk_add_f32 v[126:127], v[126:127], v[198:199]
	v_lshl_add_u64 v[198:199], v[202:203], 2, s[56:57]
	v_pk_add_f32 v[124:125], v[124:125], v[196:197]
	global_store_dwordx4 v[198:199], v[126:129], off
	global_store_dwordx4 v[198:199], v[122:125], off offset:16
	v_cvt_pk_bf16_f32 v194, v126, v127
	v_cvt_pk_bf16_f32 v196, v122, v123
	v_mul_f32_e32 v127, v127, v127
	v_mul_f32_e32 v123, v123, v123
	v_fmac_f32_e32 v127, v126, v126
	v_mul_f32_e32 v126, v129, v129
	v_fmac_f32_e32 v123, v122, v122
	v_mul_f32_e32 v122, v125, v125
	v_cvt_pk_bf16_f32 v195, v128, v129
	v_cvt_pk_bf16_f32 v197, v124, v125
	v_lshl_add_u64 v[200:201], v[202:203], 1, s[54:55]
	v_fmac_f32_e32 v126, v128, v128
	v_fmac_f32_e32 v122, v124, v124
	v_pk_add_f32 v[120:121], v[120:121], v[214:215]
	v_pk_add_f32 v[118:119], v[118:119], v[212:213]
	v_pk_add_f32 v[114:115], v[114:115], v[208:209]
	global_store_dwordx4 v[200:201], v[194:197], off
	v_add_f32_e32 v126, v127, v126
	v_add_f32_e32 v122, v123, v122
	v_pk_add_f32 v[116:117], v[116:117], v[210:211]
	global_store_dwordx4 v[198:199], v[118:121], off offset:512
	global_store_dwordx4 v[198:199], v[114:117], off offset:528
	v_cvt_pk_bf16_f32 v124, v114, v115
	v_add_f32_e32 v128, v126, v122
	v_mul_f32_e32 v115, v115, v115
	v_cvt_pk_bf16_f32 v122, v118, v119
	v_mul_f32_e32 v119, v119, v119
	v_fmac_f32_e32 v115, v114, v114
	v_mul_f32_e32 v114, v117, v117
	v_cvt_pk_bf16_f32 v125, v116, v117
	v_fmac_f32_e32 v119, v118, v118
	v_mul_f32_e32 v118, v121, v121
	v_fmac_f32_e32 v114, v116, v116
	v_and_b32_e32 v116, 64, v238
	v_fmac_f32_e32 v118, v120, v120
	v_add_f32_e32 v114, v115, v114
	v_xor_b32_e32 v115, 1, v238
	v_add_u32_e32 v117, 64, v116
	v_add_f32_e32 v118, v119, v118
	v_cmp_lt_i32_e64 s[4:5], v115, v117
	v_add_f32_e32 v114, v118, v114
	v_add_f32_e32 v114, v128, v114
	v_cndmask_b32_e64 v115, v238, v115, s[4:5]
	v_lshlrev_b32_e32 v116, 2, v115
	ds_bpermute_b32 v115, v116, v114
	v_or_b32_e32 v126, 0x80, v202
	v_mov_b32_e32 v127, v1
	v_cvt_pk_bf16_f32 v123, v120, v121
	v_lshl_add_u64 v[126:127], v[126:127], 1, s[54:55]
	s_waitcnt lgkmcnt(0)
	v_add_f32_e32 v114, v114, v115
	v_xor_b32_e32 v115, 2, v238
	v_cmp_lt_i32_e64 s[4:5], v115, v117
	global_store_dwordx4 v[126:127], v[122:125], off
	s_nop 0
	v_cndmask_b32_e64 v115, v238, v115, s[4:5]
	v_lshlrev_b32_e32 v117, 2, v115
	ds_bpermute_b32 v115, v117, v114
	s_and_saveexec_b64 s[4:5], vcc
	s_cbranch_execz .LBB0_1541
	s_waitcnt lgkmcnt(0)
	v_add_f32_e32 v118, v114, v115
	v_lshl_add_u64 v[114:115], v[190:191], 2, s[52:53]
	global_atomic_add_f32 v[114:115], v118, off

; DEVI u32x4 pack8(const f32x4 a, const f32x4 b) { u32x4 w; w.x = cvtpk(a[0], a[1]); w.y = cvtpk(a[2], a[3]); w.z = cvtpk(b[0], b[1]); w.w = cvtpk(b[2], b[3]); return w; }
; DEVI unsigned char* WSP() { return *(unsigned char* const __attribute__((address_space(4)))*)(kargs() + 8 * 22); }
; #define ROWLOOP _Pragma("unroll") for (int ai = 0; ai < 2; ++ai) _Pragma("unroll") for (int m = 0; m < 4; ++m)
;     DEVI void operator()(AccRef acc, const Unit& u, int wr, int wc, int fr, int fq) const {
;         unsigned char* ws = WSP();
;         const float* ssq = (const float*)(ws + O_SSQZ) + (size_t)(1 + l) * MT; bf16_t* ah = (bf16_t*)(ws + O_AH);
;         ROWLOOP {
;             const int row = ROWOF(u);
;             const float r = rsqrtf(ssq[row] * (1.f / 1024.f) + EPSF);
; #pragma unroll
;             for (int bj = 0; bj < 2; ++bj) {
;                 f32x4 a = acc[ai][bj][m][0] * r, b = acc[ai][bj][m][1] * r;
; #pragma unroll
;                 for (int j = 0; j < 4; ++j) { const float x = fmaxf(a[j], 0.f), y = fmaxf(b[j], 0.f); a[j] = x * x; b[j] = y * y; }
;                 *(u32x4*)(ah + (size_t)row * DFF + u.pn * 256 + bj * 128 + wc * 32 + 8 * fq) = pack8(a, b);
;             }
;         }
;     }
.LBB0_1623:
	s_mov_b64 s[52:53], s[0:1]
	v_mbcnt_lo_u32_b32 v0, -1, 0
	v_mbcnt_hi_u32_b32 v0, -1, v0
	v_lshl_or_b32 v0, s33, 6, v0
	s_load_dwordx2 s[52:53], s[52:53], 0xb0
	v_readfirstlane_b32 s11, v0
	s_mov_b64 s[56:57], 0x28990800
	s_waitcnt lgkmcnt(0)
	s_add_u32 s54, s52, s12
	s_addc_u32 s55, s53, 0
	s_ashr_i32 s47, s11, 2
	s_lshl_b32 s4, s4, 8
	s_andn2_b32 s47, s47, 63
	s_add_i32 s47, s47, s4
	v_and_or_b32 v142, v0, 15, s47
	v_bfe_u32 v166, v0, 2, 4
	v_and_b32_e32 v164, 3, v0
	v_lshl_add_u32 v164, v164, 4, v166
	v_add_u32_e32 v166, s47, v166
	v_lshlrev_b32_e32 v164, 2, v164
	v_mov_b32_e32 v167, 0
	v_ashrrev_i32_e32 v143, 31, v142
	v_lshl_add_u64 v[144:145], v[142:143], 2, s[54:55]
	s_mov_b32 s4, 0xa5000
	v_add_co_u32_e32 v146, vcc, s4, v144
	s_mov_b64 s[54:55], 0xa5000
	s_nop 0
	v_addc_co_u32_e32 v147, vcc, 0, v145, vcc
	global_load_dword v152, v[146:147], off
	global_load_dword v156, v[146:147], off offset:64
	global_load_dword v157, v[146:147], off offset:128
	global_load_dword v158, v[146:147], off offset:192
	global_load_dword v159, v[146:147], off offset:512
	global_load_dword v160, v[146:147], off offset:576
	global_load_dword v161, v[146:147], off offset:640
	global_load_dword v162, v[146:147], off offset:704
	s_lshl_b32 s4, s5, 8
	v_lshlrev_b64 v[150:151], 13, v[166:167]
	s_ashr_i32 s5, s4, 31
	v_lshl_add_u64 v[146:147], v[144:145], 0, s[54:55]
	s_lshl_b64 s[4:5], s[4:5], 1
	s_add_u32 s4, s52, s4
	s_addc_u32 s5, s53, s5
	s_and_b32 s11, s11, 0xc0
	s_add_u32 s4, s4, s11
	v_and_b32_e32 v0, 3, v0
	v_lshlrev_b32_e32 v0, 4, v0
	s_addc_u32 s5, s5, 0
	s_waitcnt vmcnt(0)
	v_fmamk_f32 v143, v152, 0x3a800000, v233
	v_mul_f32_e32 v144, 0x4b800000, v143
	v_cmp_gt_f32_e32 vcc, s25, v143
	s_nop 1
	v_cndmask_b32_e32 v143, v143, v144, vcc
	v_rsq_f32_e32 v143, v143
	v_lshl_add_u64 v[144:145], s[4:5], 0, v[0:1]
	v_lshl_add_u64 v[144:145], v[144:145], 0, s[56:57]
	v_lshl_add_u64 v[150:151], v[144:145], 0, v[150:151]
	v_mul_f32_e32 v0, 0x45800000, v143
	v_cndmask_b32_e32 v0, v143, v0, vcc
	v_pk_mul_f32 v[128:129], v[128:129], v[0:1] op_sel_hi:[1,0]
	v_pk_mul_f32 v[126:127], v[126:127], v[0:1] op_sel_hi:[1,0]
	v_pk_mul_f32 v[124:125], v[124:125], v[0:1] op_sel_hi:[1,0]
	v_pk_mul_f32 v[122:123], v[122:123], v[0:1] op_sel_hi:[1,0]
	v_pk_mul_f32 v[120:121], v[120:121], v[0:1] op_sel_hi:[1,0]
	v_pk_mul_f32 v[118:119], v[118:119], v[0:1] op_sel_hi:[1,0]
	v_pk_mul_f32 v[116:117], v[116:117], v[0:1] op_sel_hi:[1,0]
	v_pk_mul_f32 v[114:115], v[114:115], v[0:1] op_sel_hi:[1,0]
	v_max_f32_e32 v126, 0, v126
	v_max_f32_e32 v122, 0, v122
	v_max_f32_e32 v127, 0, v127
	v_max_f32_e32 v123, 0, v123
	v_max_f32_e32 v128, 0, v128
	v_max_f32_e32 v124, 0, v124
	v_max_f32_e32 v129, 0, v129
	v_max_f32_e32 v125, 0, v125
	v_max_f32_e32 v118, 0, v118
	v_max_f32_e32 v114, 0, v114
	v_max_f32_e32 v119, 0, v119
	v_max_f32_e32 v115, 0, v115
	v_max_f32_e32 v120, 0, v120
	v_max_f32_e32 v116, 0, v116
	v_max_f32_e32 v121, 0, v121
	v_max_f32_e32 v117, 0, v117
	v_pk_mul_f32 v[126:127], v[126:127], v[126:127]
	v_pk_mul_f32 v[122:123], v[122:123], v[122:123]
	v_pk_mul_f32 v[128:129], v[128:129], v[128:129]
	v_pk_mul_f32 v[124:125], v[124:125], v[124:125]
	v_pk_mul_f32 v[118:119], v[118:119], v[118:119]
	v_pk_mul_f32 v[152:153], v[114:115], v[114:115]
	v_pk_mul_f32 v[120:121], v[120:121], v[120:121]
	v_pk_mul_f32 v[154:155], v[116:117], v[116:117]
	v_cvt_pk_bf16_f32 v114, v126, v127
	v_cvt_pk_bf16_f32 v115, v128, v129
	v_cvt_pk_bf16_f32 v116, v122, v123
	v_cvt_pk_bf16_f32 v117, v124, v125
	v_cvt_pk_bf16_f32 v118, v118, v119
	v_cvt_pk_bf16_f32 v119, v120, v121
	v_cvt_pk_bf16_f32 v120, v152, v153
	v_cvt_pk_bf16_f32 v121, v154, v155
	ds_bpermute_b32 v114, v164, v114
	ds_bpermute_b32 v115, v164, v115
	ds_bpermute_b32 v116, v164, v116
	ds_bpermute_b32 v117, v164, v117
	ds_bpermute_b32 v118, v164, v118
	ds_bpermute_b32 v119, v164, v119
	ds_bpermute_b32 v120, v164, v120
	ds_bpermute_b32 v121, v164, v121
	s_waitcnt lgkmcnt(0)
	global_store_dwordx4 v[150:151], v[114:117], off
	global_store_dwordx4 v[150:151], v[118:121], off offset:256
	s_nop 0
	v_or_b32_e32 v114, 16, v166
	v_fmamk_f32 v0, v156, 0x3a800000, v233
	v_mul_f32_e32 v115, 0x4b800000, v0
	v_cmp_gt_f32_e32 vcc, s25, v0
	s_nop 1
	v_cndmask_b32_e32 v0, v0, v115, vcc
	v_rsq_f32_e32 v0, v0
	v_ashrrev_i32_e32 v115, 31, v114
	v_lshlrev_b64 v[114:115], 13, v[114:115]
	v_lshl_add_u64 v[114:115], v[144:145], 0, v[114:115]
	v_mul_f32_e32 v116, 0x45800000, v0
	v_cndmask_b32_e32 v0, v0, v116, vcc
	v_pk_mul_f32 v[112:113], v[112:113], v[0:1] op_sel_hi:[1,0]
	v_pk_mul_f32 v[110:111], v[110:111], v[0:1] op_sel_hi:[1,0]
	v_pk_mul_f32 v[108:109], v[108:109], v[0:1] op_sel_hi:[1,0]
	v_pk_mul_f32 v[106:107], v[106:107], v[0:1] op_sel_hi:[1,0]
	v_pk_mul_f32 v[104:105], v[104:105], v[0:1] op_sel_hi:[1,0]
	v_pk_mul_f32 v[102:103], v[102:103], v[0:1] op_sel_hi:[1,0]
	v_pk_mul_f32 v[100:101], v[100:101], v[0:1] op_sel_hi:[1,0]
	v_pk_mul_f32 v[98:99], v[98:99], v[0:1] op_sel_hi:[1,0]
	v_max_f32_e32 v110, 0, v110
	v_max_f32_e32 v106, 0, v106
	v_max_f32_e32 v111, 0, v111
	v_max_f32_e32 v107, 0, v107
	v_max_f32_e32 v112, 0, v112
	v_max_f32_e32 v108, 0, v108
	v_max_f32_e32 v113, 0, v113
	v_max_f32_e32 v109, 0, v109
	v_max_f32_e32 v102, 0, v102
	v_max_f32_e32 v98, 0, v98
	v_max_f32_e32 v103, 0, v103
	v_max_f32_e32 v99, 0, v99
	v_max_f32_e32 v104, 0, v104
	v_max_f32_e32 v100, 0, v100
	v_max_f32_e32 v105, 0, v105
	v_max_f32_e32 v101, 0, v101
	v_pk_mul_f32 v[110:111], v[110:111], v[110:111]
	v_pk_mul_f32 v[106:107], v[106:107], v[106:107]
	v_pk_mul_f32 v[112:113], v[112:113], v[112:113]
	v_pk_mul_f32 v[108:109], v[108:109], v[108:109]
	v_pk_mul_f32 v[102:103], v[102:103], v[102:103]
	v_pk_mul_f32 v[116:117], v[98:99], v[98:99]
	v_pk_mul_f32 v[104:105], v[104:105], v[104:105]
	v_pk_mul_f32 v[118:119], v[100:101], v[100:101]
	v_cvt_pk_bf16_f32 v98, v110, v111
	v_cvt_pk_bf16_f32 v99, v112, v113
	v_cvt_pk_bf16_f32 v100, v106, v107
	v_cvt_pk_bf16_f32 v101, v108, v109
	v_cvt_pk_bf16_f32 v102, v102, v103
	v_cvt_pk_bf16_f32 v103, v104, v105
	v_cvt_pk_bf16_f32 v104, v116, v117
	v_cvt_pk_bf16_f32 v105, v118, v119
	ds_bpermute_b32 v98, v164, v98
	ds_bpermute_b32 v99, v164, v99
	ds_bpermute_b32 v100, v164, v100
	ds_bpermute_b32 v101, v164, v101
	ds_bpermute_b32 v102, v164, v102
	ds_bpermute_b32 v103, v164, v103
	ds_bpermute_b32 v104, v164, v104
	ds_bpermute_b32 v105, v164, v105
	s_waitcnt lgkmcnt(0)
; DEVI u32x4 pack8(const f32x4 a, const f32x4 b) { u32x4 w; w.x = cvtpk(a[0], a[1]); w.y = cvtpk(a[2], a[3]); w.z = cvtpk(b[0], b[1]); w.w = cvtpk(b[2], b[3]); return w; }
; #define ROWLOOP _Pragma("unroll") for (int ai = 0; ai < 2; ++ai) _Pragma("unroll") for (int m = 0; m < 4; ++m)
;     DEVI void operator()(AccRef acc, const Unit& u, int wr, int wc, int fr, int fq) const {
;     ...
;         ROWLOOP {
;             const int row = ROWOF(u);
;             const float r = rsqrtf(ssq[row] * (1.f / 1024.f) + EPSF);
; #pragma unroll
;             for (int bj = 0; bj < 2; ++bj) {
;                 f32x4 a = acc[ai][bj][m][0] * r, b = acc[ai][bj][m][1] * r;
; #pragma unroll
;                 for (int j = 0; j < 4; ++j) { const float x = fmaxf(a[j], 0.f), y = fmaxf(b[j], 0.f); a[j] = x * x; b[j] = y * y; }
;                 *(u32x4*)(ah + (size_t)row * DFF + u.pn * 256 + bj * 128 + wc * 32 + 8 * fq) = pack8(a, b);
;             }
	global_store_dwordx4 v[114:115], v[98:101], off
	global_store_dwordx4 v[114:115], v[102:105], off offset:256
	s_nop 0
	v_or_b32_e32 v98, 32, v166
	v_fmamk_f32 v0, v157, 0x3a800000, v233
	v_mul_f32_e32 v99, 0x4b800000, v0
	v_cmp_gt_f32_e32 vcc, s25, v0
	s_nop 1
	v_cndmask_b32_e32 v0, v0, v99, vcc
	v_rsq_f32_e32 v0, v0
	v_ashrrev_i32_e32 v99, 31, v98
	v_lshlrev_b64 v[98:99], 13, v[98:99]
	v_lshl_add_u64 v[98:99], v[144:145], 0, v[98:99]
	v_mul_f32_e32 v100, 0x45800000, v0
	v_cndmask_b32_e32 v0, v0, v100, vcc
	v_pk_mul_f32 v[96:97], v[96:97], v[0:1] op_sel_hi:[1,0]
	v_pk_mul_f32 v[94:95], v[94:95], v[0:1] op_sel_hi:[1,0]
	v_pk_mul_f32 v[92:93], v[92:93], v[0:1] op_sel_hi:[1,0]
	v_pk_mul_f32 v[90:91], v[90:91], v[0:1] op_sel_hi:[1,0]
	v_pk_mul_f32 v[88:89], v[88:89], v[0:1] op_sel_hi:[1,0]
	v_pk_mul_f32 v[86:87], v[86:87], v[0:1] op_sel_hi:[1,0]
	v_pk_mul_f32 v[84:85], v[84:85], v[0:1] op_sel_hi:[1,0]
	v_pk_mul_f32 v[82:83], v[82:83], v[0:1] op_sel_hi:[1,0]
	v_max_f32_e32 v94, 0, v94
	v_max_f32_e32 v90, 0, v90
	v_max_f32_e32 v95, 0, v95
	v_max_f32_e32 v91, 0, v91
	v_max_f32_e32 v96, 0, v96
	v_max_f32_e32 v92, 0, v92
	v_max_f32_e32 v97, 0, v97
	v_max_f32_e32 v93, 0, v93
	v_max_f32_e32 v86, 0, v86
	v_max_f32_e32 v82, 0, v82
	v_max_f32_e32 v87, 0, v87
	v_max_f32_e32 v83, 0, v83
	v_max_f32_e32 v88, 0, v88
	v_max_f32_e32 v84, 0, v84
	v_max_f32_e32 v89, 0, v89
	v_max_f32_e32 v85, 0, v85
	v_pk_mul_f32 v[94:95], v[94:95], v[94:95]
	v_pk_mul_f32 v[90:91], v[90:91], v[90:91]
	v_pk_mul_f32 v[96:97], v[96:97], v[96:97]
	v_pk_mul_f32 v[92:93], v[92:93], v[92:93]
	v_pk_mul_f32 v[86:87], v[86:87], v[86:87]
	v_pk_mul_f32 v[100:101], v[82:83], v[82:83]
	v_pk_mul_f32 v[88:89], v[88:89], v[88:89]
	v_pk_mul_f32 v[102:103], v[84:85], v[84:85]
	v_cvt_pk_bf16_f32 v82, v94, v95
	v_cvt_pk_bf16_f32 v83, v96, v97
	v_cvt_pk_bf16_f32 v84, v90, v91
	v_cvt_pk_bf16_f32 v85, v92, v93
	v_cvt_pk_bf16_f32 v86, v86, v87
	v_cvt_pk_bf16_f32 v87, v88, v89
	v_cvt_pk_bf16_f32 v88, v100, v101
	v_cvt_pk_bf16_f32 v89, v102, v103
	ds_bpermute_b32 v82, v164, v82
	ds_bpermute_b32 v83, v164, v83
	ds_bpermute_b32 v84, v164, v84
	ds_bpermute_b32 v85, v164, v85
	ds_bpermute_b32 v86, v164, v86
	ds_bpermute_b32 v87, v164, v87
	ds_bpermute_b32 v88, v164, v88
	ds_bpermute_b32 v89, v164, v89
	s_waitcnt lgkmcnt(0)
	global_store_dwordx4 v[98:99], v[82:85], off
	global_store_dwordx4 v[98:99], v[86:89], off offset:256
	s_nop 0
	v_or_b32_e32 v82, 48, v166
	v_fmamk_f32 v0, v158, 0x3a800000, v233
	v_mul_f32_e32 v83, 0x4b800000, v0
	v_cmp_gt_f32_e32 vcc, s25, v0
	s_nop 1
	v_cndmask_b32_e32 v0, v0, v83, vcc
	v_rsq_f32_e32 v0, v0
	v_ashrrev_i32_e32 v83, 31, v82
	v_lshlrev_b64 v[82:83], 13, v[82:83]
	v_lshl_add_u64 v[82:83], v[144:145], 0, v[82:83]
	v_mul_f32_e32 v84, 0x45800000, v0
	v_cndmask_b32_e32 v0, v0, v84, vcc
	v_pk_mul_f32 v[80:81], v[80:81], v[0:1] op_sel_hi:[1,0]
	v_pk_mul_f32 v[78:79], v[78:79], v[0:1] op_sel_hi:[1,0]
	v_pk_mul_f32 v[76:77], v[76:77], v[0:1] op_sel_hi:[1,0]
	v_pk_mul_f32 v[74:75], v[74:75], v[0:1] op_sel_hi:[1,0]
	v_pk_mul_f32 v[72:73], v[72:73], v[0:1] op_sel_hi:[1,0]
	v_pk_mul_f32 v[70:71], v[70:71], v[0:1] op_sel_hi:[1,0]
	v_pk_mul_f32 v[68:69], v[68:69], v[0:1] op_sel_hi:[1,0]
	v_pk_mul_f32 v[66:67], v[66:67], v[0:1] op_sel_hi:[1,0]
	v_max_f32_e32 v78, 0, v78
	v_max_f32_e32 v74, 0, v74
	v_max_f32_e32 v79, 0, v79
	v_max_f32_e32 v75, 0, v75
	v_max_f32_e32 v80, 0, v80
	v_max_f32_e32 v76, 0, v76
	v_max_f32_e32 v81, 0, v81
	v_max_f32_e32 v77, 0, v77
	v_max_f32_e32 v70, 0, v70
	v_max_f32_e32 v66, 0, v66
	v_max_f32_e32 v71, 0, v71
	v_max_f32_e32 v67, 0, v67
	v_max_f32_e32 v72, 0, v72
	v_max_f32_e32 v68, 0, v68
	v_max_f32_e32 v73, 0, v73
	v_max_f32_e32 v69, 0, v69
	v_pk_mul_f32 v[78:79], v[78:79], v[78:79]
	v_pk_mul_f32 v[74:75], v[74:75], v[74:75]
	v_pk_mul_f32 v[80:81], v[80:81], v[80:81]
	v_pk_mul_f32 v[76:77], v[76:77], v[76:77]
	v_pk_mul_f32 v[70:71], v[70:71], v[70:71]
	v_pk_mul_f32 v[84:85], v[66:67], v[66:67]
	v_pk_mul_f32 v[72:73], v[72:73], v[72:73]
	v_pk_mul_f32 v[86:87], v[68:69], v[68:69]
	v_cvt_pk_bf16_f32 v66, v78, v79
	v_cvt_pk_bf16_f32 v67, v80, v81
	v_cvt_pk_bf16_f32 v68, v74, v75
	v_cvt_pk_bf16_f32 v69, v76, v77
	v_cvt_pk_bf16_f32 v70, v70, v71
	v_cvt_pk_bf16_f32 v71, v72, v73
	v_cvt_pk_bf16_f32 v72, v84, v85
	v_cvt_pk_bf16_f32 v73, v86, v87
	ds_bpermute_b32 v66, v164, v66
	ds_bpermute_b32 v67, v164, v67
	ds_bpermute_b32 v68, v164, v68
	ds_bpermute_b32 v69, v164, v69
	ds_bpermute_b32 v70, v164, v70
	ds_bpermute_b32 v71, v164, v71
	ds_bpermute_b32 v72, v164, v72
	ds_bpermute_b32 v73, v164, v73
	s_waitcnt lgkmcnt(0)
; DEVI u32x4 pack8(const f32x4 a, const f32x4 b) { u32x4 w; w.x = cvtpk(a[0], a[1]); w.y = cvtpk(a[2], a[3]); w.z = cvtpk(b[0], b[1]); w.w = cvtpk(b[2], b[3]); return w; }
; #define ROWLOOP _Pragma("unroll") for (int ai = 0; ai < 2; ++ai) _Pragma("unroll") for (int m = 0; m < 4; ++m)
;     DEVI void operator()(AccRef acc, const Unit& u, int wr, int wc, int fr, int fq) const {
;     ...
;         ROWLOOP {
;             const int row = ROWOF(u);
;             const float r = rsqrtf(ssq[row] * (1.f / 1024.f) + EPSF);
; #pragma unroll
;             for (int bj = 0; bj < 2; ++bj) {
;                 f32x4 a = acc[ai][bj][m][0] * r, b = acc[ai][bj][m][1] * r;
; #pragma unroll
;                 for (int j = 0; j < 4; ++j) { const float x = fmaxf(a[j], 0.f), y = fmaxf(b[j], 0.f); a[j] = x * x; b[j] = y * y; }
;                 *(u32x4*)(ah + (size_t)row * DFF + u.pn * 256 + bj * 128 + wc * 32 + 8 * fq) = pack8(a, b);
;             }
	global_store_dwordx4 v[82:83], v[66:69], off
	global_store_dwordx4 v[82:83], v[70:73], off offset:256
	s_nop 0
	v_add_u32_e32 v66, 0x80, v166
	v_fmamk_f32 v0, v159, 0x3a800000, v233
	v_mul_f32_e32 v67, 0x4b800000, v0
	v_cmp_gt_f32_e32 vcc, s25, v0
	s_nop 1
	v_cndmask_b32_e32 v0, v0, v67, vcc
	v_rsq_f32_e32 v0, v0
	v_ashrrev_i32_e32 v67, 31, v66
	v_lshlrev_b64 v[66:67], 13, v[66:67]
	v_lshl_add_u64 v[66:67], v[144:145], 0, v[66:67]
	v_mul_f32_e32 v68, 0x45800000, v0
	v_cndmask_b32_e32 v0, v0, v68, vcc
	v_pk_mul_f32 v[64:65], v[64:65], v[0:1] op_sel_hi:[1,0]
	v_pk_mul_f32 v[62:63], v[62:63], v[0:1] op_sel_hi:[1,0]
	v_pk_mul_f32 v[60:61], v[60:61], v[0:1] op_sel_hi:[1,0]
	v_pk_mul_f32 v[58:59], v[58:59], v[0:1] op_sel_hi:[1,0]
	v_pk_mul_f32 v[56:57], v[56:57], v[0:1] op_sel_hi:[1,0]
	v_pk_mul_f32 v[54:55], v[54:55], v[0:1] op_sel_hi:[1,0]
	v_pk_mul_f32 v[52:53], v[52:53], v[0:1] op_sel_hi:[1,0]
	v_pk_mul_f32 v[50:51], v[50:51], v[0:1] op_sel_hi:[1,0]
	v_max_f32_e32 v62, 0, v62
	v_max_f32_e32 v58, 0, v58
	v_max_f32_e32 v63, 0, v63
	v_max_f32_e32 v59, 0, v59
	v_max_f32_e32 v64, 0, v64
	v_max_f32_e32 v60, 0, v60
	v_max_f32_e32 v65, 0, v65
	v_max_f32_e32 v61, 0, v61
	v_max_f32_e32 v54, 0, v54
	v_max_f32_e32 v50, 0, v50
	v_max_f32_e32 v55, 0, v55
	v_max_f32_e32 v51, 0, v51
	v_max_f32_e32 v56, 0, v56
	v_max_f32_e32 v52, 0, v52
	v_max_f32_e32 v57, 0, v57
	v_max_f32_e32 v53, 0, v53
	v_pk_mul_f32 v[62:63], v[62:63], v[62:63]
	v_pk_mul_f32 v[58:59], v[58:59], v[58:59]
	v_pk_mul_f32 v[64:65], v[64:65], v[64:65]
	v_pk_mul_f32 v[60:61], v[60:61], v[60:61]
	v_pk_mul_f32 v[54:55], v[54:55], v[54:55]
	v_pk_mul_f32 v[68:69], v[50:51], v[50:51]
	v_pk_mul_f32 v[56:57], v[56:57], v[56:57]
	v_pk_mul_f32 v[70:71], v[52:53], v[52:53]
	v_cvt_pk_bf16_f32 v50, v62, v63
	v_cvt_pk_bf16_f32 v51, v64, v65
	v_cvt_pk_bf16_f32 v52, v58, v59
	v_cvt_pk_bf16_f32 v53, v60, v61
	v_cvt_pk_bf16_f32 v54, v54, v55
	v_cvt_pk_bf16_f32 v55, v56, v57
	v_cvt_pk_bf16_f32 v56, v68, v69
	v_cvt_pk_bf16_f32 v57, v70, v71
	ds_bpermute_b32 v50, v164, v50
	ds_bpermute_b32 v51, v164, v51
	ds_bpermute_b32 v52, v164, v52
	ds_bpermute_b32 v53, v164, v53
	ds_bpermute_b32 v54, v164, v54
	ds_bpermute_b32 v55, v164, v55
	ds_bpermute_b32 v56, v164, v56
	ds_bpermute_b32 v57, v164, v57
	s_waitcnt lgkmcnt(0)
	global_store_dwordx4 v[66:67], v[50:53], off
	global_store_dwordx4 v[66:67], v[54:57], off offset:256
	s_nop 0
	v_add_u32_e32 v50, 0x90, v166
	v_fmamk_f32 v0, v160, 0x3a800000, v233
	v_mul_f32_e32 v51, 0x4b800000, v0
	v_cmp_gt_f32_e32 vcc, s25, v0
	s_nop 1
	v_cndmask_b32_e32 v0, v0, v51, vcc
	v_rsq_f32_e32 v0, v0
	v_ashrrev_i32_e32 v51, 31, v50
	v_lshlrev_b64 v[50:51], 13, v[50:51]
	v_lshl_add_u64 v[50:51], v[144:145], 0, v[50:51]
	v_mul_f32_e32 v52, 0x45800000, v0
	v_cndmask_b32_e32 v0, v0, v52, vcc
	v_pk_mul_f32 v[48:49], v[48:49], v[0:1] op_sel_hi:[1,0]
	v_pk_mul_f32 v[46:47], v[46:47], v[0:1] op_sel_hi:[1,0]
	v_pk_mul_f32 v[44:45], v[44:45], v[0:1] op_sel_hi:[1,0]
	v_pk_mul_f32 v[42:43], v[42:43], v[0:1] op_sel_hi:[1,0]
	v_pk_mul_f32 v[40:41], v[40:41], v[0:1] op_sel_hi:[1,0]
	v_pk_mul_f32 v[38:39], v[38:39], v[0:1] op_sel_hi:[1,0]
	v_pk_mul_f32 v[36:37], v[36:37], v[0:1] op_sel_hi:[1,0]
	v_pk_mul_f32 v[34:35], v[34:35], v[0:1] op_sel_hi:[1,0]
	v_max_f32_e32 v46, 0, v46
	v_max_f32_e32 v42, 0, v42
	v_max_f32_e32 v47, 0, v47
	v_max_f32_e32 v43, 0, v43
	v_max_f32_e32 v48, 0, v48
	v_max_f32_e32 v44, 0, v44
	v_max_f32_e32 v49, 0, v49
	v_max_f32_e32 v45, 0, v45
	v_max_f32_e32 v38, 0, v38
	v_max_f32_e32 v34, 0, v34
	v_max_f32_e32 v39, 0, v39
	v_max_f32_e32 v35, 0, v35
	v_max_f32_e32 v40, 0, v40
	v_max_f32_e32 v36, 0, v36
	v_max_f32_e32 v41, 0, v41
	v_max_f32_e32 v37, 0, v37
	v_pk_mul_f32 v[46:47], v[46:47], v[46:47]
	v_pk_mul_f32 v[42:43], v[42:43], v[42:43]
	v_pk_mul_f32 v[48:49], v[48:49], v[48:49]
	v_pk_mul_f32 v[44:45], v[44:45], v[44:45]
	v_pk_mul_f32 v[38:39], v[38:39], v[38:39]
	v_pk_mul_f32 v[52:53], v[34:35], v[34:35]
	v_pk_mul_f32 v[40:41], v[40:41], v[40:41]
	v_pk_mul_f32 v[54:55], v[36:37], v[36:37]
	v_cvt_pk_bf16_f32 v34, v46, v47
	v_cvt_pk_bf16_f32 v35, v48, v49
	v_cvt_pk_bf16_f32 v36, v42, v43
	v_cvt_pk_bf16_f32 v37, v44, v45
	v_cvt_pk_bf16_f32 v38, v38, v39
	v_cvt_pk_bf16_f32 v39, v40, v41
	v_cvt_pk_bf16_f32 v40, v52, v53
	v_cvt_pk_bf16_f32 v41, v54, v55
	ds_bpermute_b32 v34, v164, v34
	ds_bpermute_b32 v35, v164, v35
	ds_bpermute_b32 v36, v164, v36
	ds_bpermute_b32 v37, v164, v37
	ds_bpermute_b32 v38, v164, v38
	ds_bpermute_b32 v39, v164, v39
	ds_bpermute_b32 v40, v164, v40
	ds_bpermute_b32 v41, v164, v41
	s_waitcnt lgkmcnt(0)
; DEVI u32x4 pack8(const f32x4 a, const f32x4 b) { u32x4 w; w.x = cvtpk(a[0], a[1]); w.y = cvtpk(a[2], a[3]); w.z = cvtpk(b[0], b[1]); w.w = cvtpk(b[2], b[3]); return w; }
; #define PG8_BAR __builtin_amdgcn_s_barrier()
; #define ROWLOOP _Pragma("unroll") for (int ai = 0; ai < 2; ++ai) _Pragma("unroll") for (int m = 0; m < 4; ++m)
; template <class Epi, class Sched>
; __device__ __forceinline__ void gemm_phase(int wv, LAS unsigned char* lds, const Gemm g, const Sched& S, const Epi& E) {
;     ...
;         if (wr == 1) PG8_BAR;
;     DEVI void operator()(AccRef acc, const Unit& u, int wr, int wc, int fr, int fq) const {
;     ...
;         ROWLOOP {
;             const int row = ROWOF(u);
;             const float r = rsqrtf(ssq[row] * (1.f / 1024.f) + EPSF);
; #pragma unroll
;             for (int bj = 0; bj < 2; ++bj) {
;                 f32x4 a = acc[ai][bj][m][0] * r, b = acc[ai][bj][m][1] * r;
; #pragma unroll
;                 for (int j = 0; j < 4; ++j) { const float x = fmaxf(a[j], 0.f), y = fmaxf(b[j], 0.f); a[j] = x * x; b[j] = y * y; }
;                 *(u32x4*)(ah + (size_t)row * DFF + u.pn * 256 + bj * 128 + wc * 32 + 8 * fq) = pack8(a, b);
;             }
	global_store_dwordx4 v[50:51], v[34:37], off
	global_store_dwordx4 v[50:51], v[38:41], off offset:256
	s_nop 0
	v_add_u32_e32 v34, 0xa0, v166
	v_fmamk_f32 v0, v161, 0x3a800000, v233
	v_mul_f32_e32 v35, 0x4b800000, v0
	v_cmp_gt_f32_e32 vcc, s25, v0
	s_nop 1
	v_cndmask_b32_e32 v0, v0, v35, vcc
	v_rsq_f32_e32 v0, v0
	v_ashrrev_i32_e32 v35, 31, v34
	v_lshlrev_b64 v[34:35], 13, v[34:35]
	v_lshl_add_u64 v[34:35], v[144:145], 0, v[34:35]
	v_mul_f32_e32 v36, 0x45800000, v0
	v_cndmask_b32_e32 v0, v0, v36, vcc
	v_pk_mul_f32 v[32:33], v[32:33], v[0:1] op_sel_hi:[1,0]
	v_pk_mul_f32 v[30:31], v[30:31], v[0:1] op_sel_hi:[1,0]
	v_pk_mul_f32 v[28:29], v[28:29], v[0:1] op_sel_hi:[1,0]
	v_pk_mul_f32 v[26:27], v[26:27], v[0:1] op_sel_hi:[1,0]
	v_pk_mul_f32 v[24:25], v[24:25], v[0:1] op_sel_hi:[1,0]
	v_pk_mul_f32 v[22:23], v[22:23], v[0:1] op_sel_hi:[1,0]
	v_pk_mul_f32 v[20:21], v[20:21], v[0:1] op_sel_hi:[1,0]
	v_pk_mul_f32 v[18:19], v[18:19], v[0:1] op_sel_hi:[1,0]
	v_max_f32_e32 v30, 0, v30
	v_max_f32_e32 v26, 0, v26
	v_max_f32_e32 v31, 0, v31
	v_max_f32_e32 v27, 0, v27
	v_max_f32_e32 v32, 0, v32
	v_max_f32_e32 v28, 0, v28
	v_max_f32_e32 v33, 0, v33
	v_max_f32_e32 v29, 0, v29
	v_max_f32_e32 v22, 0, v22
	v_max_f32_e32 v18, 0, v18
	v_max_f32_e32 v23, 0, v23
	v_max_f32_e32 v19, 0, v19
	v_max_f32_e32 v24, 0, v24
	v_max_f32_e32 v20, 0, v20
	v_max_f32_e32 v25, 0, v25
	v_max_f32_e32 v21, 0, v21
	v_pk_mul_f32 v[30:31], v[30:31], v[30:31]
	v_pk_mul_f32 v[26:27], v[26:27], v[26:27]
	v_pk_mul_f32 v[32:33], v[32:33], v[32:33]
	v_pk_mul_f32 v[28:29], v[28:29], v[28:29]
	v_pk_mul_f32 v[22:23], v[22:23], v[22:23]
	v_pk_mul_f32 v[36:37], v[18:19], v[18:19]
	v_pk_mul_f32 v[24:25], v[24:25], v[24:25]
	v_pk_mul_f32 v[38:39], v[20:21], v[20:21]
	v_cvt_pk_bf16_f32 v18, v30, v31
	v_cvt_pk_bf16_f32 v19, v32, v33
	v_cvt_pk_bf16_f32 v20, v26, v27
	v_cvt_pk_bf16_f32 v21, v28, v29
	v_cvt_pk_bf16_f32 v22, v22, v23
	v_cvt_pk_bf16_f32 v23, v24, v25
	v_cvt_pk_bf16_f32 v24, v36, v37
	v_cvt_pk_bf16_f32 v25, v38, v39
	ds_bpermute_b32 v18, v164, v18
	ds_bpermute_b32 v19, v164, v19
	ds_bpermute_b32 v20, v164, v20
	ds_bpermute_b32 v21, v164, v21
	ds_bpermute_b32 v22, v164, v22
	ds_bpermute_b32 v23, v164, v23
	ds_bpermute_b32 v24, v164, v24
	ds_bpermute_b32 v25, v164, v25
	s_waitcnt lgkmcnt(0)
	global_store_dwordx4 v[34:35], v[18:21], off
	global_store_dwordx4 v[34:35], v[22:25], off offset:256
	s_nop 0
	v_add_u32_e32 v18, 0xb0, v166
	v_ashrrev_i32_e32 v19, 31, v18
	v_lshlrev_b64 v[18:19], 13, v[18:19]
	s_andn2_b64 vcc, exec, s[2:3]
	v_lshl_add_u64 v[18:19], v[144:145], 0, v[18:19]
	s_mov_b64 s[2:3], -1
	v_fmamk_f32 v0, v162, 0x3a800000, v233
	v_mul_f32_e32 v20, 0x4b800000, v0
	v_cmp_gt_f32_e64 s[4:5], s25, v0
	s_nop 1
	v_cndmask_b32_e64 v0, v0, v20, s[4:5]
	v_rsq_f32_e32 v0, v0
	s_nop 0
	v_mul_f32_e32 v20, 0x45800000, v0
	v_cndmask_b32_e64 v0, v0, v20, s[4:5]
	v_pk_mul_f32 v[16:17], v[16:17], v[0:1] op_sel_hi:[1,0]
	v_pk_mul_f32 v[14:15], v[14:15], v[0:1] op_sel_hi:[1,0]
	v_pk_mul_f32 v[12:13], v[12:13], v[0:1] op_sel_hi:[1,0]
	v_pk_mul_f32 v[10:11], v[10:11], v[0:1] op_sel_hi:[1,0]
	v_pk_mul_f32 v[8:9], v[8:9], v[0:1] op_sel_hi:[1,0]
	v_pk_mul_f32 v[6:7], v[6:7], v[0:1] op_sel_hi:[1,0]
	v_pk_mul_f32 v[4:5], v[4:5], v[0:1] op_sel_hi:[1,0]
	v_pk_mul_f32 v[2:3], v[2:3], v[0:1] op_sel_hi:[1,0]
	v_max_f32_e32 v14, 0, v14
	v_max_f32_e32 v10, 0, v10
	v_max_f32_e32 v15, 0, v15
	v_max_f32_e32 v11, 0, v11
	v_max_f32_e32 v16, 0, v16
	v_max_f32_e32 v12, 0, v12
	v_max_f32_e32 v17, 0, v17
	v_max_f32_e32 v13, 0, v13
	v_max_f32_e32 v6, 0, v6
	v_max_f32_e32 v2, 0, v2
	v_max_f32_e32 v7, 0, v7
	v_max_f32_e32 v3, 0, v3
	v_max_f32_e32 v8, 0, v8
	v_max_f32_e32 v4, 0, v4
	v_max_f32_e32 v9, 0, v9
	v_max_f32_e32 v5, 0, v5
	v_pk_mul_f32 v[14:15], v[14:15], v[14:15]
	v_pk_mul_f32 v[10:11], v[10:11], v[10:11]
	v_pk_mul_f32 v[16:17], v[16:17], v[16:17]
	v_pk_mul_f32 v[12:13], v[12:13], v[12:13]
	v_pk_mul_f32 v[6:7], v[6:7], v[6:7]
	v_pk_mul_f32 v[20:21], v[2:3], v[2:3]
	v_pk_mul_f32 v[8:9], v[8:9], v[8:9]
	v_pk_mul_f32 v[22:23], v[4:5], v[4:5]
	v_cvt_pk_bf16_f32 v2, v14, v15
	v_cvt_pk_bf16_f32 v3, v16, v17
	v_cvt_pk_bf16_f32 v4, v10, v11
	v_cvt_pk_bf16_f32 v5, v12, v13
	v_cvt_pk_bf16_f32 v6, v6, v7
	v_cvt_pk_bf16_f32 v7, v8, v9
	v_cvt_pk_bf16_f32 v8, v20, v21
	v_cvt_pk_bf16_f32 v9, v22, v23
	ds_bpermute_b32 v2, v164, v2
	ds_bpermute_b32 v3, v164, v3
	ds_bpermute_b32 v4, v164, v4
	ds_bpermute_b32 v5, v164, v5
	ds_bpermute_b32 v6, v164, v6
	ds_bpermute_b32 v7, v164, v7
	ds_bpermute_b32 v8, v164, v8
	ds_bpermute_b32 v9, v164, v9
	s_waitcnt lgkmcnt(0)
	global_store_dwordx4 v[18:19], v[2:5], off
	global_store_dwordx4 v[18:19], v[6:9], off offset:256
	s_cbranch_vccnz .LBB0_1616
	s_andn2_b64 vcc, exec, s[6:7]
	s_cbranch_vccnz .LBB0_1615
	s_barrier
	s_branch .LBB0_1615

; #define TID() tid_now(wv)
; DEVI const float* IN(int i) { return *(const float* const __attribute__((address_space(4)))*)(kargs() + 8 * i); }
; DEVI float* OUTP() { return *(float* const __attribute__((address_space(4)))*)(kargs() + 8 * 21); }
; DEVI unsigned char* WSP() { return *(unsigned char* const __attribute__((address_space(4)))*)(kargs() + 8 * 22); }
; template <class Epi, class Sched>
; __device__ __forceinline__ void gemm_phase(int wv, LAS unsigned char* lds, const Gemm g, const Sched& S, const Epi& E) {
;     ...
;         { const int t2 = TID(), w2 = __builtin_amdgcn_readfirstlane(t2 >> 6), l2 = t2 & 63; Unit eu = cur; eu.ks = 0; if (g.nNr) { eu.pn = cur.pn % g.nNr; eu.ks = cur.pn / g.nNr; } E(acc, eu, w2 >> 2, w2 & 3, l2 & 15, l2 >> 4); }
;     DEVI void operator()(AccRef acc, const Unit& u, int wr, int wc, int fr, int fq) const {
;         unsigned char* ws = WSP(); float* out = OUTP();
;         const bool samp = u.pm * 256 >= MP;
;         const float* base = from_in ? (samp ? IN(1) - (size_t)MP * 1024 : IN(0)) : out;
;         bf16_t* xb = (bf16_t*)(ws + O_XB); float* ssq = (float*)(ws + O_SSQZ) + (size_t)ssq_slot * MT;
.LBB0_1701:
	s_mov_b64 s[54:55], s[0:1]
	v_mbcnt_lo_u32_b32 v0, -1, 0
	v_mbcnt_hi_u32_b32 v0, -1, v0
	v_lshl_or_b32 v0, s33, 6, v0
	v_bfe_u32 v187, v0, 2, 4
	v_and_b32_e32 v186, 3, v0
	v_lshl_add_u32 v186, v186, 4, v187
	v_lshlrev_b32_e32 v186, 2, v186
	ds_bpermute_b32 v2, v186, v2
	ds_bpermute_b32 v3, v186, v3
	ds_bpermute_b32 v4, v186, v4
	ds_bpermute_b32 v5, v186, v5
	ds_bpermute_b32 v6, v186, v6
	ds_bpermute_b32 v7, v186, v7
	ds_bpermute_b32 v8, v186, v8
	ds_bpermute_b32 v9, v186, v9
	s_waitcnt lgkmcnt(7)
	ds_bpermute_b32 v10, v186, v10
	ds_bpermute_b32 v11, v186, v11
	ds_bpermute_b32 v12, v186, v12
	ds_bpermute_b32 v13, v186, v13
	ds_bpermute_b32 v14, v186, v14
	ds_bpermute_b32 v15, v186, v15
	ds_bpermute_b32 v16, v186, v16
	ds_bpermute_b32 v17, v186, v17
	s_waitcnt lgkmcnt(7)
	ds_bpermute_b32 v18, v186, v18
	ds_bpermute_b32 v19, v186, v19
	ds_bpermute_b32 v20, v186, v20
	ds_bpermute_b32 v21, v186, v21
	ds_bpermute_b32 v22, v186, v22
	ds_bpermute_b32 v23, v186, v23
	ds_bpermute_b32 v24, v186, v24
	ds_bpermute_b32 v25, v186, v25
	s_waitcnt lgkmcnt(7)
	ds_bpermute_b32 v26, v186, v26
	ds_bpermute_b32 v27, v186, v27
	ds_bpermute_b32 v28, v186, v28
	ds_bpermute_b32 v29, v186, v29
	ds_bpermute_b32 v30, v186, v30
	ds_bpermute_b32 v31, v186, v31
	ds_bpermute_b32 v32, v186, v32
	ds_bpermute_b32 v33, v186, v33
	s_waitcnt lgkmcnt(7)
	ds_bpermute_b32 v34, v186, v34
	ds_bpermute_b32 v35, v186, v35
	ds_bpermute_b32 v36, v186, v36
	ds_bpermute_b32 v37, v186, v37
	ds_bpermute_b32 v38, v186, v38
	ds_bpermute_b32 v39, v186, v39
	ds_bpermute_b32 v40, v186, v40
	ds_bpermute_b32 v41, v186, v41
	s_waitcnt lgkmcnt(7)
	ds_bpermute_b32 v42, v186, v42
	ds_bpermute_b32 v43, v186, v43
	ds_bpermute_b32 v44, v186, v44
	ds_bpermute_b32 v45, v186, v45
	ds_bpermute_b32 v46, v186, v46
	ds_bpermute_b32 v47, v186, v47
	ds_bpermute_b32 v48, v186, v48
	ds_bpermute_b32 v49, v186, v49
	s_waitcnt lgkmcnt(7)
	ds_bpermute_b32 v50, v186, v50
	ds_bpermute_b32 v51, v186, v51
	ds_bpermute_b32 v52, v186, v52
	ds_bpermute_b32 v53, v186, v53
	ds_bpermute_b32 v54, v186, v54
	ds_bpermute_b32 v55, v186, v55
	ds_bpermute_b32 v56, v186, v56
	ds_bpermute_b32 v57, v186, v57
	s_waitcnt lgkmcnt(7)
	ds_bpermute_b32 v58, v186, v58
	ds_bpermute_b32 v59, v186, v59
	ds_bpermute_b32 v60, v186, v60
	ds_bpermute_b32 v61, v186, v61
	ds_bpermute_b32 v62, v186, v62
	ds_bpermute_b32 v63, v186, v63
	ds_bpermute_b32 v64, v186, v64
	ds_bpermute_b32 v65, v186, v65
	s_waitcnt lgkmcnt(7)
	ds_bpermute_b32 v66, v186, v66
	ds_bpermute_b32 v67, v186, v67
	ds_bpermute_b32 v68, v186, v68
	ds_bpermute_b32 v69, v186, v69
	ds_bpermute_b32 v70, v186, v70
	ds_bpermute_b32 v71, v186, v71
	ds_bpermute_b32 v72, v186, v72
	ds_bpermute_b32 v73, v186, v73
	s_waitcnt lgkmcnt(7)
	ds_bpermute_b32 v74, v186, v74
	ds_bpermute_b32 v75, v186, v75
	ds_bpermute_b32 v76, v186, v76
	ds_bpermute_b32 v77, v186, v77
	ds_bpermute_b32 v78, v186, v78
	ds_bpermute_b32 v79, v186, v79
	ds_bpermute_b32 v80, v186, v80
	ds_bpermute_b32 v81, v186, v81
	s_waitcnt lgkmcnt(7)
	ds_bpermute_b32 v82, v186, v82
	ds_bpermute_b32 v83, v186, v83
	ds_bpermute_b32 v84, v186, v84
	ds_bpermute_b32 v85, v186, v85
	ds_bpermute_b32 v86, v186, v86
	ds_bpermute_b32 v87, v186, v87
	ds_bpermute_b32 v88, v186, v88
	ds_bpermute_b32 v89, v186, v89
	s_waitcnt lgkmcnt(7)
	ds_bpermute_b32 v90, v186, v90
	ds_bpermute_b32 v91, v186, v91
	ds_bpermute_b32 v92, v186, v92
	ds_bpermute_b32 v93, v186, v93
	ds_bpermute_b32 v94, v186, v94
	ds_bpermute_b32 v95, v186, v95
	ds_bpermute_b32 v96, v186, v96
	ds_bpermute_b32 v97, v186, v97
	s_waitcnt lgkmcnt(7)
	ds_bpermute_b32 v98, v186, v98
	ds_bpermute_b32 v99, v186, v99
	ds_bpermute_b32 v100, v186, v100
	ds_bpermute_b32 v101, v186, v101
	ds_bpermute_b32 v102, v186, v102
	ds_bpermute_b32 v103, v186, v103
	ds_bpermute_b32 v104, v186, v104
	ds_bpermute_b32 v105, v186, v105
	s_waitcnt lgkmcnt(7)
	ds_bpermute_b32 v106, v186, v106
	ds_bpermute_b32 v107, v186, v107
	ds_bpermute_b32 v108, v186, v108
	ds_bpermute_b32 v109, v186, v109
	ds_bpermute_b32 v110, v186, v110
	ds_bpermute_b32 v111, v186, v111
	ds_bpermute_b32 v112, v186, v112
	ds_bpermute_b32 v113, v186, v113
	s_waitcnt lgkmcnt(7)
	ds_bpermute_b32 v114, v186, v114
	ds_bpermute_b32 v115, v186, v115
	ds_bpermute_b32 v116, v186, v116
	ds_bpermute_b32 v117, v186, v117
	ds_bpermute_b32 v118, v186, v118
	ds_bpermute_b32 v119, v186, v119
	ds_bpermute_b32 v120, v186, v120
	ds_bpermute_b32 v121, v186, v121
	s_waitcnt lgkmcnt(7)
	ds_bpermute_b32 v122, v186, v122
	ds_bpermute_b32 v123, v186, v123
	ds_bpermute_b32 v124, v186, v124
	ds_bpermute_b32 v125, v186, v125
	ds_bpermute_b32 v130, v186, v130
	ds_bpermute_b32 v131, v186, v131
	ds_bpermute_b32 v132, v186, v132
	ds_bpermute_b32 v133, v186, v133
	s_waitcnt lgkmcnt(0)
	s_load_dwordx2 s[54:55], s[54:55], 0xb0
	s_mov_b64 s[56:57], s[0:1]
	s_load_dwordx2 s[58:59], s[56:57], 0xa8
	v_readfirstlane_b32 s47, v0
	s_waitcnt lgkmcnt(0)
; DEVI u32x4 pack8(const f32x4 a, const f32x4 b) { u32x4 w; w.x = cvtpk(a[0], a[1]); w.y = cvtpk(a[2], a[3]); w.z = cvtpk(b[0], b[1]); w.w = cvtpk(b[2], b[3]); return w; }
; DEVI float ss4(const f32x4 a) { return (a[0] * a[0] + a[1] * a[1]) + (a[2] * a[2] + a[3] * a[3]); }
; DEVI float red_fq(float s) { s += __shfl_xor(s, 16); s += __shfl_xor(s, 32); return s; }
;     DEVI void operator()(AccRef acc, const Unit& u, int wr, int wc, int fr, int fq) const {
;     ...
; #pragma unroll
;         for (int ai = 0; ai < 2; ++ai) {
;             f32x4 b0[4][2], b1[4][2];
; #pragma unroll
;             for (int m = 0; m < 4; ++m)
; #pragma unroll
;                 for (int bj = 0; bj < 2; ++bj) { const float* bp = base + (unsigned)ROWOF(u) * 1024u + u.pn * 256 + bj * 128 + wc * 32 + 8 * fq; b0[m][bj] = *(const f32x4*)bp; b1[m][bj] = *(const f32x4*)(bp + 4); }
; #pragma unroll
;             for (int m = 0; m < 4; ++m) {
;                 const int row = ROWOF(u);
;                 float s = 0.f;
; #pragma unroll
;                 for (int bj = 0; bj < 2; ++bj) {
;                     const unsigned off = (unsigned)row * 1024u + u.pn * 256 + bj * 128 + wc * 32 + 8 * fq;
;                     const f32x4 o0 = b0[m][bj] + acc[ai][bj][m][0], o1 = b1[m][bj] + acc[ai][bj][m][1];
;                     *(f32x4*)(out + off) = o0; *(f32x4*)(out + off + 4) = o1;
;                     if (wxb) { *(u32x4*)(xb + off) = pack8(o0, o1); s += ss4(o0) + ss4(o1); }
;                 }
;                 if (wxb) { s = red_fq(s); if (fq == 0) unsafeAtomicAdd(ssq + row, s); }
;             }
	s_add_u32 s56, s54, 0xbbb0800
	s_addc_u32 s57, s55, 0
	s_add_u32 s54, s54, 0xa5000
	s_addc_u32 s55, s55, 0
	s_lshl_b32 s5, s6, 8
	s_ashr_i32 s6, s47, 2
	s_andn2_b32 s6, s6, 63
	s_lshl_b32 s4, s4, 8
	s_add_i32 s6, s6, s5
	s_ashr_i32 s5, s4, 31
	v_bfe_u32 v216, v0, 2, 4
	v_or_b32_e32 v216, s6, v216
	s_lshl_b64 s[6:7], s[4:5], 2
	s_add_u32 s5, s58, s6
	s_addc_u32 s7, s59, s7
	s_lshr_b32 s6, s47, 1
	s_and_b32 s47, s6, 0x60
	s_lshl_b32 s6, s47, 2
	v_and_b32_e32 v126, 3, v0
	s_add_u32 s6, s5, s6
	s_addc_u32 s7, s7, 0
	v_lshlrev_b32_e32 v0, 5, v126
	v_lshl_add_u64 v[218:219], s[6:7], 0, v[0:1]
	s_or_b32 s4, s47, s4
	v_lshlrev_b32_e32 v220, 10, v216
	v_mov_b32_e32 v221, v1
	v_lshl_or_b32 v226, v126, 3, s4
	v_cmp_eq_u32_e64 s[4:5], 0, v126
	v_lshl_add_u64 v[126:127], v[220:221], 2, v[218:219]
	v_or_b32_e32 v0, 0x4000, v220
	global_load_dwordx4 v[186:189], v[126:127], off offset:16
	global_load_dwordx4 v[190:193], v[126:127], off
	global_load_dwordx4 v[178:181], v[126:127], off offset:528
	global_load_dwordx4 v[182:185], v[126:127], off offset:512
	v_lshl_add_u64 v[126:127], v[0:1], 2, v[218:219]
	v_or_b32_e32 v0, 0x8000, v220
	global_load_dwordx4 v[170:173], v[126:127], off offset:16
	global_load_dwordx4 v[174:177], v[126:127], off
	global_load_dwordx4 v[162:165], v[126:127], off offset:528
	global_load_dwordx4 v[166:169], v[126:127], off offset:512
	v_lshl_add_u64 v[126:127], v[0:1], 2, v[218:219]
	v_or_b32_e32 v0, 0xc000, v220
	v_lshl_add_u64 v[134:135], v[0:1], 2, v[218:219]
	global_load_dwordx4 v[154:157], v[126:127], off offset:16
	global_load_dwordx4 v[158:161], v[126:127], off
	global_load_dwordx4 v[146:149], v[126:127], off offset:528
	global_load_dwordx4 v[150:153], v[126:127], off offset:512
	global_load_dwordx4 v[138:141], v[134:135], off offset:16
	global_load_dwordx4 v[142:145], v[134:135], off
	s_nop 0
	global_load_dwordx4 v[126:129], v[134:135], off offset:528
	s_nop 0
	global_load_dwordx4 v[134:137], v[134:135], off offset:512
	v_add_u32_e32 v0, v220, v226
	v_lshl_add_u64 v[222:223], v[0:1], 2, s[58:59]
	s_mov_b64 s[60:61], -1
	s_andn2_b64 vcc, exec, s[44:45]
	s_waitcnt vmcnt(0)
	v_pk_add_f32 v[186:187], v[122:123], v[186:187]
	v_cndmask_b32_e64 v122, 0, 1, s[44:45]
	v_pk_add_f32 v[192:193], v[132:133], v[192:193]
	v_pk_add_f32 v[190:191], v[130:131], v[190:191]
	v_pk_add_f32 v[188:189], v[124:125], v[188:189]
	v_cmp_ne_u32_e64 s[6:7], 1, v122
	v_pk_add_f32 v[122:123], v[118:119], v[182:183]
	v_pk_add_f32 v[130:131], v[110:111], v[178:179]
	global_store_dwordx4 v[222:223], v[190:193], off
	global_store_dwordx4 v[222:223], v[186:189], off offset:16
	s_cbranch_vccnz .LBB0_1705
	v_cvt_pk_bf16_f32 v194, v190, v191
	v_cvt_pk_bf16_f32 v195, v192, v193
	v_cvt_pk_bf16_f32 v196, v186, v187
	v_cvt_pk_bf16_f32 v197, v188, v189
	v_lshl_add_u64 v[110:111], v[0:1], 1, s[56:57]
	global_store_dwordx4 v[110:111], v[194:197], off
	v_mul_f32_e32 v110, v191, v191
	v_mul_f32_e32 v111, v193, v193
	v_fmac_f32_e32 v110, v190, v190
	v_fmac_f32_e32 v111, v192, v192
	v_add_f32_e32 v110, v110, v111
	v_mul_f32_e32 v111, v187, v187
	v_mul_f32_e32 v118, v189, v189
	v_fmac_f32_e32 v111, v186, v186
	v_fmac_f32_e32 v118, v188, v188
	v_add_f32_e32 v111, v111, v118
	v_pk_add_f32 v[124:125], v[120:121], v[184:185]
	v_add_f32_e32 v110, v110, v111
	v_mul_f32_e32 v111, v123, v123
	v_mul_f32_e32 v118, v125, v125
	v_pk_add_f32 v[132:133], v[112:113], v[180:181]
	v_fmac_f32_e32 v111, v122, v122
	v_fmac_f32_e32 v118, v124, v124
	v_add_f32_e32 v111, v111, v118
	v_mul_f32_e32 v118, v131, v131
	v_mul_f32_e32 v119, v133, v133
	v_fmac_f32_e32 v118, v130, v130
	v_fmac_f32_e32 v119, v132, v132
	v_add_f32_e32 v118, v118, v119
	v_add_f32_e32 v111, v111, v118
	v_and_b32_e32 v118, 64, v238
	v_add_f32_e32 v110, v110, v111
	v_xor_b32_e32 v111, 1, v238
	v_add_u32_e32 v118, 64, v118
	v_cmp_lt_i32_e32 vcc, v111, v118
	v_or_b32_e32 v0, 0x80, v0
	v_cvt_pk_bf16_f32 v186, v122, v123
	v_cndmask_b32_e32 v111, v238, v111, vcc
	v_lshlrev_b32_e32 v111, 2, v111
	ds_bpermute_b32 v111, v111, v110
	v_cvt_pk_bf16_f32 v187, v124, v125
	v_cvt_pk_bf16_f32 v188, v130, v131
	v_cvt_pk_bf16_f32 v189, v132, v133
	global_store_dwordx4 v[222:223], v[122:125], off offset:512
	global_store_dwordx4 v[222:223], v[130:133], off offset:528
	s_waitcnt lgkmcnt(0)
	v_add_f32_e32 v110, v110, v111
	v_xor_b32_e32 v111, 2, v238
	v_cmp_lt_i32_e32 vcc, v111, v118
	v_lshl_add_u64 v[118:119], v[0:1], 1, s[56:57]
	global_store_dwordx4 v[118:119], v[186:189], off
	v_cndmask_b32_e32 v111, v238, v111, vcc
	v_lshlrev_b32_e32 v111, 2, v111
	ds_bpermute_b32 v111, v111, v110
	s_and_saveexec_b64 s[60:61], s[4:5]
	s_cbranch_execz .LBB0_1704
	v_ashrrev_i32_e32 v217, 31, v216
	s_waitcnt lgkmcnt(0)
	v_add_f32_e32 v0, v110, v111
	v_lshl_add_u64 v[110:111], v[216:217], 2, s[54:55]
	global_atomic_add_f32 v[110:111], v0, off

; DEVI u32x4 pack8(const f32x4 a, const f32x4 b) { u32x4 w; w.x = cvtpk(a[0], a[1]); w.y = cvtpk(a[2], a[3]); w.z = cvtpk(b[0], b[1]); w.w = cvtpk(b[2], b[3]); return w; }
; DEVI float ss4(const f32x4 a) { return (a[0] * a[0] + a[1] * a[1]) + (a[2] * a[2] + a[3] * a[3]); }
; DEVI float red_fq(float s) { s += __shfl_xor(s, 16); s += __shfl_xor(s, 32); return s; }
;     DEVI void operator()(AccRef acc, const Unit& u, int wr, int wc, int fr, int fq) const {
;     ...
;             for (int m = 0; m < 4; ++m) {
;                 const int row = ROWOF(u);
;                 float s = 0.f;
; #pragma unroll
;                 for (int bj = 0; bj < 2; ++bj) {
;                     const unsigned off = (unsigned)row * 1024u + u.pn * 256 + bj * 128 + wc * 32 + 8 * fq;
;                     const f32x4 o0 = b0[m][bj] + acc[ai][bj][m][0], o1 = b1[m][bj] + acc[ai][bj][m][1];
;                     *(f32x4*)(out + off) = o0; *(f32x4*)(out + off + 4) = o1;
;                     if (wxb) { *(u32x4*)(xb + off) = pack8(o0, o1); s += ss4(o0) + ss4(o1); }
;                 }
;                 if (wxb) { s = red_fq(s); if (fq == 0) unsafeAtomicAdd(ssq + row, s); }
;             }
.LBB0_1707:
	s_nop 0
	v_or_b32_e32 v124, 16, v216
	v_lshl_add_u32 v0, v124, 10, v226
	v_pk_add_f32 v[116:117], v[116:117], v[176:177]
	v_pk_add_f32 v[114:115], v[114:115], v[174:175]
	v_pk_add_f32 v[120:121], v[108:109], v[172:173]
	v_pk_add_f32 v[118:119], v[106:107], v[170:171]
	v_lshl_add_u64 v[122:123], v[0:1], 2, s[58:59]
	s_mov_b64 s[60:61], -1
	s_and_b64 vcc, exec, s[6:7]
	s_waitcnt lgkmcnt(0)
	v_pk_add_f32 v[110:111], v[102:103], v[166:167]
	v_pk_add_f32 v[106:107], v[94:95], v[162:163]
	global_store_dwordx4 v[122:123], v[114:117], off
	global_store_dwordx4 v[122:123], v[118:121], off offset:16
	s_cbranch_vccnz .LBB0_1711
	v_cvt_pk_bf16_f32 v130, v114, v115
	v_cvt_pk_bf16_f32 v131, v116, v117
	v_cvt_pk_bf16_f32 v132, v118, v119
	v_cvt_pk_bf16_f32 v133, v120, v121
	v_lshl_add_u64 v[94:95], v[0:1], 1, s[56:57]
	global_store_dwordx4 v[94:95], v[130:133], off
	v_mul_f32_e32 v94, v115, v115
	v_mul_f32_e32 v95, v117, v117
	v_fmac_f32_e32 v94, v114, v114
	v_fmac_f32_e32 v95, v116, v116
	v_add_f32_e32 v94, v94, v95
	v_mul_f32_e32 v95, v119, v119
	v_mul_f32_e32 v102, v121, v121
	v_fmac_f32_e32 v95, v118, v118
	v_fmac_f32_e32 v102, v120, v120
	v_add_f32_e32 v95, v95, v102
	v_pk_add_f32 v[112:113], v[104:105], v[168:169]
	v_add_f32_e32 v94, v94, v95
	v_mul_f32_e32 v95, v111, v111
	v_mul_f32_e32 v102, v113, v113
	v_pk_add_f32 v[108:109], v[96:97], v[164:165]
	v_fmac_f32_e32 v95, v110, v110
	v_fmac_f32_e32 v102, v112, v112
	v_add_f32_e32 v95, v95, v102
	v_mul_f32_e32 v102, v107, v107
	v_mul_f32_e32 v103, v109, v109
	v_fmac_f32_e32 v102, v106, v106
	v_fmac_f32_e32 v103, v108, v108
	v_add_f32_e32 v102, v102, v103
	v_add_f32_e32 v95, v95, v102
	v_and_b32_e32 v102, 64, v238
	v_add_f32_e32 v94, v94, v95
	v_xor_b32_e32 v95, 1, v238
	v_add_u32_e32 v102, 64, v102
	v_cmp_lt_i32_e32 vcc, v95, v102
	v_or_b32_e32 v0, 0x80, v0
	v_cvt_pk_bf16_f32 v114, v110, v111
	v_cndmask_b32_e32 v95, v238, v95, vcc
	v_lshlrev_b32_e32 v95, 2, v95
	ds_bpermute_b32 v95, v95, v94
	v_cvt_pk_bf16_f32 v115, v112, v113
	v_cvt_pk_bf16_f32 v116, v106, v107
	v_cvt_pk_bf16_f32 v117, v108, v109
	global_store_dwordx4 v[122:123], v[110:113], off offset:512
	global_store_dwordx4 v[122:123], v[106:109], off offset:528
	s_waitcnt lgkmcnt(0)
	v_add_f32_e32 v94, v94, v95
	v_xor_b32_e32 v95, 2, v238
	v_cmp_lt_i32_e32 vcc, v95, v102
	v_lshl_add_u64 v[102:103], v[0:1], 1, s[56:57]
	global_store_dwordx4 v[102:103], v[114:117], off
	v_cndmask_b32_e32 v95, v238, v95, vcc
	v_lshlrev_b32_e32 v95, 2, v95
	ds_bpermute_b32 v95, v95, v94
	s_and_saveexec_b64 s[60:61], s[4:5]
	s_cbranch_execz .LBB0_1710
	v_ashrrev_i32_e32 v125, 31, v124
	s_waitcnt lgkmcnt(0)
	v_add_f32_e32 v0, v94, v95
	v_lshl_add_u64 v[94:95], v[124:125], 2, s[54:55]
	global_atomic_add_f32 v[94:95], v0, off

; DEVI u32x4 pack8(const f32x4 a, const f32x4 b) { u32x4 w; w.x = cvtpk(a[0], a[1]); w.y = cvtpk(a[2], a[3]); w.z = cvtpk(b[0], b[1]); w.w = cvtpk(b[2], b[3]); return w; }
; DEVI float ss4(const f32x4 a) { return (a[0] * a[0] + a[1] * a[1]) + (a[2] * a[2] + a[3] * a[3]); }
; DEVI float red_fq(float s) { s += __shfl_xor(s, 16); s += __shfl_xor(s, 32); return s; }
;     DEVI void operator()(AccRef acc, const Unit& u, int wr, int wc, int fr, int fq) const {
;     ...
;             for (int m = 0; m < 4; ++m) {
;                 const int row = ROWOF(u);
;                 float s = 0.f;
; #pragma unroll
;                 for (int bj = 0; bj < 2; ++bj) {
;                     const unsigned off = (unsigned)row * 1024u + u.pn * 256 + bj * 128 + wc * 32 + 8 * fq;
;                     const f32x4 o0 = b0[m][bj] + acc[ai][bj][m][0], o1 = b1[m][bj] + acc[ai][bj][m][1];
;                     *(f32x4*)(out + off) = o0; *(f32x4*)(out + off + 4) = o1;
;                     if (wxb) { *(u32x4*)(xb + off) = pack8(o0, o1); s += ss4(o0) + ss4(o1); }
;                 }
;                 if (wxb) { s = red_fq(s); if (fq == 0) unsafeAtomicAdd(ssq + row, s); }
;             }
.LBB0_1713:
	s_nop 1
	v_or_b32_e32 v108, 32, v216
	v_lshl_add_u32 v0, v108, 10, v226
	v_pk_add_f32 v[100:101], v[100:101], v[160:161]
	v_pk_add_f32 v[98:99], v[98:99], v[158:159]
	v_pk_add_f32 v[104:105], v[92:93], v[156:157]
	v_pk_add_f32 v[102:103], v[90:91], v[154:155]
	v_lshl_add_u64 v[106:107], v[0:1], 2, s[58:59]
	s_mov_b64 s[60:61], -1
	s_and_b64 vcc, exec, s[6:7]
	s_waitcnt lgkmcnt(0)
	v_pk_add_f32 v[94:95], v[86:87], v[150:151]
	v_pk_add_f32 v[90:91], v[78:79], v[146:147]
	global_store_dwordx4 v[106:107], v[98:101], off
	global_store_dwordx4 v[106:107], v[102:105], off offset:16
	s_cbranch_vccnz .LBB0_1717
	v_cvt_pk_bf16_f32 v110, v98, v99
	v_cvt_pk_bf16_f32 v111, v100, v101
	v_cvt_pk_bf16_f32 v112, v102, v103
	v_cvt_pk_bf16_f32 v113, v104, v105
	v_lshl_add_u64 v[78:79], v[0:1], 1, s[56:57]
	global_store_dwordx4 v[78:79], v[110:113], off
	v_mul_f32_e32 v78, v99, v99
	v_mul_f32_e32 v79, v101, v101
	v_fmac_f32_e32 v78, v98, v98
	v_fmac_f32_e32 v79, v100, v100
	v_add_f32_e32 v78, v78, v79
	v_mul_f32_e32 v79, v103, v103
	v_mul_f32_e32 v86, v105, v105
	v_fmac_f32_e32 v79, v102, v102
	v_fmac_f32_e32 v86, v104, v104
	v_add_f32_e32 v79, v79, v86
	v_pk_add_f32 v[96:97], v[88:89], v[152:153]
	v_add_f32_e32 v78, v78, v79
	v_mul_f32_e32 v79, v95, v95
	v_mul_f32_e32 v86, v97, v97
	v_pk_add_f32 v[92:93], v[80:81], v[148:149]
	v_fmac_f32_e32 v79, v94, v94
	v_fmac_f32_e32 v86, v96, v96
	v_add_f32_e32 v79, v79, v86
	v_mul_f32_e32 v86, v91, v91
	v_mul_f32_e32 v87, v93, v93
	v_fmac_f32_e32 v86, v90, v90
	v_fmac_f32_e32 v87, v92, v92
	v_add_f32_e32 v86, v86, v87
	v_add_f32_e32 v79, v79, v86
	v_and_b32_e32 v86, 64, v238
	v_add_f32_e32 v78, v78, v79
	v_xor_b32_e32 v79, 1, v238
	v_add_u32_e32 v86, 64, v86
	v_cmp_lt_i32_e32 vcc, v79, v86
	v_or_b32_e32 v0, 0x80, v0
	v_cvt_pk_bf16_f32 v98, v94, v95
	v_cndmask_b32_e32 v79, v238, v79, vcc
	v_lshlrev_b32_e32 v79, 2, v79
	ds_bpermute_b32 v79, v79, v78
	v_cvt_pk_bf16_f32 v99, v96, v97
	v_cvt_pk_bf16_f32 v100, v90, v91
	v_cvt_pk_bf16_f32 v101, v92, v93
	global_store_dwordx4 v[106:107], v[94:97], off offset:512
	global_store_dwordx4 v[106:107], v[90:93], off offset:528
	s_waitcnt lgkmcnt(0)
	v_add_f32_e32 v78, v78, v79
	v_xor_b32_e32 v79, 2, v238
	v_cmp_lt_i32_e32 vcc, v79, v86
	v_lshl_add_u64 v[86:87], v[0:1], 1, s[56:57]
	global_store_dwordx4 v[86:87], v[98:101], off
	v_cndmask_b32_e32 v79, v238, v79, vcc
	v_lshlrev_b32_e32 v79, 2, v79
	ds_bpermute_b32 v79, v79, v78
	s_and_saveexec_b64 s[60:61], s[4:5]
	s_cbranch_execz .LBB0_1716
	v_ashrrev_i32_e32 v109, 31, v108
	s_waitcnt lgkmcnt(0)
	v_add_f32_e32 v0, v78, v79
	v_lshl_add_u64 v[78:79], v[108:109], 2, s[54:55]
	global_atomic_add_f32 v[78:79], v0, off

; DEVI u32x4 pack8(const f32x4 a, const f32x4 b) { u32x4 w; w.x = cvtpk(a[0], a[1]); w.y = cvtpk(a[2], a[3]); w.z = cvtpk(b[0], b[1]); w.w = cvtpk(b[2], b[3]); return w; }
; DEVI float ss4(const f32x4 a) { return (a[0] * a[0] + a[1] * a[1]) + (a[2] * a[2] + a[3] * a[3]); }
; DEVI float red_fq(float s) { s += __shfl_xor(s, 16); s += __shfl_xor(s, 32); return s; }
;     DEVI void operator()(AccRef acc, const Unit& u, int wr, int wc, int fr, int fq) const {
;     ...
;             for (int m = 0; m < 4; ++m) {
;                 const int row = ROWOF(u);
;                 float s = 0.f;
; #pragma unroll
;                 for (int bj = 0; bj < 2; ++bj) {
;                     const unsigned off = (unsigned)row * 1024u + u.pn * 256 + bj * 128 + wc * 32 + 8 * fq;
;                     const f32x4 o0 = b0[m][bj] + acc[ai][bj][m][0], o1 = b1[m][bj] + acc[ai][bj][m][1];
;                     *(f32x4*)(out + off) = o0; *(f32x4*)(out + off + 4) = o1;
;                     if (wxb) { *(u32x4*)(xb + off) = pack8(o0, o1); s += ss4(o0) + ss4(o1); }
;                 }
;                 if (wxb) { s = red_fq(s); if (fq == 0) unsafeAtomicAdd(ssq + row, s); }
;             }
.LBB0_1719:
	s_nop 1
	v_or_b32_e32 v92, 48, v216
	v_lshl_add_u32 v0, v92, 10, v226
	v_pk_add_f32 v[84:85], v[84:85], v[144:145]
	v_pk_add_f32 v[82:83], v[82:83], v[142:143]
	v_pk_add_f32 v[88:89], v[76:77], v[140:141]
	v_pk_add_f32 v[86:87], v[74:75], v[138:139]
	v_lshl_add_u64 v[90:91], v[0:1], 2, s[58:59]
	s_mov_b64 s[60:61], -1
	s_and_b64 vcc, exec, s[6:7]
	s_waitcnt lgkmcnt(0)
	v_pk_add_f32 v[78:79], v[70:71], v[134:135]
	v_pk_add_f32 v[74:75], v[66:67], v[126:127]
	global_store_dwordx4 v[90:91], v[82:85], off
	global_store_dwordx4 v[90:91], v[86:89], off offset:16
	s_cbranch_vccnz .LBB0_1723
	v_cvt_pk_bf16_f32 v94, v82, v83
	v_cvt_pk_bf16_f32 v95, v84, v85
	v_cvt_pk_bf16_f32 v96, v86, v87
	v_cvt_pk_bf16_f32 v97, v88, v89
	v_lshl_add_u64 v[66:67], v[0:1], 1, s[56:57]
	global_store_dwordx4 v[66:67], v[94:97], off
	v_mul_f32_e32 v66, v83, v83
	v_mul_f32_e32 v67, v85, v85
	v_fmac_f32_e32 v66, v82, v82
	v_fmac_f32_e32 v67, v84, v84
	v_add_f32_e32 v66, v66, v67
	v_mul_f32_e32 v67, v87, v87
	v_mul_f32_e32 v70, v89, v89
	v_fmac_f32_e32 v67, v86, v86
	v_fmac_f32_e32 v70, v88, v88
	v_add_f32_e32 v67, v67, v70
	v_pk_add_f32 v[80:81], v[72:73], v[136:137]
	v_add_f32_e32 v66, v66, v67
	v_mul_f32_e32 v67, v79, v79
	v_mul_f32_e32 v70, v81, v81
	v_pk_add_f32 v[76:77], v[68:69], v[128:129]
	v_fmac_f32_e32 v67, v78, v78
	v_fmac_f32_e32 v70, v80, v80
	v_add_f32_e32 v67, v67, v70
	v_mul_f32_e32 v70, v75, v75
	v_mul_f32_e32 v71, v77, v77
	v_fmac_f32_e32 v70, v74, v74
	v_fmac_f32_e32 v71, v76, v76
	v_add_f32_e32 v70, v70, v71
	v_add_f32_e32 v67, v67, v70
	v_and_b32_e32 v70, 64, v238
	v_add_f32_e32 v66, v66, v67
	v_xor_b32_e32 v67, 1, v238
	v_add_u32_e32 v70, 64, v70
	v_cmp_lt_i32_e32 vcc, v67, v70
	v_or_b32_e32 v0, 0x80, v0
	v_cvt_pk_bf16_f32 v82, v78, v79
	v_cndmask_b32_e32 v67, v238, v67, vcc
	v_lshlrev_b32_e32 v67, 2, v67
	ds_bpermute_b32 v67, v67, v66
	v_cvt_pk_bf16_f32 v83, v80, v81
	v_cvt_pk_bf16_f32 v84, v74, v75
	v_cvt_pk_bf16_f32 v85, v76, v77
	global_store_dwordx4 v[90:91], v[78:81], off offset:512
	global_store_dwordx4 v[90:91], v[74:77], off offset:528
	s_waitcnt lgkmcnt(0)
	v_add_f32_e32 v66, v66, v67
	v_xor_b32_e32 v67, 2, v238
	v_cmp_lt_i32_e32 vcc, v67, v70
	v_lshl_add_u64 v[70:71], v[0:1], 1, s[56:57]
	global_store_dwordx4 v[70:71], v[82:85], off
	v_cndmask_b32_e32 v67, v238, v67, vcc
	v_lshlrev_b32_e32 v67, 2, v67
	ds_bpermute_b32 v67, v67, v66
	s_and_saveexec_b64 s[60:61], s[4:5]
	s_cbranch_execz .LBB0_1722
	v_ashrrev_i32_e32 v93, 31, v92
	s_waitcnt lgkmcnt(0)
	v_add_f32_e32 v0, v66, v67
	v_lshl_add_u64 v[66:67], v[92:93], 2, s[54:55]
	global_atomic_add_f32 v[66:67], v0, off

; DEVI u32x4 pack8(const f32x4 a, const f32x4 b) { u32x4 w; w.x = cvtpk(a[0], a[1]); w.y = cvtpk(a[2], a[3]); w.z = cvtpk(b[0], b[1]); w.w = cvtpk(b[2], b[3]); return w; }
; DEVI float ss4(const f32x4 a) { return (a[0] * a[0] + a[1] * a[1]) + (a[2] * a[2] + a[3] * a[3]); }
; DEVI float red_fq(float s) { s += __shfl_xor(s, 16); s += __shfl_xor(s, 32); return s; }
;     DEVI void operator()(AccRef acc, const Unit& u, int wr, int wc, int fr, int fq) const {
;     ...
;         for (int ai = 0; ai < 2; ++ai) {
;             f32x4 b0[4][2], b1[4][2];
; #pragma unroll
;             for (int m = 0; m < 4; ++m)
; #pragma unroll
;                 for (int bj = 0; bj < 2; ++bj) { const float* bp = base + (unsigned)ROWOF(u) * 1024u + u.pn * 256 + bj * 128 + wc * 32 + 8 * fq; b0[m][bj] = *(const f32x4*)bp; b1[m][bj] = *(const f32x4*)(bp + 4); }
; #pragma unroll
;             for (int m = 0; m < 4; ++m) {
;                 const int row = ROWOF(u);
;                 float s = 0.f;
; #pragma unroll
;                 for (int bj = 0; bj < 2; ++bj) {
;                     const unsigned off = (unsigned)row * 1024u + u.pn * 256 + bj * 128 + wc * 32 + 8 * fq;
;                     const f32x4 o0 = b0[m][bj] + acc[ai][bj][m][0], o1 = b1[m][bj] + acc[ai][bj][m][1];
;                     *(f32x4*)(out + off) = o0; *(f32x4*)(out + off + 4) = o1;
;                     if (wxb) { *(u32x4*)(xb + off) = pack8(o0, o1); s += ss4(o0) + ss4(o1); }
;                 }
;                 if (wxb) { s = red_fq(s); if (fq == 0) unsafeAtomicAdd(ssq + row, s); }
;             }
.LBB0_1725:
	v_add_u32_e32 v0, 0x20000, v220
	s_waitcnt lgkmcnt(0)
	v_lshl_add_u64 v[66:67], v[0:1], 2, v[218:219]
	v_add_u32_e32 v0, 0x24000, v220
	global_load_dwordx4 v[122:125], v[66:67], off offset:16
	global_load_dwordx4 v[126:129], v[66:67], off
	global_load_dwordx4 v[114:117], v[66:67], off offset:528
	global_load_dwordx4 v[118:121], v[66:67], off offset:512
	v_lshl_add_u64 v[66:67], v[0:1], 2, v[218:219]
	v_add_u32_e32 v0, 0x28000, v220
	global_load_dwordx4 v[106:109], v[66:67], off offset:16
	global_load_dwordx4 v[110:113], v[66:67], off
	global_load_dwordx4 v[98:101], v[66:67], off offset:528
	global_load_dwordx4 v[102:105], v[66:67], off offset:512
	v_lshl_add_u64 v[66:67], v[0:1], 2, v[218:219]
	v_add_u32_e32 v0, 0x2c000, v220
	v_lshl_add_u64 v[70:71], v[0:1], 2, v[218:219]
	global_load_dwordx4 v[90:93], v[66:67], off offset:16
	global_load_dwordx4 v[94:97], v[66:67], off
	global_load_dwordx4 v[82:85], v[66:67], off offset:528
	global_load_dwordx4 v[86:89], v[66:67], off offset:512
	global_load_dwordx4 v[74:77], v[70:71], off offset:16
	global_load_dwordx4 v[78:81], v[70:71], off
	s_nop 0
	global_load_dwordx4 v[66:69], v[70:71], off offset:528
	s_nop 0
	global_load_dwordx4 v[70:73], v[70:71], off offset:512
	v_add_u32_e32 v130, 0x80, v216
	v_lshl_add_u32 v0, v130, 10, v226
	s_mov_b64 s[60:61], -1
	s_and_b64 vcc, exec, s[6:7]
	v_lshl_add_u64 v[132:133], v[0:1], 2, s[58:59]
	s_waitcnt vmcnt(15)
	v_pk_add_f32 v[124:125], v[60:61], v[124:125]
	s_waitcnt vmcnt(14)
	v_pk_add_f32 v[128:129], v[64:65], v[128:129]
	v_pk_add_f32 v[126:127], v[62:63], v[126:127]
	v_pk_add_f32 v[122:123], v[58:59], v[122:123]
	s_waitcnt vmcnt(12)
	v_pk_add_f32 v[62:63], v[54:55], v[118:119]
	v_pk_add_f32 v[58:59], v[46:47], v[114:115]
	global_store_dwordx4 v[132:133], v[126:129], off
	global_store_dwordx4 v[132:133], v[122:125], off offset:16
	s_cbranch_vccnz .LBB0_1729
	v_cvt_pk_bf16_f32 v134, v126, v127
	v_cvt_pk_bf16_f32 v135, v128, v129
	v_cvt_pk_bf16_f32 v136, v122, v123
	v_cvt_pk_bf16_f32 v137, v124, v125
	v_lshl_add_u64 v[46:47], v[0:1], 1, s[56:57]
	global_store_dwordx4 v[46:47], v[134:137], off
	v_mul_f32_e32 v46, v127, v127
	v_mul_f32_e32 v47, v129, v129
	v_fmac_f32_e32 v46, v126, v126
	v_fmac_f32_e32 v47, v128, v128
	v_add_f32_e32 v46, v46, v47
	v_mul_f32_e32 v47, v123, v123
	v_mul_f32_e32 v54, v125, v125
	v_fmac_f32_e32 v47, v122, v122
	v_fmac_f32_e32 v54, v124, v124
	v_add_f32_e32 v47, v47, v54
	v_pk_add_f32 v[64:65], v[56:57], v[120:121]
	v_add_f32_e32 v46, v46, v47
	v_mul_f32_e32 v47, v63, v63
	v_mul_f32_e32 v54, v65, v65
	v_pk_add_f32 v[60:61], v[48:49], v[116:117]
	v_fmac_f32_e32 v47, v62, v62
	v_fmac_f32_e32 v54, v64, v64
	v_add_f32_e32 v47, v47, v54
	v_mul_f32_e32 v54, v59, v59
	v_mul_f32_e32 v55, v61, v61
	v_fmac_f32_e32 v54, v58, v58
	v_fmac_f32_e32 v55, v60, v60
	v_add_f32_e32 v54, v54, v55
	v_add_f32_e32 v47, v47, v54
	v_and_b32_e32 v54, 64, v238
	v_add_f32_e32 v46, v46, v47
	v_xor_b32_e32 v47, 1, v238
	v_add_u32_e32 v54, 64, v54
	v_cmp_lt_i32_e32 vcc, v47, v54
	v_or_b32_e32 v0, 0x80, v0
	v_cvt_pk_bf16_f32 v122, v62, v63
	v_cndmask_b32_e32 v47, v238, v47, vcc
	v_lshlrev_b32_e32 v47, 2, v47
	ds_bpermute_b32 v47, v47, v46
	v_cvt_pk_bf16_f32 v123, v64, v65
	v_cvt_pk_bf16_f32 v124, v58, v59
	v_cvt_pk_bf16_f32 v125, v60, v61
	global_store_dwordx4 v[132:133], v[62:65], off offset:512
	global_store_dwordx4 v[132:133], v[58:61], off offset:528
	s_waitcnt lgkmcnt(0)
	v_add_f32_e32 v46, v46, v47
	v_xor_b32_e32 v47, 2, v238
	v_cmp_lt_i32_e32 vcc, v47, v54
	v_lshl_add_u64 v[54:55], v[0:1], 1, s[56:57]
	global_store_dwordx4 v[54:55], v[122:125], off
	v_cndmask_b32_e32 v47, v238, v47, vcc
	v_lshlrev_b32_e32 v47, 2, v47
	ds_bpermute_b32 v47, v47, v46
	s_and_saveexec_b64 s[60:61], s[4:5]
	s_cbranch_execz .LBB0_1728
	v_ashrrev_i32_e32 v131, 31, v130
	s_waitcnt lgkmcnt(0)
	v_add_f32_e32 v0, v46, v47
	v_lshl_add_u64 v[46:47], v[130:131], 2, s[54:55]
	global_atomic_add_f32 v[46:47], v0, off

; DEVI u32x4 pack8(const f32x4 a, const f32x4 b) { u32x4 w; w.x = cvtpk(a[0], a[1]); w.y = cvtpk(a[2], a[3]); w.z = cvtpk(b[0], b[1]); w.w = cvtpk(b[2], b[3]); return w; }
; DEVI float ss4(const f32x4 a) { return (a[0] * a[0] + a[1] * a[1]) + (a[2] * a[2] + a[3] * a[3]); }
; DEVI float red_fq(float s) { s += __shfl_xor(s, 16); s += __shfl_xor(s, 32); return s; }
;     DEVI void operator()(AccRef acc, const Unit& u, int wr, int wc, int fr, int fq) const {
;     ...
;             for (int m = 0; m < 4; ++m) {
;                 const int row = ROWOF(u);
;                 float s = 0.f;
; #pragma unroll
;                 for (int bj = 0; bj < 2; ++bj) {
;                     const unsigned off = (unsigned)row * 1024u + u.pn * 256 + bj * 128 + wc * 32 + 8 * fq;
;                     const f32x4 o0 = b0[m][bj] + acc[ai][bj][m][0], o1 = b1[m][bj] + acc[ai][bj][m][1];
;                     *(f32x4*)(out + off) = o0; *(f32x4*)(out + off + 4) = o1;
;                     if (wxb) { *(u32x4*)(xb + off) = pack8(o0, o1); s += ss4(o0) + ss4(o1); }
;                 }
;                 if (wxb) { s = red_fq(s); if (fq == 0) unsafeAtomicAdd(ssq + row, s); }
;             }
.LBB0_1731:
	s_nop 1
	v_add_u32_e32 v60, 0x90, v216
	v_lshl_add_u32 v0, v60, 10, v226
	s_waitcnt vmcnt(12)
	v_pk_add_f32 v[52:53], v[52:53], v[112:113]
	v_pk_add_f32 v[50:51], v[50:51], v[110:111]
	v_pk_add_f32 v[56:57], v[44:45], v[108:109]
	v_pk_add_f32 v[54:55], v[42:43], v[106:107]
	v_lshl_add_u64 v[58:59], v[0:1], 2, s[58:59]
	s_mov_b64 s[60:61], -1
	s_and_b64 vcc, exec, s[6:7]
	s_waitcnt vmcnt(10) lgkmcnt(0)
	v_pk_add_f32 v[46:47], v[38:39], v[102:103]
	v_pk_add_f32 v[42:43], v[30:31], v[98:99]
	global_store_dwordx4 v[58:59], v[50:53], off
	global_store_dwordx4 v[58:59], v[54:57], off offset:16
	s_cbranch_vccnz .LBB0_1735
	v_cvt_pk_bf16_f32 v62, v50, v51
	v_cvt_pk_bf16_f32 v63, v52, v53
	v_cvt_pk_bf16_f32 v64, v54, v55
	v_cvt_pk_bf16_f32 v65, v56, v57
	v_lshl_add_u64 v[30:31], v[0:1], 1, s[56:57]
	global_store_dwordx4 v[30:31], v[62:65], off
	v_mul_f32_e32 v30, v51, v51
	v_mul_f32_e32 v31, v53, v53
	v_fmac_f32_e32 v30, v50, v50
	v_fmac_f32_e32 v31, v52, v52
	v_add_f32_e32 v30, v30, v31
	v_mul_f32_e32 v31, v55, v55
	v_mul_f32_e32 v38, v57, v57
	v_fmac_f32_e32 v31, v54, v54
	v_fmac_f32_e32 v38, v56, v56
	v_add_f32_e32 v31, v31, v38
	v_pk_add_f32 v[48:49], v[40:41], v[104:105]
	v_add_f32_e32 v30, v30, v31
	v_mul_f32_e32 v31, v47, v47
	v_mul_f32_e32 v38, v49, v49
	v_pk_add_f32 v[44:45], v[32:33], v[100:101]
	v_fmac_f32_e32 v31, v46, v46
	v_fmac_f32_e32 v38, v48, v48
	v_add_f32_e32 v31, v31, v38
	v_mul_f32_e32 v38, v43, v43
	v_mul_f32_e32 v39, v45, v45
	v_fmac_f32_e32 v38, v42, v42
	v_fmac_f32_e32 v39, v44, v44
	v_add_f32_e32 v38, v38, v39
	v_add_f32_e32 v31, v31, v38
	v_and_b32_e32 v38, 64, v238
	v_add_f32_e32 v30, v30, v31
	v_xor_b32_e32 v31, 1, v238
	v_add_u32_e32 v38, 64, v38
	v_cmp_lt_i32_e32 vcc, v31, v38
	v_or_b32_e32 v0, 0x80, v0
	v_cvt_pk_bf16_f32 v50, v46, v47
	v_cndmask_b32_e32 v31, v238, v31, vcc
	v_lshlrev_b32_e32 v31, 2, v31
	ds_bpermute_b32 v31, v31, v30
	v_cvt_pk_bf16_f32 v51, v48, v49
	v_cvt_pk_bf16_f32 v52, v42, v43
	v_cvt_pk_bf16_f32 v53, v44, v45
	global_store_dwordx4 v[58:59], v[46:49], off offset:512
	global_store_dwordx4 v[58:59], v[42:45], off offset:528
	s_waitcnt lgkmcnt(0)
	v_add_f32_e32 v30, v30, v31
	v_xor_b32_e32 v31, 2, v238
	v_cmp_lt_i32_e32 vcc, v31, v38
	v_lshl_add_u64 v[38:39], v[0:1], 1, s[56:57]
	global_store_dwordx4 v[38:39], v[50:53], off
	v_cndmask_b32_e32 v31, v238, v31, vcc
	v_lshlrev_b32_e32 v31, 2, v31
	ds_bpermute_b32 v31, v31, v30
	s_and_saveexec_b64 s[60:61], s[4:5]
	s_cbranch_execz .LBB0_1734
	v_ashrrev_i32_e32 v61, 31, v60
	s_waitcnt lgkmcnt(0)
	v_add_f32_e32 v0, v30, v31
	v_lshl_add_u64 v[30:31], v[60:61], 2, s[54:55]
	global_atomic_add_f32 v[30:31], v0, off

; DEVI u32x4 pack8(const f32x4 a, const f32x4 b) { u32x4 w; w.x = cvtpk(a[0], a[1]); w.y = cvtpk(a[2], a[3]); w.z = cvtpk(b[0], b[1]); w.w = cvtpk(b[2], b[3]); return w; }
; DEVI float ss4(const f32x4 a) { return (a[0] * a[0] + a[1] * a[1]) + (a[2] * a[2] + a[3] * a[3]); }
; DEVI float red_fq(float s) { s += __shfl_xor(s, 16); s += __shfl_xor(s, 32); return s; }
;     DEVI void operator()(AccRef acc, const Unit& u, int wr, int wc, int fr, int fq) const {
;     ...
;             for (int m = 0; m < 4; ++m) {
;                 const int row = ROWOF(u);
;                 float s = 0.f;
; #pragma unroll
;                 for (int bj = 0; bj < 2; ++bj) {
;                     const unsigned off = (unsigned)row * 1024u + u.pn * 256 + bj * 128 + wc * 32 + 8 * fq;
;                     const f32x4 o0 = b0[m][bj] + acc[ai][bj][m][0], o1 = b1[m][bj] + acc[ai][bj][m][1];
;                     *(f32x4*)(out + off) = o0; *(f32x4*)(out + off + 4) = o1;
;                     if (wxb) { *(u32x4*)(xb + off) = pack8(o0, o1); s += ss4(o0) + ss4(o1); }
;                 }
;                 if (wxb) { s = red_fq(s); if (fq == 0) unsafeAtomicAdd(ssq + row, s); }
;             }
.LBB0_1737:
	s_nop 1
	v_add_u32_e32 v44, 0xa0, v216
	v_lshl_add_u32 v0, v44, 10, v226
	s_waitcnt vmcnt(10)
	v_pk_add_f32 v[36:37], v[36:37], v[96:97]
	v_pk_add_f32 v[34:35], v[34:35], v[94:95]
	v_pk_add_f32 v[40:41], v[28:29], v[92:93]
	v_pk_add_f32 v[38:39], v[26:27], v[90:91]
	v_lshl_add_u64 v[42:43], v[0:1], 2, s[58:59]
	s_mov_b64 s[60:61], -1
	s_and_b64 vcc, exec, s[6:7]
	s_waitcnt vmcnt(8) lgkmcnt(0)
	v_pk_add_f32 v[30:31], v[22:23], v[86:87]
	v_pk_add_f32 v[26:27], v[14:15], v[82:83]
	global_store_dwordx4 v[42:43], v[34:37], off
	global_store_dwordx4 v[42:43], v[38:41], off offset:16
	s_cbranch_vccnz .LBB0_1741
	v_cvt_pk_bf16_f32 v46, v34, v35
	v_cvt_pk_bf16_f32 v47, v36, v37
	v_cvt_pk_bf16_f32 v48, v38, v39
	v_cvt_pk_bf16_f32 v49, v40, v41
	v_lshl_add_u64 v[14:15], v[0:1], 1, s[56:57]
	global_store_dwordx4 v[14:15], v[46:49], off
	v_mul_f32_e32 v14, v35, v35
	v_mul_f32_e32 v15, v37, v37
	v_fmac_f32_e32 v14, v34, v34
	v_fmac_f32_e32 v15, v36, v36
	v_add_f32_e32 v14, v14, v15
	v_mul_f32_e32 v15, v39, v39
	v_mul_f32_e32 v22, v41, v41
	v_fmac_f32_e32 v15, v38, v38
	v_fmac_f32_e32 v22, v40, v40
	v_add_f32_e32 v15, v15, v22
	v_pk_add_f32 v[32:33], v[24:25], v[88:89]
	v_add_f32_e32 v14, v14, v15
	v_mul_f32_e32 v15, v31, v31
	v_mul_f32_e32 v22, v33, v33
	v_pk_add_f32 v[28:29], v[16:17], v[84:85]
	v_fmac_f32_e32 v15, v30, v30
	v_fmac_f32_e32 v22, v32, v32
	v_add_f32_e32 v15, v15, v22
	v_mul_f32_e32 v22, v27, v27
	v_mul_f32_e32 v23, v29, v29
	v_fmac_f32_e32 v22, v26, v26
	v_fmac_f32_e32 v23, v28, v28
	v_add_f32_e32 v22, v22, v23
	v_add_f32_e32 v15, v15, v22
	v_and_b32_e32 v22, 64, v238
	v_add_f32_e32 v14, v14, v15
	v_xor_b32_e32 v15, 1, v238
	v_add_u32_e32 v22, 64, v22
	v_cmp_lt_i32_e32 vcc, v15, v22
	v_or_b32_e32 v0, 0x80, v0
	v_cvt_pk_bf16_f32 v34, v30, v31
	v_cndmask_b32_e32 v15, v238, v15, vcc
	v_lshlrev_b32_e32 v15, 2, v15
	ds_bpermute_b32 v15, v15, v14
	v_cvt_pk_bf16_f32 v35, v32, v33
	v_cvt_pk_bf16_f32 v36, v26, v27
	v_cvt_pk_bf16_f32 v37, v28, v29
	global_store_dwordx4 v[42:43], v[30:33], off offset:512
	global_store_dwordx4 v[42:43], v[26:29], off offset:528
	s_waitcnt lgkmcnt(0)
	v_add_f32_e32 v14, v14, v15
	v_xor_b32_e32 v15, 2, v238
	v_cmp_lt_i32_e32 vcc, v15, v22
	v_lshl_add_u64 v[22:23], v[0:1], 1, s[56:57]
	global_store_dwordx4 v[22:23], v[34:37], off
	v_cndmask_b32_e32 v15, v238, v15, vcc
	v_lshlrev_b32_e32 v15, 2, v15
	ds_bpermute_b32 v15, v15, v14
	s_and_saveexec_b64 s[60:61], s[4:5]
	s_cbranch_execz .LBB0_1740
	v_ashrrev_i32_e32 v45, 31, v44
	s_waitcnt lgkmcnt(0)
	v_add_f32_e32 v0, v14, v15
	v_lshl_add_u64 v[14:15], v[44:45], 2, s[54:55]
	global_atomic_add_f32 v[14:15], v0, off

; DEVI u32x4 pack8(const f32x4 a, const f32x4 b) { u32x4 w; w.x = cvtpk(a[0], a[1]); w.y = cvtpk(a[2], a[3]); w.z = cvtpk(b[0], b[1]); w.w = cvtpk(b[2], b[3]); return w; }
; DEVI float ss4(const f32x4 a) { return (a[0] * a[0] + a[1] * a[1]) + (a[2] * a[2] + a[3] * a[3]); }
; DEVI float red_fq(float s) { s += __shfl_xor(s, 16); s += __shfl_xor(s, 32); return s; }
;     DEVI void operator()(AccRef acc, const Unit& u, int wr, int wc, int fr, int fq) const {
;     ...
;             for (int m = 0; m < 4; ++m) {
;                 const int row = ROWOF(u);
;                 float s = 0.f;
; #pragma unroll
;                 for (int bj = 0; bj < 2; ++bj) {
;                     const unsigned off = (unsigned)row * 1024u + u.pn * 256 + bj * 128 + wc * 32 + 8 * fq;
;                     const f32x4 o0 = b0[m][bj] + acc[ai][bj][m][0], o1 = b1[m][bj] + acc[ai][bj][m][1];
;                     *(f32x4*)(out + off) = o0; *(f32x4*)(out + off + 4) = o1;
;                     if (wxb) { *(u32x4*)(xb + off) = pack8(o0, o1); s += ss4(o0) + ss4(o1); }
;                 }
;                 if (wxb) { s = red_fq(s); if (fq == 0) unsafeAtomicAdd(ssq + row, s); }
;             }
.LBB0_1743:
	s_nop 1
	v_add_u32_e32 v28, 0xb0, v216
	v_lshl_add_u32 v0, v28, 10, v226
	s_waitcnt vmcnt(8)
	v_pk_add_f32 v[20:21], v[20:21], v[80:81]
	v_pk_add_f32 v[18:19], v[18:19], v[78:79]
	v_pk_add_f32 v[24:25], v[12:13], v[76:77]
	v_pk_add_f32 v[22:23], v[10:11], v[74:75]
	v_lshl_add_u64 v[26:27], v[0:1], 2, s[58:59]
	s_mov_b64 s[58:59], -1
	s_and_b64 vcc, exec, s[6:7]
	s_waitcnt vmcnt(6) lgkmcnt(0)
	v_pk_add_f32 v[14:15], v[6:7], v[70:71]
	v_pk_add_f32 v[10:11], v[2:3], v[66:67]
	global_store_dwordx4 v[26:27], v[18:21], off
	global_store_dwordx4 v[26:27], v[22:25], off offset:16
	s_cbranch_vccnz .LBB0_1747
	v_cvt_pk_bf16_f32 v30, v18, v19
	v_cvt_pk_bf16_f32 v31, v20, v21
	v_cvt_pk_bf16_f32 v32, v22, v23
	v_cvt_pk_bf16_f32 v33, v24, v25
	v_lshl_add_u64 v[2:3], v[0:1], 1, s[56:57]
	global_store_dwordx4 v[2:3], v[30:33], off
	v_mul_f32_e32 v2, v19, v19
	v_mul_f32_e32 v3, v21, v21
	v_fmac_f32_e32 v2, v18, v18
	v_fmac_f32_e32 v3, v20, v20
	v_add_f32_e32 v2, v2, v3
	v_mul_f32_e32 v3, v23, v23
	v_mul_f32_e32 v6, v25, v25
	v_fmac_f32_e32 v3, v22, v22
	v_fmac_f32_e32 v6, v24, v24
	v_add_f32_e32 v3, v3, v6
	v_pk_add_f32 v[16:17], v[8:9], v[72:73]
	v_add_f32_e32 v2, v2, v3
	v_mul_f32_e32 v3, v15, v15
	v_mul_f32_e32 v6, v17, v17
	v_pk_add_f32 v[12:13], v[4:5], v[68:69]
	v_fmac_f32_e32 v3, v14, v14
	v_fmac_f32_e32 v6, v16, v16
	v_add_f32_e32 v3, v3, v6
	v_mul_f32_e32 v6, v11, v11
	v_mul_f32_e32 v7, v13, v13
	v_fmac_f32_e32 v6, v10, v10
	v_fmac_f32_e32 v7, v12, v12
	v_add_f32_e32 v6, v6, v7
	v_add_f32_e32 v3, v3, v6
	v_and_b32_e32 v6, 64, v238
	v_add_f32_e32 v2, v2, v3
	v_xor_b32_e32 v3, 1, v238
	v_add_u32_e32 v6, 64, v6
	v_cmp_lt_i32_e32 vcc, v3, v6
	v_or_b32_e32 v0, 0x80, v0
	v_cvt_pk_bf16_f32 v18, v14, v15
	v_cndmask_b32_e32 v3, v238, v3, vcc
	v_lshlrev_b32_e32 v3, 2, v3
	ds_bpermute_b32 v3, v3, v2
	v_cvt_pk_bf16_f32 v19, v16, v17
	v_cvt_pk_bf16_f32 v20, v10, v11
	v_cvt_pk_bf16_f32 v21, v12, v13
	global_store_dwordx4 v[26:27], v[14:17], off offset:512
	global_store_dwordx4 v[26:27], v[10:13], off offset:528
	s_waitcnt lgkmcnt(0)
	v_add_f32_e32 v2, v2, v3
	v_xor_b32_e32 v3, 2, v238
	v_cmp_lt_i32_e32 vcc, v3, v6
	v_lshl_add_u64 v[6:7], v[0:1], 1, s[56:57]
	global_store_dwordx4 v[6:7], v[18:21], off
	v_cndmask_b32_e32 v3, v238, v3, vcc
	v_lshlrev_b32_e32 v3, 2, v3
	ds_bpermute_b32 v3, v3, v2
	s_and_saveexec_b64 s[6:7], s[4:5]
	s_cbranch_execz .LBB0_1746
	v_ashrrev_i32_e32 v29, 31, v28
	s_waitcnt lgkmcnt(0)
	v_add_f32_e32 v0, v2, v3
	v_lshl_add_u64 v[2:3], v[28:29], 2, s[54:55]
	global_atomic_add_f32 v[2:3], v0, off
